# leading wave half defers its load-segment waits (vmcnt(8), lgkmcnt(0)) to after the pre-MFMA barrier; trailing half unchanged
# baseline (speedup 1.0000x reference)
; #define PG8_STAGE(bufoff, gbase, voff) do { _Pragma("unroll") for (int _i = 0; _i < 2; ++_i) \
;         __builtin_amdgcn_global_load_lds((const unsigned*)((const char*)(gbase) + (voff)[_i]), (PG8_LAS unsigned*)(lds + (bufoff) + ldsw + _i * 8192), 16, 0, 0); } while (0)
; #define PG8_LDA(dst, b, h) do { _Pragma("unroll") for (int m = 0; m < 4; ++m) _Pragma("unroll") for (int k = 0; k < 2; ++k) dst[m][k] = *(const PG8_LAS bf16x8*)(lds + PG8_SA(b, h) + aoff + m * 2048 + k * 1024); } while (0)
; #define PG8_LDB(dst, b, h) do { _Pragma("unroll") for (int n = 0; n < 2; ++n) _Pragma("unroll") for (int k = 0; k < 2; ++k) dst[n][k] = *(const PG8_LAS bf16x8*)(lds + PG8_SB(b, h) + boff + n * 2048 + k * 1024); } while (0)
; #define PG8_MMA(ai, bj, At, Bt) do { __builtin_amdgcn_s_setprio(1); _Pragma("unroll") for (int m = 0; m < 4; ++m) _Pragma("unroll") for (int n = 0; n < 2; ++n) _Pragma("unroll") for (int k = 0; k < 2; ++k) \
;         acc[ai][bj][m][n] = __builtin_amdgcn_mfma_f32_16x16x32_bf16(Bt[n][k], At[m][k], acc[ai][bj][m][n], 0, 0, 0); __builtin_amdgcn_s_setprio(0); } while (0)
; #define PG8_BAR __builtin_amdgcn_s_barrier()
; template <class Epi, class Sched, bool ALIGN_EPI = false, bool SP2 = false>
; __device__ __forceinline__ void gemm_phase(PG8_LAS unsigned char* lds, const Gemm g, const Sched& S, const Epi& E) {
;     ...
;         const bool has_next = S.next(ui + 1, nxt);
;         const char* nA = has_next ? (const char*)g.A + (size_t)nxt.pm * tstep : cA; const char* nB = has_next ? (const char*)g.Bt + (size_t)nxt.pn * tstep : cB;
;         for (int t = 0; t < nt; t += 2) {
;             const bool last = (t == nt - 2);
;             const char* a1 = cA + (size_t)(t + 1) * kstep;
;             const char* a2 = last ? nA : cA + (size_t)(t + 2) * kstep; const char* b2 = last ? nB : cB + (size_t)(t + 2) * kstep;
;             const char* a3 = a2 + kstep; const char* b3 = b2 + kstep;
;             if (last && has_next) S.a_ready(nxt);
;             if constexpr (SP2) {
;             PG8_LDB(B0, 0, 0); PG8_LDB(B1, 0, 1); PG8_SCHED; PG8_LDA(At, 0, 0); PG8_STAGE(PG8_SA(1, 1), a1 + hstep, voffA);
;             PG8_WAIT_V(8); PG8_WAIT_L(0); PG8_BAR; PG8_MMA(0, 0, At, B0); PG8_MMA(0, 1, At, B1); PG8_BAR; PG8_SCHED;
;             PG8_LDA(At, 0, 1); PG8_STAGE(PG8_SB(0, 0), b2, voffB); PG8_STAGE(PG8_SB(0, 1), b2 + hstepB, voffB); PG8_STAGE(PG8_SA(0, 0), a2, voffA);
.LBB0_169:
	s_add_u32 s93, s46, 0x100
	s_addc_u32 s94, s47, 0
	s_ashr_i32 s69, s68, 31
	s_lshl_b64 s[4:5], s[68:69], 20
	s_add_u32 s76, s52, s4
	s_addc_u32 s77, s53, s5
	s_and_b64 s[4:5], s[38:39], exec
	s_cselect_b32 s4, s77, s71
	s_cselect_b32 s5, s76, s70
	s_ashr_i32 s63, s62, 31
	s_lshl_b64 s[6:7], s[62:63], 20
	v_readlane_b32 s8, v249, 19
	v_readlane_b32 s9, v249, 20
	s_add_u32 s72, s8, s6
	s_addc_u32 s73, s9, s7
	s_and_b64 s[6:7], s[38:39], exec
	s_cselect_b32 s6, s73, s47
	s_cselect_b32 s7, s72, s46
	s_add_u32 s8, s70, 0x80080
	s_addc_u32 s9, s71, 0
	v_lshl_add_u64 v[144:145], s[8:9], 0, v[140:141]
	v_lshl_add_u64 v[146:147], s[8:9], 0, v[142:143]
	s_mov_b32 s8, -2
	s_mov_b64 s[46:47], 0
	v_add_u32_e32 v186, 0x10000, v139
	v_add_u32_e32 v187, 0x14000, v139
	v_add_u32_e32 v198, 0x18000, v139
	v_add_u32_e32 v199, 0x1c000, v139
	s_add_u32 s9, s70, s46
	s_addc_u32 s10, s71, s47
	s_add_u32 s9, s9, 0x100
	s_addc_u32 s10, s10, 0
	s_add_u32 s100, s9, 0x7ff80
	s_addc_u32 s101, s10, 0
	s_add_u32 s11, s93, s46
	s_addc_u32 s12, s94, s47
	s_add_i32 s13, 0, 0x10000
	s_cmpk_eq_i32 s46, 0xf00
	s_cselect_b32 s85, s4, s10
	s_cselect_b32 s84, s5, s9
	s_cselect_b32 s81, s6, s12
	s_cselect_b32 s80, s7, s11
	s_add_i32 s9, 0, 0x14000
	ds_read_b128 v[148:151], v186
	ds_read_b128 v[152:155], v186 offset:1024
	ds_read_b128 v[156:159], v186 offset:2048
	ds_read_b128 v[160:163], v186 offset:3072
	ds_read_b128 v[166:169], v187
	ds_read_b128 v[170:173], v187 offset:1024
	ds_read_b128 v[174:177], v187 offset:2048
	ds_read_b128 v[178:181], v187 offset:3072
	s_add_i32 m0, s1, 0xc000
	ds_read_b128 v[182:185], v165
	ds_read_b128 v[206:209], v165 offset:1024
	ds_read_b128 v[210:213], v165 offset:2048
	ds_read_b128 v[214:217], v165 offset:3072
	ds_read_b128 v[218:221], v165 offset:4096
	ds_read_b128 v[236:239], v165 offset:5120
	ds_read_b128 v[240:243], v165 offset:6144
	ds_read_b128 v[244:247], v165 offset:7168
	global_load_lds_dwordx4 v140, s[100:101]
	s_add_i32 m0, s1, 0xe000
	s_nop 0
	global_load_lds_dwordx4 v142, s[100:101]
	s_cmp_lg_u32 s54, 0
	s_cbranch_scc1 .Llw_7026
	s_waitcnt vmcnt(8)
	s_waitcnt lgkmcnt(0)
.Llw_7026:
	s_barrier
	s_waitcnt vmcnt(8)
	s_waitcnt lgkmcnt(0)
	v_mfma_f32_16x16x32_bf16 v[126:129], v[148:151], v[182:185], 0
	v_mfma_f32_16x16x32_bf16 v[122:125], v[156:159], v[182:185], 0
	v_mfma_f32_16x16x32_bf16 v[118:121], v[148:151], v[210:213], 0
	v_mfma_f32_16x16x32_bf16 v[114:117], v[156:159], v[210:213], 0
	v_mfma_f32_16x16x32_bf16 v[110:113], v[148:151], v[218:221], 0
	v_mfma_f32_16x16x32_bf16 v[106:109], v[156:159], v[218:221], 0
	v_mfma_f32_16x16x32_bf16 v[102:105], v[148:151], v[240:243], 0
	v_mfma_f32_16x16x32_bf16 v[98:101], v[156:159], v[240:243], 0
	v_mfma_f32_16x16x32_bf16 v[126:129], v[152:155], v[206:209], v[126:129]
	v_mfma_f32_16x16x32_bf16 v[122:125], v[160:163], v[206:209], v[122:125]
	v_mfma_f32_16x16x32_bf16 v[118:121], v[152:155], v[214:217], v[118:121]
	v_mfma_f32_16x16x32_bf16 v[114:117], v[160:163], v[214:217], v[114:117]
	v_mfma_f32_16x16x32_bf16 v[110:113], v[152:155], v[236:239], v[110:113]
	v_mfma_f32_16x16x32_bf16 v[106:109], v[160:163], v[236:239], v[106:109]
	v_mfma_f32_16x16x32_bf16 v[102:105], v[152:155], v[244:247], v[102:105]
	v_mfma_f32_16x16x32_bf16 v[98:101], v[160:163], v[244:247], v[98:101]
	v_mfma_f32_16x16x32_bf16 v[94:97], v[166:169], v[182:185], 0
	v_mfma_f32_16x16x32_bf16 v[90:93], v[174:177], v[182:185], 0
	v_mfma_f32_16x16x32_bf16 v[86:89], v[166:169], v[210:213], 0
	v_mfma_f32_16x16x32_bf16 v[82:85], v[174:177], v[210:213], 0
	v_mfma_f32_16x16x32_bf16 v[78:81], v[166:169], v[218:221], 0
	v_mfma_f32_16x16x32_bf16 v[74:77], v[174:177], v[218:221], 0
	v_mfma_f32_16x16x32_bf16 v[70:73], v[166:169], v[240:243], 0
	v_mfma_f32_16x16x32_bf16 v[66:69], v[174:177], v[240:243], 0
	v_mfma_f32_16x16x32_bf16 v[94:97], v[170:173], v[206:209], v[94:97]
	v_mfma_f32_16x16x32_bf16 v[90:93], v[178:181], v[206:209], v[90:93]
	v_mfma_f32_16x16x32_bf16 v[86:89], v[170:173], v[214:217], v[86:89]
	v_mfma_f32_16x16x32_bf16 v[82:85], v[178:181], v[214:217], v[82:85]
	v_mfma_f32_16x16x32_bf16 v[78:81], v[170:173], v[236:239], v[78:81]
	v_mfma_f32_16x16x32_bf16 v[74:77], v[178:181], v[236:239], v[74:77]
	v_mfma_f32_16x16x32_bf16 v[70:73], v[170:173], v[244:247], v[70:73]
	v_mfma_f32_16x16x32_bf16 v[66:69], v[178:181], v[244:247], v[66:69]
	s_barrier
	s_add_i32 s10, s13, s0
	s_mov_b32 m0, s10
	ds_read_b128 v[182:185], v165 offset:16384
	ds_read_b128 v[206:209], v165 offset:17408
	ds_read_b128 v[210:213], v165 offset:18432
	ds_read_b128 v[214:217], v165 offset:19456
	ds_read_b128 v[218:221], v165 offset:20480
	ds_read_b128 v[236:239], v165 offset:21504
	ds_read_b128 v[240:243], v165 offset:22528
	ds_read_b128 v[244:247], v165 offset:23552
	global_load_lds_dwordx4 v132, s[80:81]
	s_add_i32 m0, s10, 0x2000
	s_add_u32 s10, s80, 0x20000
	s_addc_u32 s11, s81, 0
	s_add_i32 s9, s9, s0
	global_load_lds_dwordx4 v136, s[80:81]
	s_mov_b32 m0, s9
	s_nop 0
	global_load_lds_dwordx4 v132, s[10:11]
	s_add_i32 m0, s9, 0x2000
	s_nop 0
	global_load_lds_dwordx4 v136, s[10:11]
	s_mov_b32 m0, s1
	s_nop 0
	global_load_lds_dwordx4 v130, s[84:85]
	s_mov_b32 m0, s25
	s_nop 0
	global_load_lds_dwordx4 v134, s[84:85]
	s_cmp_lg_u32 s54, 0
	s_cbranch_scc1 .Llw_7095
	s_waitcnt vmcnt(8)
	s_waitcnt lgkmcnt(0)
; #define PG8_STAGE(bufoff, gbase, voff) do { _Pragma("unroll") for (int _i = 0; _i < 2; ++_i) \
;         __builtin_amdgcn_global_load_lds((const unsigned*)((const char*)(gbase) + (voff)[_i]), (PG8_LAS unsigned*)(lds + (bufoff) + ldsw + _i * 8192), 16, 0, 0); } while (0)
; #define PG8_LDA(dst, b, h) do { _Pragma("unroll") for (int m = 0; m < 4; ++m) _Pragma("unroll") for (int k = 0; k < 2; ++k) dst[m][k] = *(const PG8_LAS bf16x8*)(lds + PG8_SA(b, h) + aoff + m * 2048 + k * 1024); } while (0)
; #define PG8_LDB(dst, b, h) do { _Pragma("unroll") for (int n = 0; n < 2; ++n) _Pragma("unroll") for (int k = 0; k < 2; ++k) dst[n][k] = *(const PG8_LAS bf16x8*)(lds + PG8_SB(b, h) + boff + n * 2048 + k * 1024); } while (0)
; #define PG8_MMA(ai, bj, At, Bt) do { __builtin_amdgcn_s_setprio(1); _Pragma("unroll") for (int m = 0; m < 4; ++m) _Pragma("unroll") for (int n = 0; n < 2; ++n) _Pragma("unroll") for (int k = 0; k < 2; ++k) \
;         acc[ai][bj][m][n] = __builtin_amdgcn_mfma_f32_16x16x32_bf16(Bt[n][k], At[m][k], acc[ai][bj][m][n], 0, 0, 0); __builtin_amdgcn_s_setprio(0); } while (0)
; #define PG8_WAIT_V(n) asm volatile("s_waitcnt vmcnt(" #n ")" ::: "memory")
; #define PG8_WAIT_L(n) asm volatile("s_waitcnt lgkmcnt(" #n ")" ::: "memory")
; #define PG8_BAR __builtin_amdgcn_s_barrier()
; #define PG8_SCHED __builtin_amdgcn_sched_barrier(0)
; template <class Epi, class Sched, bool ALIGN_EPI = false, bool SP2 = false>
; __device__ __forceinline__ void gemm_phase(PG8_LAS unsigned char* lds, const Gemm g, const Sched& S, const Epi& E) {
;     ...
;             PG8_WAIT_V(8); PG8_WAIT_L(0); PG8_BAR; PG8_MMA(1, 0, At, B0); PG8_MMA(1, 1, At, B1); PG8_BAR; PG8_SCHED;
;             PG8_LDB(B0, 1, 0); PG8_LDB(B1, 1, 1); PG8_SCHED; PG8_LDA(At, 1, 0); PG8_STAGE(PG8_SA(0, 1), a2 + hstep, voffA);
;             PG8_WAIT_V(8); PG8_WAIT_L(0); PG8_BAR; PG8_MMA(0, 0, At, B0); PG8_MMA(0, 1, At, B1); PG8_BAR; PG8_SCHED;
.Llw_7095:
	s_barrier
	s_waitcnt vmcnt(8)
	s_waitcnt lgkmcnt(0)
	v_mfma_f32_16x16x32_bf16 v[62:65], v[148:151], v[182:185], 0
	v_mfma_f32_16x16x32_bf16 v[58:61], v[156:159], v[182:185], 0
	v_mfma_f32_16x16x32_bf16 v[54:57], v[148:151], v[210:213], 0
	v_mfma_f32_16x16x32_bf16 v[50:53], v[156:159], v[210:213], 0
	v_mfma_f32_16x16x32_bf16 v[46:49], v[148:151], v[218:221], 0
	v_mfma_f32_16x16x32_bf16 v[42:45], v[156:159], v[218:221], 0
	v_mfma_f32_16x16x32_bf16 v[38:41], v[148:151], v[240:243], 0
	v_mfma_f32_16x16x32_bf16 v[34:37], v[156:159], v[240:243], 0
	v_mfma_f32_16x16x32_bf16 v[62:65], v[152:155], v[206:209], v[62:65]
	v_mfma_f32_16x16x32_bf16 v[58:61], v[160:163], v[206:209], v[58:61]
	v_mfma_f32_16x16x32_bf16 v[54:57], v[152:155], v[214:217], v[54:57]
	v_mfma_f32_16x16x32_bf16 v[50:53], v[160:163], v[214:217], v[50:53]
	v_mfma_f32_16x16x32_bf16 v[46:49], v[152:155], v[236:239], v[46:49]
	v_mfma_f32_16x16x32_bf16 v[42:45], v[160:163], v[236:239], v[42:45]
	v_mfma_f32_16x16x32_bf16 v[38:41], v[152:155], v[244:247], v[38:41]
	v_mfma_f32_16x16x32_bf16 v[34:37], v[160:163], v[244:247], v[34:37]
	v_mfma_f32_16x16x32_bf16 v[30:33], v[166:169], v[182:185], 0
	v_mfma_f32_16x16x32_bf16 v[26:29], v[174:177], v[182:185], 0
	v_mfma_f32_16x16x32_bf16 v[22:25], v[166:169], v[210:213], 0
	v_mfma_f32_16x16x32_bf16 v[18:21], v[174:177], v[210:213], 0
	v_mfma_f32_16x16x32_bf16 v[14:17], v[166:169], v[218:221], 0
	v_mfma_f32_16x16x32_bf16 v[10:13], v[174:177], v[218:221], 0
	v_mfma_f32_16x16x32_bf16 v[6:9], v[166:169], v[240:243], 0
	v_mfma_f32_16x16x32_bf16 v[2:5], v[174:177], v[240:243], 0
	v_mfma_f32_16x16x32_bf16 v[30:33], v[170:173], v[206:209], v[30:33]
	v_mfma_f32_16x16x32_bf16 v[26:29], v[178:181], v[206:209], v[26:29]
	v_mfma_f32_16x16x32_bf16 v[22:25], v[170:173], v[214:217], v[22:25]
	v_mfma_f32_16x16x32_bf16 v[18:21], v[178:181], v[214:217], v[18:21]
	v_mfma_f32_16x16x32_bf16 v[14:17], v[170:173], v[236:239], v[14:17]
	v_mfma_f32_16x16x32_bf16 v[10:13], v[178:181], v[236:239], v[10:13]
	v_mfma_f32_16x16x32_bf16 v[6:9], v[170:173], v[244:247], v[6:9]
	v_mfma_f32_16x16x32_bf16 v[2:5], v[178:181], v[244:247], v[2:5]
	s_barrier
	s_add_i32 s9, 0, 0x18000
	s_add_i32 s12, 0, 0x1c000
	ds_read_b128 v[148:151], v198
	ds_read_b128 v[152:155], v198 offset:1024
	ds_read_b128 v[156:159], v198 offset:2048
	ds_read_b128 v[160:163], v198 offset:3072
	ds_read_b128 v[166:169], v199
	ds_read_b128 v[170:173], v199 offset:1024
	ds_read_b128 v[174:177], v199 offset:2048
	ds_read_b128 v[178:181], v199 offset:3072
	s_add_u32 s10, s84, 0x80000
	s_addc_u32 s11, s85, 0
	s_mov_b32 m0, s42
	ds_read_b128 v[182:185], v165 offset:32768
	ds_read_b128 v[206:209], v165 offset:33792
	ds_read_b128 v[210:213], v165 offset:34816
	ds_read_b128 v[214:217], v165 offset:35840
	ds_read_b128 v[218:221], v165 offset:36864
	ds_read_b128 v[236:239], v165 offset:37888
	ds_read_b128 v[240:243], v165 offset:38912
	ds_read_b128 v[244:247], v165 offset:39936
	global_load_lds_dwordx4 v130, s[10:11]
	s_mov_b32 m0, s51
	s_nop 0
	global_load_lds_dwordx4 v134, s[10:11]
	s_cmp_lg_u32 s54, 0
	s_cbranch_scc1 .Llw_7162
	s_waitcnt vmcnt(8)
	s_waitcnt lgkmcnt(0)
.Llw_7162:
	s_barrier
	s_waitcnt vmcnt(8)
	s_waitcnt lgkmcnt(0)
	v_mfma_f32_16x16x32_bf16 v[126:129], v[148:151], v[182:185], v[126:129]
	v_mfma_f32_16x16x32_bf16 v[122:125], v[156:159], v[182:185], v[122:125]
	v_mfma_f32_16x16x32_bf16 v[118:121], v[148:151], v[210:213], v[118:121]
	v_mfma_f32_16x16x32_bf16 v[114:117], v[156:159], v[210:213], v[114:117]
	v_mfma_f32_16x16x32_bf16 v[110:113], v[148:151], v[218:221], v[110:113]
	v_mfma_f32_16x16x32_bf16 v[106:109], v[156:159], v[218:221], v[106:109]
	v_mfma_f32_16x16x32_bf16 v[102:105], v[148:151], v[240:243], v[102:105]
	v_mfma_f32_16x16x32_bf16 v[98:101], v[156:159], v[240:243], v[98:101]
	v_mfma_f32_16x16x32_bf16 v[126:129], v[152:155], v[206:209], v[126:129]
	v_mfma_f32_16x16x32_bf16 v[122:125], v[160:163], v[206:209], v[122:125]
	v_mfma_f32_16x16x32_bf16 v[118:121], v[152:155], v[214:217], v[118:121]
	v_mfma_f32_16x16x32_bf16 v[114:117], v[160:163], v[214:217], v[114:117]
	v_mfma_f32_16x16x32_bf16 v[110:113], v[152:155], v[236:239], v[110:113]
	v_mfma_f32_16x16x32_bf16 v[106:109], v[160:163], v[236:239], v[106:109]
	v_mfma_f32_16x16x32_bf16 v[102:105], v[152:155], v[244:247], v[102:105]
	v_mfma_f32_16x16x32_bf16 v[98:101], v[160:163], v[244:247], v[98:101]
	v_mfma_f32_16x16x32_bf16 v[94:97], v[166:169], v[182:185], v[94:97]
	v_mfma_f32_16x16x32_bf16 v[90:93], v[174:177], v[182:185], v[90:93]
	v_mfma_f32_16x16x32_bf16 v[86:89], v[166:169], v[210:213], v[86:89]
	v_mfma_f32_16x16x32_bf16 v[82:85], v[174:177], v[210:213], v[82:85]
	v_mfma_f32_16x16x32_bf16 v[78:81], v[166:169], v[218:221], v[78:81]
	v_mfma_f32_16x16x32_bf16 v[74:77], v[174:177], v[218:221], v[74:77]
	v_mfma_f32_16x16x32_bf16 v[70:73], v[166:169], v[240:243], v[70:73]
	v_mfma_f32_16x16x32_bf16 v[66:69], v[174:177], v[240:243], v[66:69]
	v_mfma_f32_16x16x32_bf16 v[94:97], v[170:173], v[206:209], v[94:97]
	v_mfma_f32_16x16x32_bf16 v[90:93], v[178:181], v[206:209], v[90:93]
	v_mfma_f32_16x16x32_bf16 v[86:89], v[170:173], v[214:217], v[86:89]
	v_mfma_f32_16x16x32_bf16 v[82:85], v[178:181], v[214:217], v[82:85]
	v_mfma_f32_16x16x32_bf16 v[78:81], v[170:173], v[236:239], v[78:81]
	v_mfma_f32_16x16x32_bf16 v[74:77], v[178:181], v[236:239], v[74:77]
	v_mfma_f32_16x16x32_bf16 v[70:73], v[170:173], v[244:247], v[70:73]
	v_mfma_f32_16x16x32_bf16 v[66:69], v[178:181], v[244:247], v[66:69]
	s_barrier
	s_add_i32 s9, s9, s0
	s_mov_b32 m0, s9
	ds_read_b128 v[182:185], v165 offset:49152
	ds_read_b128 v[206:209], v165 offset:50176
	ds_read_b128 v[210:213], v165 offset:51200
	ds_read_b128 v[214:217], v165 offset:52224
	ds_read_b128 v[218:221], v165 offset:53248
	ds_read_b128 v[236:239], v165 offset:54272
	ds_read_b128 v[240:243], v165 offset:55296
	ds_read_b128 v[244:247], v165 offset:56320
	s_add_u32 s100, s80, s60
	s_addc_u32 s101, s81, s61
	global_load_lds_dwordx4 v132, s[100:101]
	s_add_i32 m0, s9, 0x2000
	s_add_u32 s10, s80, 0x20080
	s_addc_u32 s11, s81, 0
	s_add_i32 s9, s12, s0
	global_load_lds_dwordx4 v136, s[100:101]
	s_mov_b32 m0, s9
	s_nop 0
	global_load_lds_dwordx4 v132, s[10:11]
	s_add_i32 m0, s9, 0x2000
	s_nop 0
	global_load_lds_dwordx4 v136, s[10:11]
	s_mov_b32 m0, s66
	s_add_u32 s100, s84, s60
	s_addc_u32 s101, s85, s61
	global_load_lds_dwordx4 v130, s[100:101]
	s_mov_b32 m0, s67
	s_nop 0
	global_load_lds_dwordx4 v134, s[100:101]
	s_cmp_lg_u32 s54, 0
	s_cbranch_scc1 .Llw_7234
	s_waitcnt vmcnt(8)
	s_waitcnt lgkmcnt(0)
; #define PG8_STAGE(bufoff, gbase, voff) do { _Pragma("unroll") for (int _i = 0; _i < 2; ++_i) \
;         __builtin_amdgcn_global_load_lds((const unsigned*)((const char*)(gbase) + (voff)[_i]), (PG8_LAS unsigned*)(lds + (bufoff) + ldsw + _i * 8192), 16, 0, 0); } while (0)
; #define PG8_LDA(dst, b, h) do { _Pragma("unroll") for (int m = 0; m < 4; ++m) _Pragma("unroll") for (int k = 0; k < 2; ++k) dst[m][k] = *(const PG8_LAS bf16x8*)(lds + PG8_SA(b, h) + aoff + m * 2048 + k * 1024); } while (0)
; #define PG8_LDB(dst, b, h) do { _Pragma("unroll") for (int n = 0; n < 2; ++n) _Pragma("unroll") for (int k = 0; k < 2; ++k) dst[n][k] = *(const PG8_LAS bf16x8*)(lds + PG8_SB(b, h) + boff + n * 2048 + k * 1024); } while (0)
; #define PG8_MMA(ai, bj, At, Bt) do { __builtin_amdgcn_s_setprio(1); _Pragma("unroll") for (int m = 0; m < 4; ++m) _Pragma("unroll") for (int n = 0; n < 2; ++n) _Pragma("unroll") for (int k = 0; k < 2; ++k) \
;         acc[ai][bj][m][n] = __builtin_amdgcn_mfma_f32_16x16x32_bf16(Bt[n][k], At[m][k], acc[ai][bj][m][n], 0, 0, 0); __builtin_amdgcn_s_setprio(0); } while (0)
; #define PG8_WAIT_V(n) asm volatile("s_waitcnt vmcnt(" #n ")" ::: "memory")
; template <class Epi, class Sched, bool ALIGN_EPI = false, bool SP2 = false>
; __device__ __forceinline__ void gemm_phase(PG8_LAS unsigned char* lds, const Gemm g, const Sched& S, const Epi& E) {
;     ...
;             PG8_LDB(B0, 0, 0); PG8_LDB(B1, 0, 1); PG8_SCHED; PG8_LDA(At, 0, 0); PG8_STAGE(PG8_SA(1, 1), a1 + hstep, voffA);
;             PG8_WAIT_V(8); PG8_WAIT_L(0); PG8_BAR; PG8_MMA(0, 0, At, B0); PG8_MMA(0, 1, At, B1); PG8_BAR; PG8_SCHED;
;             PG8_LDA(At, 0, 1); PG8_STAGE(PG8_SB(0, 0), b2, voffB); PG8_STAGE(PG8_SB(0, 1), b2 + hstepB, voffB); PG8_STAGE(PG8_SA(0, 0), a2, voffA);
;             PG8_WAIT_V(8); PG8_WAIT_L(0); PG8_BAR; PG8_MMA(1, 0, At, B0); PG8_MMA(1, 1, At, B1); PG8_BAR; PG8_SCHED;
;             PG8_LDB(B0, 1, 0); PG8_LDB(B1, 1, 1); PG8_SCHED; PG8_LDA(At, 1, 0); PG8_STAGE(PG8_SA(0, 1), a2 + hstep, voffA);
;             PG8_WAIT_V(8); PG8_WAIT_L(0); PG8_BAR; PG8_MMA(0, 0, At, B0); PG8_MMA(0, 1, At, B1); PG8_BAR; PG8_SCHED;
;             PG8_LDA(At, 1, 1); PG8_STAGE(PG8_SB(1, 0), b3, voffB); PG8_STAGE(PG8_SB(1, 1), b3 + hstepB, voffB); PG8_STAGE(PG8_SA(1, 0), a3, voffA);
;             PG8_WAIT_V(8); PG8_WAIT_L(0); PG8_BAR; PG8_MMA(1, 0, At, B0); PG8_MMA(1, 1, At, B1); PG8_BAR; PG8_SCHED;
.Llw_7234:
	s_barrier
	s_waitcnt vmcnt(8)
	s_waitcnt lgkmcnt(0)
	v_mfma_f32_16x16x32_bf16 v[62:65], v[148:151], v[182:185], v[62:65]
	v_mfma_f32_16x16x32_bf16 v[58:61], v[156:159], v[182:185], v[58:61]
	v_mfma_f32_16x16x32_bf16 v[54:57], v[148:151], v[210:213], v[54:57]
	v_mfma_f32_16x16x32_bf16 v[50:53], v[156:159], v[210:213], v[50:53]
	v_mfma_f32_16x16x32_bf16 v[46:49], v[148:151], v[218:221], v[46:49]
	v_mfma_f32_16x16x32_bf16 v[42:45], v[156:159], v[218:221], v[42:45]
	v_mfma_f32_16x16x32_bf16 v[38:41], v[148:151], v[240:243], v[38:41]
	v_mfma_f32_16x16x32_bf16 v[34:37], v[156:159], v[240:243], v[34:37]
	v_mfma_f32_16x16x32_bf16 v[62:65], v[152:155], v[206:209], v[62:65]
	v_mfma_f32_16x16x32_bf16 v[58:61], v[160:163], v[206:209], v[58:61]
	v_mfma_f32_16x16x32_bf16 v[54:57], v[152:155], v[214:217], v[54:57]
	v_mfma_f32_16x16x32_bf16 v[50:53], v[160:163], v[214:217], v[50:53]
	v_mfma_f32_16x16x32_bf16 v[46:49], v[152:155], v[236:239], v[46:49]
	v_mfma_f32_16x16x32_bf16 v[42:45], v[160:163], v[236:239], v[42:45]
	v_mfma_f32_16x16x32_bf16 v[38:41], v[152:155], v[244:247], v[38:41]
	v_mfma_f32_16x16x32_bf16 v[34:37], v[160:163], v[244:247], v[34:37]
	v_mfma_f32_16x16x32_bf16 v[30:33], v[166:169], v[182:185], v[30:33]
	v_mfma_f32_16x16x32_bf16 v[26:29], v[174:177], v[182:185], v[26:29]
	v_mfma_f32_16x16x32_bf16 v[22:25], v[166:169], v[210:213], v[22:25]
	v_mfma_f32_16x16x32_bf16 v[18:21], v[174:177], v[210:213], v[18:21]
	v_mfma_f32_16x16x32_bf16 v[14:17], v[166:169], v[218:221], v[14:17]
	v_mfma_f32_16x16x32_bf16 v[10:13], v[174:177], v[218:221], v[10:13]
	v_mfma_f32_16x16x32_bf16 v[6:9], v[166:169], v[240:243], v[6:9]
	v_mfma_f32_16x16x32_bf16 v[2:5], v[174:177], v[240:243], v[2:5]
	v_mfma_f32_16x16x32_bf16 v[30:33], v[170:173], v[206:209], v[30:33]
	v_mfma_f32_16x16x32_bf16 v[26:29], v[178:181], v[206:209], v[26:29]
	v_mfma_f32_16x16x32_bf16 v[22:25], v[170:173], v[214:217], v[22:25]
	v_mfma_f32_16x16x32_bf16 v[18:21], v[178:181], v[214:217], v[18:21]
	v_mfma_f32_16x16x32_bf16 v[14:17], v[170:173], v[236:239], v[14:17]
	v_mfma_f32_16x16x32_bf16 v[10:13], v[178:181], v[236:239], v[10:13]
	v_mfma_f32_16x16x32_bf16 v[6:9], v[170:173], v[244:247], v[6:9]
	v_mfma_f32_16x16x32_bf16 v[2:5], v[178:181], v[244:247], v[2:5]
	s_barrier
	s_add_i32 s8, s8, 2
	s_add_u32 s46, s46, 0x100
	s_addc_u32 s47, s47, 0
	s_cmp_gt_u32 s8, 29
.LBB0_170:
	s_add_u32 s9, s70, s46
	s_addc_u32 s10, s71, s47
	s_add_u32 s9, s9, 0x100
	s_addc_u32 s10, s10, 0
	s_add_u32 s100, s9, 0x7ff80
	s_addc_u32 s101, s10, 0
	s_add_u32 s11, s93, s46
	s_addc_u32 s12, s94, s47
	s_add_i32 s13, 0, 0x10000
	s_cmpk_eq_i32 s46, 0xf00
	s_cselect_b32 s85, s4, s10
	s_cselect_b32 s84, s5, s9
	s_cselect_b32 s81, s6, s12
	s_cselect_b32 s80, s7, s11
	s_add_i32 s9, 0, 0x14000
	ds_read_b128 v[148:151], v186
	ds_read_b128 v[152:155], v186 offset:1024
	ds_read_b128 v[156:159], v186 offset:2048
	ds_read_b128 v[160:163], v186 offset:3072
	ds_read_b128 v[166:169], v187
	ds_read_b128 v[170:173], v187 offset:1024
	ds_read_b128 v[174:177], v187 offset:2048
	ds_read_b128 v[178:181], v187 offset:3072
	s_add_i32 m0, s1, 0xc000
	ds_read_b128 v[182:185], v165
	ds_read_b128 v[206:209], v165 offset:1024
	ds_read_b128 v[210:213], v165 offset:2048
	ds_read_b128 v[214:217], v165 offset:3072
	ds_read_b128 v[218:221], v165 offset:4096
	ds_read_b128 v[236:239], v165 offset:5120
	ds_read_b128 v[240:243], v165 offset:6144
	ds_read_b128 v[244:247], v165 offset:7168
	global_load_lds_dwordx4 v140, s[100:101]
	s_add_i32 m0, s1, 0xe000
	s_nop 0
	global_load_lds_dwordx4 v142, s[100:101]
	s_cmp_lg_u32 s54, 0
	s_cbranch_scc1 .Llw_7319
	s_waitcnt vmcnt(8)
	s_waitcnt lgkmcnt(0)
; #define PG8_STAGE(bufoff, gbase, voff) do { _Pragma("unroll") for (int _i = 0; _i < 2; ++_i) \
;         __builtin_amdgcn_global_load_lds((const unsigned*)((const char*)(gbase) + (voff)[_i]), (PG8_LAS unsigned*)(lds + (bufoff) + ldsw + _i * 8192), 16, 0, 0); } while (0)
; #define PG8_LDA(dst, b, h) do { _Pragma("unroll") for (int m = 0; m < 4; ++m) _Pragma("unroll") for (int k = 0; k < 2; ++k) dst[m][k] = *(const PG8_LAS bf16x8*)(lds + PG8_SA(b, h) + aoff + m * 2048 + k * 1024); } while (0)
; #define PG8_LDB(dst, b, h) do { _Pragma("unroll") for (int n = 0; n < 2; ++n) _Pragma("unroll") for (int k = 0; k < 2; ++k) dst[n][k] = *(const PG8_LAS bf16x8*)(lds + PG8_SB(b, h) + boff + n * 2048 + k * 1024); } while (0)
; #define PG8_MMA(ai, bj, At, Bt) do { __builtin_amdgcn_s_setprio(1); _Pragma("unroll") for (int m = 0; m < 4; ++m) _Pragma("unroll") for (int n = 0; n < 2; ++n) _Pragma("unroll") for (int k = 0; k < 2; ++k) \
;         acc[ai][bj][m][n] = __builtin_amdgcn_mfma_f32_16x16x32_bf16(Bt[n][k], At[m][k], acc[ai][bj][m][n], 0, 0, 0); __builtin_amdgcn_s_setprio(0); } while (0)
; #define PG8_WAIT_V(n) asm volatile("s_waitcnt vmcnt(" #n ")" ::: "memory")
; #define PG8_WAIT_L(n) asm volatile("s_waitcnt lgkmcnt(" #n ")" ::: "memory")
; #define PG8_BAR __builtin_amdgcn_s_barrier()
; #define PG8_SCHED __builtin_amdgcn_sched_barrier(0)
; template <class Epi, class Sched, bool ALIGN_EPI = false, bool SP2 = false>
; __device__ __forceinline__ void gemm_phase(PG8_LAS unsigned char* lds, const Gemm g, const Sched& S, const Epi& E) {
;     ...
;             PG8_WAIT_V(8); PG8_WAIT_L(0); PG8_BAR; PG8_MMA(0, 0, At, B0); PG8_MMA(0, 1, At, B1); PG8_BAR; PG8_SCHED;
;             PG8_LDA(At, 0, 1); PG8_STAGE(PG8_SB(0, 0), b2, voffB); PG8_STAGE(PG8_SB(0, 1), b2 + hstepB, voffB); PG8_STAGE(PG8_SA(0, 0), a2, voffA);
;             PG8_WAIT_V(8); PG8_WAIT_L(0); PG8_BAR; PG8_MMA(1, 0, At, B0); PG8_MMA(1, 1, At, B1); PG8_BAR; PG8_SCHED;
;             PG8_LDB(B0, 1, 0); PG8_LDB(B1, 1, 1); PG8_SCHED; PG8_LDA(At, 1, 0); PG8_STAGE(PG8_SA(0, 1), a2 + hstep, voffA);
;             PG8_WAIT_V(8); PG8_WAIT_L(0); PG8_BAR; PG8_MMA(0, 0, At, B0); PG8_MMA(0, 1, At, B1); PG8_BAR; PG8_SCHED;
.Llw_7319:
	s_barrier
	s_waitcnt vmcnt(8)
	s_waitcnt lgkmcnt(0)
	v_mfma_f32_16x16x32_bf16 v[126:129], v[148:151], v[182:185], v[126:129]
	v_mfma_f32_16x16x32_bf16 v[122:125], v[156:159], v[182:185], v[122:125]
	v_mfma_f32_16x16x32_bf16 v[118:121], v[148:151], v[210:213], v[118:121]
	v_mfma_f32_16x16x32_bf16 v[114:117], v[156:159], v[210:213], v[114:117]
	v_mfma_f32_16x16x32_bf16 v[110:113], v[148:151], v[218:221], v[110:113]
	v_mfma_f32_16x16x32_bf16 v[106:109], v[156:159], v[218:221], v[106:109]
	v_mfma_f32_16x16x32_bf16 v[102:105], v[148:151], v[240:243], v[102:105]
	v_mfma_f32_16x16x32_bf16 v[98:101], v[156:159], v[240:243], v[98:101]
	v_mfma_f32_16x16x32_bf16 v[126:129], v[152:155], v[206:209], v[126:129]
	v_mfma_f32_16x16x32_bf16 v[122:125], v[160:163], v[206:209], v[122:125]
	v_mfma_f32_16x16x32_bf16 v[118:121], v[152:155], v[214:217], v[118:121]
	v_mfma_f32_16x16x32_bf16 v[114:117], v[160:163], v[214:217], v[114:117]
	v_mfma_f32_16x16x32_bf16 v[110:113], v[152:155], v[236:239], v[110:113]
	v_mfma_f32_16x16x32_bf16 v[106:109], v[160:163], v[236:239], v[106:109]
	v_mfma_f32_16x16x32_bf16 v[102:105], v[152:155], v[244:247], v[102:105]
	v_mfma_f32_16x16x32_bf16 v[98:101], v[160:163], v[244:247], v[98:101]
	v_mfma_f32_16x16x32_bf16 v[94:97], v[166:169], v[182:185], v[94:97]
	v_mfma_f32_16x16x32_bf16 v[90:93], v[174:177], v[182:185], v[90:93]
	v_mfma_f32_16x16x32_bf16 v[86:89], v[166:169], v[210:213], v[86:89]
	v_mfma_f32_16x16x32_bf16 v[82:85], v[174:177], v[210:213], v[82:85]
	v_mfma_f32_16x16x32_bf16 v[78:81], v[166:169], v[218:221], v[78:81]
	v_mfma_f32_16x16x32_bf16 v[74:77], v[174:177], v[218:221], v[74:77]
	v_mfma_f32_16x16x32_bf16 v[70:73], v[166:169], v[240:243], v[70:73]
	v_mfma_f32_16x16x32_bf16 v[66:69], v[174:177], v[240:243], v[66:69]
	v_mfma_f32_16x16x32_bf16 v[94:97], v[170:173], v[206:209], v[94:97]
	v_mfma_f32_16x16x32_bf16 v[90:93], v[178:181], v[206:209], v[90:93]
	v_mfma_f32_16x16x32_bf16 v[86:89], v[170:173], v[214:217], v[86:89]
	v_mfma_f32_16x16x32_bf16 v[82:85], v[178:181], v[214:217], v[82:85]
	v_mfma_f32_16x16x32_bf16 v[78:81], v[170:173], v[236:239], v[78:81]
	v_mfma_f32_16x16x32_bf16 v[74:77], v[178:181], v[236:239], v[74:77]
	v_mfma_f32_16x16x32_bf16 v[70:73], v[170:173], v[244:247], v[70:73]
	v_mfma_f32_16x16x32_bf16 v[66:69], v[178:181], v[244:247], v[66:69]
	s_barrier
	s_add_i32 s10, s13, s0
	s_mov_b32 m0, s10
	ds_read_b128 v[182:185], v165 offset:16384
	ds_read_b128 v[206:209], v165 offset:17408
	ds_read_b128 v[210:213], v165 offset:18432
	ds_read_b128 v[214:217], v165 offset:19456
	ds_read_b128 v[218:221], v165 offset:20480
	ds_read_b128 v[236:239], v165 offset:21504
	ds_read_b128 v[240:243], v165 offset:22528
	ds_read_b128 v[244:247], v165 offset:23552
	global_load_lds_dwordx4 v132, s[80:81]
	s_add_i32 m0, s10, 0x2000
	s_add_u32 s10, s80, 0x20000
	s_addc_u32 s11, s81, 0
	s_add_i32 s9, s9, s0
	global_load_lds_dwordx4 v136, s[80:81]
	s_mov_b32 m0, s9
	s_nop 0
	global_load_lds_dwordx4 v132, s[10:11]
	s_add_i32 m0, s9, 0x2000
	s_nop 0
	global_load_lds_dwordx4 v136, s[10:11]
	s_mov_b32 m0, s1
	s_nop 0
	global_load_lds_dwordx4 v130, s[84:85]
	s_mov_b32 m0, s25
	s_nop 0
	global_load_lds_dwordx4 v134, s[84:85]
	s_cmp_lg_u32 s54, 0
	s_cbranch_scc1 .Llw_7388
	s_waitcnt vmcnt(8)
	s_waitcnt lgkmcnt(0)
.Llw_7388:
	s_barrier
	s_waitcnt vmcnt(8)
	s_waitcnt lgkmcnt(0)
	v_mfma_f32_16x16x32_bf16 v[62:65], v[148:151], v[182:185], v[62:65]
	v_mfma_f32_16x16x32_bf16 v[58:61], v[156:159], v[182:185], v[58:61]
	v_mfma_f32_16x16x32_bf16 v[54:57], v[148:151], v[210:213], v[54:57]
	v_mfma_f32_16x16x32_bf16 v[50:53], v[156:159], v[210:213], v[50:53]
	v_mfma_f32_16x16x32_bf16 v[46:49], v[148:151], v[218:221], v[46:49]
	v_mfma_f32_16x16x32_bf16 v[42:45], v[156:159], v[218:221], v[42:45]
	v_mfma_f32_16x16x32_bf16 v[38:41], v[148:151], v[240:243], v[38:41]
	v_mfma_f32_16x16x32_bf16 v[34:37], v[156:159], v[240:243], v[34:37]
	v_mfma_f32_16x16x32_bf16 v[62:65], v[152:155], v[206:209], v[62:65]
	v_mfma_f32_16x16x32_bf16 v[58:61], v[160:163], v[206:209], v[58:61]
	v_mfma_f32_16x16x32_bf16 v[54:57], v[152:155], v[214:217], v[54:57]
	v_mfma_f32_16x16x32_bf16 v[50:53], v[160:163], v[214:217], v[50:53]
	v_mfma_f32_16x16x32_bf16 v[46:49], v[152:155], v[236:239], v[46:49]
	v_mfma_f32_16x16x32_bf16 v[42:45], v[160:163], v[236:239], v[42:45]
	v_mfma_f32_16x16x32_bf16 v[38:41], v[152:155], v[244:247], v[38:41]
	v_mfma_f32_16x16x32_bf16 v[34:37], v[160:163], v[244:247], v[34:37]
	v_mfma_f32_16x16x32_bf16 v[30:33], v[166:169], v[182:185], v[30:33]
	v_mfma_f32_16x16x32_bf16 v[26:29], v[174:177], v[182:185], v[26:29]
	v_mfma_f32_16x16x32_bf16 v[22:25], v[166:169], v[210:213], v[22:25]
	v_mfma_f32_16x16x32_bf16 v[18:21], v[174:177], v[210:213], v[18:21]
	v_mfma_f32_16x16x32_bf16 v[14:17], v[166:169], v[218:221], v[14:17]
	v_mfma_f32_16x16x32_bf16 v[10:13], v[174:177], v[218:221], v[10:13]
	v_mfma_f32_16x16x32_bf16 v[6:9], v[166:169], v[240:243], v[6:9]
	v_mfma_f32_16x16x32_bf16 v[2:5], v[174:177], v[240:243], v[2:5]
	v_mfma_f32_16x16x32_bf16 v[30:33], v[170:173], v[206:209], v[30:33]
	v_mfma_f32_16x16x32_bf16 v[26:29], v[178:181], v[206:209], v[26:29]
	v_mfma_f32_16x16x32_bf16 v[22:25], v[170:173], v[214:217], v[22:25]
	v_mfma_f32_16x16x32_bf16 v[18:21], v[178:181], v[214:217], v[18:21]
	v_mfma_f32_16x16x32_bf16 v[14:17], v[170:173], v[236:239], v[14:17]
	v_mfma_f32_16x16x32_bf16 v[10:13], v[178:181], v[236:239], v[10:13]
	v_mfma_f32_16x16x32_bf16 v[6:9], v[170:173], v[244:247], v[6:9]
	v_mfma_f32_16x16x32_bf16 v[2:5], v[178:181], v[244:247], v[2:5]
	s_barrier
	s_add_i32 s9, 0, 0x18000
	s_add_i32 s12, 0, 0x1c000
	ds_read_b128 v[148:151], v198
	ds_read_b128 v[152:155], v198 offset:1024
	ds_read_b128 v[156:159], v198 offset:2048
	ds_read_b128 v[160:163], v198 offset:3072
	ds_read_b128 v[166:169], v199
	ds_read_b128 v[170:173], v199 offset:1024
	ds_read_b128 v[174:177], v199 offset:2048
	ds_read_b128 v[178:181], v199 offset:3072
	s_add_u32 s10, s84, 0x80000
	s_addc_u32 s11, s85, 0
	s_mov_b32 m0, s42
	ds_read_b128 v[182:185], v165 offset:32768
	ds_read_b128 v[206:209], v165 offset:33792
	ds_read_b128 v[210:213], v165 offset:34816
	ds_read_b128 v[214:217], v165 offset:35840
	ds_read_b128 v[218:221], v165 offset:36864
	ds_read_b128 v[236:239], v165 offset:37888
	ds_read_b128 v[240:243], v165 offset:38912
	ds_read_b128 v[244:247], v165 offset:39936
	global_load_lds_dwordx4 v130, s[10:11]
	s_mov_b32 m0, s51
	s_nop 0
	global_load_lds_dwordx4 v134, s[10:11]
	s_cmp_lg_u32 s54, 0
	s_cbranch_scc1 .Llw_7455
	s_waitcnt vmcnt(8)
	s_waitcnt lgkmcnt(0)

; #define PG8_STAGE(bufoff, gbase, voff) do { _Pragma("unroll") for (int _i = 0; _i < 2; ++_i) \
;         __builtin_amdgcn_global_load_lds((const unsigned*)((const char*)(gbase) + (voff)[_i]), (PG8_LAS unsigned*)(lds + (bufoff) + ldsw + _i * 8192), 16, 0, 0); } while (0)
; #define PG8_LDA(dst, b, h) do { _Pragma("unroll") for (int m = 0; m < 4; ++m) _Pragma("unroll") for (int k = 0; k < 2; ++k) dst[m][k] = *(const PG8_LAS bf16x8*)(lds + PG8_SA(b, h) + aoff + m * 2048 + k * 1024); } while (0)
; #define PG8_MMA(ai, bj, At, Bt) do { __builtin_amdgcn_s_setprio(1); _Pragma("unroll") for (int m = 0; m < 4; ++m) _Pragma("unroll") for (int n = 0; n < 2; ++n) _Pragma("unroll") for (int k = 0; k < 2; ++k) \
;         acc[ai][bj][m][n] = __builtin_amdgcn_mfma_f32_16x16x32_bf16(Bt[n][k], At[m][k], acc[ai][bj][m][n], 0, 0, 0); __builtin_amdgcn_s_setprio(0); } while (0)
; #define PG8_WAIT_V(n) asm volatile("s_waitcnt vmcnt(" #n ")" ::: "memory")
; #define PG8_WAIT_L(n) asm volatile("s_waitcnt lgkmcnt(" #n ")" ::: "memory")
; #define PG8_BAR __builtin_amdgcn_s_barrier()
; #define PG8_SCHED __builtin_amdgcn_sched_barrier(0)
; template <class Epi, class Sched, bool ALIGN_EPI = false, bool SP2 = false>
; __device__ __forceinline__ void gemm_phase(PG8_LAS unsigned char* lds, const Gemm g, const Sched& S, const Epi& E) {
;     ...
;             PG8_LDA(At, 1, 1); PG8_STAGE(PG8_SB(1, 0), b3, voffB); PG8_STAGE(PG8_SB(1, 1), b3 + hstepB, voffB); PG8_STAGE(PG8_SA(1, 0), a3, voffA);
;             PG8_WAIT_V(8); PG8_WAIT_L(0); PG8_BAR; PG8_MMA(1, 0, At, B0); PG8_MMA(1, 1, At, B1); PG8_BAR; PG8_SCHED;
;     ...
;         if constexpr (ALIGN_EPI) { if (wr == 0) PG8_BAR; }
;         if constexpr (!Epi::AFTER_DRAIN) { E(acc, cur, wr, wc, fr, fq, ui); S.done(cur); }
;         if (!has_next) break;
.Llw_7527:
	s_barrier
	s_waitcnt vmcnt(8)
	s_waitcnt lgkmcnt(0)
	v_mfma_f32_16x16x32_bf16 v[62:65], v[148:151], v[182:185], v[62:65]
	v_mfma_f32_16x16x32_bf16 v[58:61], v[156:159], v[182:185], v[58:61]
	v_mfma_f32_16x16x32_bf16 v[54:57], v[148:151], v[210:213], v[54:57]
	v_mfma_f32_16x16x32_bf16 v[50:53], v[156:159], v[210:213], v[50:53]
	v_mfma_f32_16x16x32_bf16 v[46:49], v[148:151], v[218:221], v[46:49]
	v_mfma_f32_16x16x32_bf16 v[42:45], v[156:159], v[218:221], v[42:45]
	v_mfma_f32_16x16x32_bf16 v[38:41], v[148:151], v[240:243], v[38:41]
	v_mfma_f32_16x16x32_bf16 v[34:37], v[156:159], v[240:243], v[34:37]
	v_mfma_f32_16x16x32_bf16 v[62:65], v[152:155], v[206:209], v[62:65]
	v_mfma_f32_16x16x32_bf16 v[58:61], v[160:163], v[206:209], v[58:61]
	v_mfma_f32_16x16x32_bf16 v[54:57], v[152:155], v[214:217], v[54:57]
	v_mfma_f32_16x16x32_bf16 v[50:53], v[160:163], v[214:217], v[50:53]
	v_mfma_f32_16x16x32_bf16 v[46:49], v[152:155], v[236:239], v[46:49]
	v_mfma_f32_16x16x32_bf16 v[42:45], v[160:163], v[236:239], v[42:45]
	v_mfma_f32_16x16x32_bf16 v[38:41], v[152:155], v[244:247], v[38:41]
	v_mfma_f32_16x16x32_bf16 v[34:37], v[160:163], v[244:247], v[34:37]
	v_mfma_f32_16x16x32_bf16 v[30:33], v[166:169], v[182:185], v[30:33]
	v_mfma_f32_16x16x32_bf16 v[26:29], v[174:177], v[182:185], v[26:29]
	v_mfma_f32_16x16x32_bf16 v[22:25], v[166:169], v[210:213], v[22:25]
	v_mfma_f32_16x16x32_bf16 v[18:21], v[174:177], v[210:213], v[18:21]
	v_mfma_f32_16x16x32_bf16 v[14:17], v[166:169], v[218:221], v[14:17]
	v_mfma_f32_16x16x32_bf16 v[10:13], v[174:177], v[218:221], v[10:13]
	v_mfma_f32_16x16x32_bf16 v[6:9], v[166:169], v[240:243], v[6:9]
	v_mfma_f32_16x16x32_bf16 v[2:5], v[174:177], v[240:243], v[2:5]
	v_mfma_f32_16x16x32_bf16 v[30:33], v[170:173], v[206:209], v[30:33]
	v_mfma_f32_16x16x32_bf16 v[26:29], v[178:181], v[206:209], v[26:29]
	v_mfma_f32_16x16x32_bf16 v[22:25], v[170:173], v[214:217], v[22:25]
	v_mfma_f32_16x16x32_bf16 v[18:21], v[178:181], v[214:217], v[18:21]
	v_mfma_f32_16x16x32_bf16 v[14:17], v[170:173], v[236:239], v[14:17]
	v_mfma_f32_16x16x32_bf16 v[10:13], v[178:181], v[236:239], v[10:13]
	v_mfma_f32_16x16x32_bf16 v[6:9], v[170:173], v[244:247], v[6:9]
	v_mfma_f32_16x16x32_bf16 v[2:5], v[178:181], v[244:247], v[2:5]
	s_barrier
	s_add_i32 s8, s8, 2
	s_add_u32 s46, s46, 0x100
	s_addc_u32 s47, s47, 0
	s_cmp_gt_u32 s8, 29
	s_cbranch_scc0 .LBB0_170
	s_and_b64 vcc, exec, s[54:55]
	s_cbranch_vccz .LBB0_173
	s_barrier

; #define PG8_STAGE(bufoff, gbase, voff) do { _Pragma("unroll") for (int _i = 0; _i < 2; ++_i) \
;         __builtin_amdgcn_global_load_lds((const unsigned*)((const char*)(gbase) + (voff)[_i]), (PG8_LAS unsigned*)(lds + (bufoff) + ldsw + _i * 8192), 16, 0, 0); } while (0)
; #define PG8_LDA(dst, b, h) do { _Pragma("unroll") for (int m = 0; m < 4; ++m) _Pragma("unroll") for (int k = 0; k < 2; ++k) dst[m][k] = *(const PG8_LAS bf16x8*)(lds + PG8_SA(b, h) + aoff + m * 2048 + k * 1024); } while (0)
; #define PG8_LDB(dst, b, h) do { _Pragma("unroll") for (int n = 0; n < 2; ++n) _Pragma("unroll") for (int k = 0; k < 2; ++k) dst[n][k] = *(const PG8_LAS bf16x8*)(lds + PG8_SB(b, h) + boff + n * 2048 + k * 1024); } while (0)
; #define PG8_MMA(ai, bj, At, Bt) do { __builtin_amdgcn_s_setprio(1); _Pragma("unroll") for (int m = 0; m < 4; ++m) _Pragma("unroll") for (int n = 0; n < 2; ++n) _Pragma("unroll") for (int k = 0; k < 2; ++k) \
;         acc[ai][bj][m][n] = __builtin_amdgcn_mfma_f32_16x16x32_bf16(Bt[n][k], At[m][k], acc[ai][bj][m][n], 0, 0, 0); __builtin_amdgcn_s_setprio(0); } while (0)
; #define PG8_WAIT_V(n) asm volatile("s_waitcnt vmcnt(" #n ")" ::: "memory")
; #define PG8_WAIT_L(n) asm volatile("s_waitcnt lgkmcnt(" #n ")" ::: "memory")
; #define PG8_BAR __builtin_amdgcn_s_barrier()
; template <class Epi, class Sched, bool ALIGN_EPI = false, bool SP2 = false>
; __device__ __forceinline__ void gemm_phase(PG8_LAS unsigned char* lds, const Gemm g, const Sched& S, const Epi& E) {
;     ...
;             const char* a1 = cA + (size_t)(t + 1) * kstep;
;             const char* a2 = last ? nA : cA + (size_t)(t + 2) * kstep; const char* b2 = last ? nB : cB + (size_t)(t + 2) * kstep;
;             const char* a3 = a2 + kstep; const char* b3 = b2 + kstep;
;             if (last && has_next) S.a_ready(nxt);
;             if constexpr (SP2) {
;             PG8_LDB(B0, 0, 0); PG8_LDB(B1, 0, 1); PG8_SCHED; PG8_LDA(At, 0, 0); PG8_STAGE(PG8_SA(1, 1), a1 + hstep, voffA);
;             PG8_WAIT_V(8); PG8_WAIT_L(0); PG8_BAR; PG8_MMA(0, 0, At, B0); PG8_MMA(0, 1, At, B1); PG8_BAR; PG8_SCHED;
;             PG8_LDA(At, 0, 1); PG8_STAGE(PG8_SB(0, 0), b2, voffB); PG8_STAGE(PG8_SB(0, 1), b2 + hstepB, voffB); PG8_STAGE(PG8_SA(0, 0), a2, voffA);
;             PG8_WAIT_V(8); PG8_WAIT_L(0); PG8_BAR; PG8_MMA(1, 0, At, B0); PG8_MMA(1, 1, At, B1); PG8_BAR; PG8_SCHED;
.LBB0_788:
	s_add_u32 s9, s68, 0xfffe0080
	s_addc_u32 s10, s69, -1
	s_add_i32 s11, 0, 0x10000
	s_cmp_eq_u32 s8, 4
	s_cselect_b32 s77, s36, s10
	s_cselect_b32 s76, s37, s9
	s_cselect_b32 s73, s4, s7
	s_cselect_b32 s72, s5, s6
	s_add_i32 s9, 0, 0x14000
	ds_read_b128 v[34:37], v186
	ds_read_b128 v[38:41], v186 offset:1024
	ds_read_b128 v[50:53], v186 offset:2048
	ds_read_b128 v[54:57], v186 offset:3072
	ds_read_b128 v[114:117], v187
	ds_read_b128 v[126:129], v187 offset:1024
	ds_read_b128 v[138:141], v187 offset:2048
	ds_read_b128 v[150:153], v187 offset:3072
	s_add_i32 m0, s66, 0xc000
	ds_read_b128 v[154:157], v217
	ds_read_b128 v[158:161], v217 offset:1024
	ds_read_b128 v[170:173], v217 offset:2048
	ds_read_b128 v[206:209], v217 offset:3072
	ds_read_b128 v[210:213], v217 offset:4096
	ds_read_b128 v[218:221], v217 offset:5120
	ds_read_b128 v[236:239], v217 offset:6144
	ds_read_b128 v[240:243], v217 offset:7168
	global_load_lds_dwordx4 v180, s[68:69]
	s_add_i32 m0, s66, 0xe000
	s_nop 0
	global_load_lds_dwordx4 v182, s[68:69]
	s_cmp_lg_u32 s46, 0
	s_cbranch_scc1 .Llw_20542
	s_waitcnt vmcnt(8)
	s_waitcnt lgkmcnt(0)
.Llw_20542:
	s_barrier
	s_waitcnt vmcnt(8)
	s_waitcnt lgkmcnt(0)
	v_mfma_f32_16x16x32_bf16 v[166:169], v[34:37], v[154:157], v[166:169]
	v_mfma_f32_16x16x32_bf16 v[162:165], v[50:53], v[154:157], v[162:165]
	v_mfma_f32_16x16x32_bf16 v[134:137], v[34:37], v[170:173], v[134:137]
	v_mfma_f32_16x16x32_bf16 v[130:133], v[50:53], v[170:173], v[130:133]
	v_mfma_f32_16x16x32_bf16 v[110:113], v[34:37], v[210:213], v[110:113]
	v_mfma_f32_16x16x32_bf16 v[106:109], v[50:53], v[210:213], v[106:109]
	v_mfma_f32_16x16x32_bf16 v[94:97], v[34:37], v[236:239], v[94:97]
	v_mfma_f32_16x16x32_bf16 v[90:93], v[50:53], v[236:239], v[90:93]
	v_mfma_f32_16x16x32_bf16 v[166:169], v[38:41], v[158:161], v[166:169]
	v_mfma_f32_16x16x32_bf16 v[162:165], v[54:57], v[158:161], v[162:165]
	v_mfma_f32_16x16x32_bf16 v[134:137], v[38:41], v[206:209], v[134:137]
	v_mfma_f32_16x16x32_bf16 v[130:133], v[54:57], v[206:209], v[130:133]
	v_mfma_f32_16x16x32_bf16 v[110:113], v[38:41], v[218:221], v[110:113]
	v_mfma_f32_16x16x32_bf16 v[106:109], v[54:57], v[218:221], v[106:109]
	v_mfma_f32_16x16x32_bf16 v[94:97], v[38:41], v[240:243], v[94:97]
	v_mfma_f32_16x16x32_bf16 v[90:93], v[54:57], v[240:243], v[90:93]
	v_mfma_f32_16x16x32_bf16 v[146:149], v[114:117], v[154:157], v[146:149]
	v_mfma_f32_16x16x32_bf16 v[142:145], v[138:141], v[154:157], v[142:145]
	v_mfma_f32_16x16x32_bf16 v[122:125], v[114:117], v[170:173], v[122:125]
	v_mfma_f32_16x16x32_bf16 v[118:121], v[138:141], v[170:173], v[118:121]
	v_mfma_f32_16x16x32_bf16 v[102:105], v[114:117], v[210:213], v[102:105]
	v_mfma_f32_16x16x32_bf16 v[98:101], v[138:141], v[210:213], v[98:101]
	v_mfma_f32_16x16x32_bf16 v[86:89], v[114:117], v[236:239], v[86:89]
	v_mfma_f32_16x16x32_bf16 v[82:85], v[138:141], v[236:239], v[82:85]
	v_mfma_f32_16x16x32_bf16 v[146:149], v[126:129], v[158:161], v[146:149]
	v_mfma_f32_16x16x32_bf16 v[142:145], v[150:153], v[158:161], v[142:145]
	v_mfma_f32_16x16x32_bf16 v[122:125], v[126:129], v[206:209], v[122:125]
	v_mfma_f32_16x16x32_bf16 v[118:121], v[150:153], v[206:209], v[118:121]
	v_mfma_f32_16x16x32_bf16 v[102:105], v[126:129], v[218:221], v[102:105]
	v_mfma_f32_16x16x32_bf16 v[98:101], v[150:153], v[218:221], v[98:101]
	v_mfma_f32_16x16x32_bf16 v[86:89], v[126:129], v[240:243], v[86:89]
	v_mfma_f32_16x16x32_bf16 v[82:85], v[150:153], v[240:243], v[82:85]
	s_barrier
	s_add_i32 s10, s11, s25
	s_mov_b32 m0, s10
	ds_read_b128 v[154:157], v217 offset:16384
	ds_read_b128 v[158:161], v217 offset:17408
	ds_read_b128 v[170:173], v217 offset:18432
	ds_read_b128 v[206:209], v217 offset:19456
	ds_read_b128 v[210:213], v217 offset:20480
	ds_read_b128 v[218:221], v217 offset:21504
	ds_read_b128 v[236:239], v217 offset:22528
	ds_read_b128 v[240:243], v217 offset:23552
	global_load_lds_dwordx4 v190, s[72:73]
	s_add_i32 m0, s10, 0x2000
	s_add_u32 s10, s72, 0x8000
	s_addc_u32 s11, s73, 0
	s_add_i32 s9, s9, s25
	global_load_lds_dwordx4 v174, s[72:73]
	s_mov_b32 m0, s9
	s_nop 0
	global_load_lds_dwordx4 v190, s[10:11]
	s_add_i32 m0, s9, 0x2000
	s_nop 0
	global_load_lds_dwordx4 v174, s[10:11]
	s_mov_b32 m0, s66
	s_nop 0
	global_load_lds_dwordx4 v178, s[76:77]
	s_mov_b32 m0, s67
	s_nop 0
	global_load_lds_dwordx4 v176, s[76:77]
	s_cmp_lg_u32 s46, 0
	s_cbranch_scc1 .Llw_20611
	s_waitcnt vmcnt(8)
	s_waitcnt lgkmcnt(0)
; #define PG8_STAGE(bufoff, gbase, voff) do { _Pragma("unroll") for (int _i = 0; _i < 2; ++_i) \
;         __builtin_amdgcn_global_load_lds((const unsigned*)((const char*)(gbase) + (voff)[_i]), (PG8_LAS unsigned*)(lds + (bufoff) + ldsw + _i * 8192), 16, 0, 0); } while (0)
; #define PG8_LDA(dst, b, h) do { _Pragma("unroll") for (int m = 0; m < 4; ++m) _Pragma("unroll") for (int k = 0; k < 2; ++k) dst[m][k] = *(const PG8_LAS bf16x8*)(lds + PG8_SA(b, h) + aoff + m * 2048 + k * 1024); } while (0)
; #define PG8_LDB(dst, b, h) do { _Pragma("unroll") for (int n = 0; n < 2; ++n) _Pragma("unroll") for (int k = 0; k < 2; ++k) dst[n][k] = *(const PG8_LAS bf16x8*)(lds + PG8_SB(b, h) + boff + n * 2048 + k * 1024); } while (0)
; #define PG8_MMA(ai, bj, At, Bt) do { __builtin_amdgcn_s_setprio(1); _Pragma("unroll") for (int m = 0; m < 4; ++m) _Pragma("unroll") for (int n = 0; n < 2; ++n) _Pragma("unroll") for (int k = 0; k < 2; ++k) \
;         acc[ai][bj][m][n] = __builtin_amdgcn_mfma_f32_16x16x32_bf16(Bt[n][k], At[m][k], acc[ai][bj][m][n], 0, 0, 0); __builtin_amdgcn_s_setprio(0); } while (0)
; #define PG8_WAIT_V(n) asm volatile("s_waitcnt vmcnt(" #n ")" ::: "memory")
; #define PG8_WAIT_L(n) asm volatile("s_waitcnt lgkmcnt(" #n ")" ::: "memory")
; #define PG8_BAR __builtin_amdgcn_s_barrier()
; #define PG8_SCHED __builtin_amdgcn_sched_barrier(0)
; template <class Epi, class Sched, bool ALIGN_EPI = false, bool SP2 = false>
; __device__ __forceinline__ void gemm_phase(PG8_LAS unsigned char* lds, const Gemm g, const Sched& S, const Epi& E) {
;     ...
;             PG8_WAIT_V(8); PG8_WAIT_L(0); PG8_BAR; PG8_MMA(1, 0, At, B0); PG8_MMA(1, 1, At, B1); PG8_BAR; PG8_SCHED;
;             PG8_LDB(B0, 1, 0); PG8_LDB(B1, 1, 1); PG8_SCHED; PG8_LDA(At, 1, 0); PG8_STAGE(PG8_SA(0, 1), a2 + hstep, voffA);
;             PG8_WAIT_V(8); PG8_WAIT_L(0); PG8_BAR; PG8_MMA(0, 0, At, B0); PG8_MMA(0, 1, At, B1); PG8_BAR; PG8_SCHED;
.Llw_20611:
	s_barrier
	s_waitcnt vmcnt(8)
	s_waitcnt lgkmcnt(0)
	v_mfma_f32_16x16x32_bf16 v[78:81], v[34:37], v[154:157], v[78:81]
	v_mfma_f32_16x16x32_bf16 v[74:77], v[50:53], v[154:157], v[74:77]
	v_mfma_f32_16x16x32_bf16 v[62:65], v[34:37], v[170:173], v[62:65]
	v_mfma_f32_16x16x32_bf16 v[58:61], v[50:53], v[170:173], v[58:61]
	v_mfma_f32_16x16x32_bf16 v[30:33], v[34:37], v[210:213], v[30:33]
	v_mfma_f32_16x16x32_bf16 v[26:29], v[50:53], v[210:213], v[26:29]
	v_mfma_f32_16x16x32_bf16 v[14:17], v[34:37], v[236:239], v[14:17]
	v_mfma_f32_16x16x32_bf16 v[10:13], v[50:53], v[236:239], v[10:13]
	v_mfma_f32_16x16x32_bf16 v[78:81], v[38:41], v[158:161], v[78:81]
	v_mfma_f32_16x16x32_bf16 v[74:77], v[54:57], v[158:161], v[74:77]
	v_mfma_f32_16x16x32_bf16 v[62:65], v[38:41], v[206:209], v[62:65]
	v_mfma_f32_16x16x32_bf16 v[58:61], v[54:57], v[206:209], v[58:61]
	v_mfma_f32_16x16x32_bf16 v[30:33], v[38:41], v[218:221], v[30:33]
	v_mfma_f32_16x16x32_bf16 v[26:29], v[54:57], v[218:221], v[26:29]
	v_mfma_f32_16x16x32_bf16 v[14:17], v[38:41], v[240:243], v[14:17]
	v_mfma_f32_16x16x32_bf16 v[10:13], v[54:57], v[240:243], v[10:13]
	v_mfma_f32_16x16x32_bf16 v[46:49], v[114:117], v[170:173], v[46:49]
	v_mfma_f32_16x16x32_bf16 v[42:45], v[138:141], v[170:173], v[42:45]
	v_mfma_f32_16x16x32_bf16 v[22:25], v[114:117], v[210:213], v[22:25]
	v_mfma_f32_16x16x32_bf16 v[18:21], v[138:141], v[210:213], v[18:21]
	v_mfma_f32_16x16x32_bf16 v[6:9], v[114:117], v[236:239], v[6:9]
	v_mfma_f32_16x16x32_bf16 v[2:5], v[138:141], v[236:239], v[2:5]
	v_mfma_f32_16x16x32_bf16 v[34:37], v[114:117], v[154:157], v[70:73]
	v_mfma_f32_16x16x32_bf16 v[38:41], v[138:141], v[154:157], v[66:69]
	v_mfma_f32_16x16x32_bf16 v[46:49], v[126:129], v[206:209], v[46:49]
	v_mfma_f32_16x16x32_bf16 v[42:45], v[150:153], v[206:209], v[42:45]
	v_mfma_f32_16x16x32_bf16 v[22:25], v[126:129], v[218:221], v[22:25]
	v_mfma_f32_16x16x32_bf16 v[18:21], v[150:153], v[218:221], v[18:21]
	v_mfma_f32_16x16x32_bf16 v[6:9], v[126:129], v[240:243], v[6:9]
	v_mfma_f32_16x16x32_bf16 v[2:5], v[150:153], v[240:243], v[2:5]
	v_mfma_f32_16x16x32_bf16 v[34:37], v[126:129], v[158:161], v[34:37]
	v_mfma_f32_16x16x32_bf16 v[38:41], v[150:153], v[158:161], v[38:41]
	s_barrier
	s_add_i32 s9, 0, 0x18000
	s_add_i32 s12, 0, 0x1c000
	ds_read_b128 v[50:53], v198
	ds_read_b128 v[54:57], v198 offset:1024
	ds_read_b128 v[66:69], v198 offset:2048
	ds_read_b128 v[70:73], v198 offset:3072
	ds_read_b128 v[114:117], v199
	ds_read_b128 v[126:129], v199 offset:1024
	ds_read_b128 v[138:141], v199 offset:2048
	ds_read_b128 v[150:153], v199 offset:3072
	s_add_u32 s10, s76, 0x20000
	s_addc_u32 s11, s77, 0
	s_mov_b32 m0, s80
	ds_read_b128 v[154:157], v217 offset:32768
	ds_read_b128 v[158:161], v217 offset:33792
	ds_read_b128 v[170:173], v217 offset:34816
	ds_read_b128 v[206:209], v217 offset:35840
	ds_read_b128 v[210:213], v217 offset:36864
	ds_read_b128 v[218:221], v217 offset:37888
	ds_read_b128 v[236:239], v217 offset:38912
	ds_read_b128 v[240:243], v217 offset:39936
	global_load_lds_dwordx4 v178, s[10:11]
	s_mov_b32 m0, s81
	s_nop 0
	global_load_lds_dwordx4 v176, s[10:11]
	s_cmp_lg_u32 s46, 0
	s_cbranch_scc1 .Llw_20678
	s_waitcnt vmcnt(8)
	s_waitcnt lgkmcnt(0)
; #define PG8_STAGE(bufoff, gbase, voff) do { _Pragma("unroll") for (int _i = 0; _i < 2; ++_i) \
;         __builtin_amdgcn_global_load_lds((const unsigned*)((const char*)(gbase) + (voff)[_i]), (PG8_LAS unsigned*)(lds + (bufoff) + ldsw + _i * 8192), 16, 0, 0); } while (0)
; #define PG8_LDA(dst, b, h) do { _Pragma("unroll") for (int m = 0; m < 4; ++m) _Pragma("unroll") for (int k = 0; k < 2; ++k) dst[m][k] = *(const PG8_LAS bf16x8*)(lds + PG8_SA(b, h) + aoff + m * 2048 + k * 1024); } while (0)
; #define PG8_MMA(ai, bj, At, Bt) do { __builtin_amdgcn_s_setprio(1); _Pragma("unroll") for (int m = 0; m < 4; ++m) _Pragma("unroll") for (int n = 0; n < 2; ++n) _Pragma("unroll") for (int k = 0; k < 2; ++k) \
;         acc[ai][bj][m][n] = __builtin_amdgcn_mfma_f32_16x16x32_bf16(Bt[n][k], At[m][k], acc[ai][bj][m][n], 0, 0, 0); __builtin_amdgcn_s_setprio(0); } while (0)
; #define PG8_WAIT_V(n) asm volatile("s_waitcnt vmcnt(" #n ")" ::: "memory")
; #define PG8_WAIT_L(n) asm volatile("s_waitcnt lgkmcnt(" #n ")" ::: "memory")
; #define PG8_BAR __builtin_amdgcn_s_barrier()
; #define PG8_SCHED __builtin_amdgcn_sched_barrier(0)
; template <class Epi, class Sched, bool ALIGN_EPI = false, bool SP2 = false>
; __device__ __forceinline__ void gemm_phase(PG8_LAS unsigned char* lds, const Gemm g, const Sched& S, const Epi& E) {
;     ...
;             PG8_WAIT_V(8); PG8_WAIT_L(0); PG8_BAR; PG8_MMA(0, 0, At, B0); PG8_MMA(0, 1, At, B1); PG8_BAR; PG8_SCHED;
;             PG8_LDA(At, 1, 1); PG8_STAGE(PG8_SB(1, 0), b3, voffB); PG8_STAGE(PG8_SB(1, 1), b3 + hstepB, voffB); PG8_STAGE(PG8_SA(1, 0), a3, voffA);
;             PG8_WAIT_V(8); PG8_WAIT_L(0); PG8_BAR; PG8_MMA(1, 0, At, B0); PG8_MMA(1, 1, At, B1); PG8_BAR; PG8_SCHED;
;     ...
;         if constexpr (ALIGN_EPI) { if (wr == 0) PG8_BAR; }
;         if constexpr (!Epi::AFTER_DRAIN) { E(acc, cur, wr, wc, fr, fq, ui); S.done(cur); }
;         if (!has_next) break;
.Llw_20678:
	s_barrier
	s_waitcnt vmcnt(8)
	s_waitcnt lgkmcnt(0)
	v_mfma_f32_16x16x32_bf16 v[166:169], v[50:53], v[154:157], v[166:169]
	v_mfma_f32_16x16x32_bf16 v[162:165], v[66:69], v[154:157], v[162:165]
	v_mfma_f32_16x16x32_bf16 v[134:137], v[50:53], v[170:173], v[134:137]
	v_mfma_f32_16x16x32_bf16 v[130:133], v[66:69], v[170:173], v[130:133]
	v_mfma_f32_16x16x32_bf16 v[110:113], v[50:53], v[210:213], v[110:113]
	v_mfma_f32_16x16x32_bf16 v[106:109], v[66:69], v[210:213], v[106:109]
	v_mfma_f32_16x16x32_bf16 v[94:97], v[50:53], v[236:239], v[94:97]
	v_mfma_f32_16x16x32_bf16 v[90:93], v[66:69], v[236:239], v[90:93]
	v_mfma_f32_16x16x32_bf16 v[166:169], v[54:57], v[158:161], v[166:169]
	v_mfma_f32_16x16x32_bf16 v[162:165], v[70:73], v[158:161], v[162:165]
	v_mfma_f32_16x16x32_bf16 v[134:137], v[54:57], v[206:209], v[134:137]
	v_mfma_f32_16x16x32_bf16 v[130:133], v[70:73], v[206:209], v[130:133]
	v_mfma_f32_16x16x32_bf16 v[110:113], v[54:57], v[218:221], v[110:113]
	v_mfma_f32_16x16x32_bf16 v[106:109], v[70:73], v[218:221], v[106:109]
	v_mfma_f32_16x16x32_bf16 v[94:97], v[54:57], v[240:243], v[94:97]
	v_mfma_f32_16x16x32_bf16 v[90:93], v[70:73], v[240:243], v[90:93]
	v_mfma_f32_16x16x32_bf16 v[146:149], v[114:117], v[154:157], v[146:149]
	v_mfma_f32_16x16x32_bf16 v[142:145], v[138:141], v[154:157], v[142:145]
	v_mfma_f32_16x16x32_bf16 v[122:125], v[114:117], v[170:173], v[122:125]
	v_mfma_f32_16x16x32_bf16 v[118:121], v[138:141], v[170:173], v[118:121]
	v_mfma_f32_16x16x32_bf16 v[102:105], v[114:117], v[210:213], v[102:105]
	v_mfma_f32_16x16x32_bf16 v[98:101], v[138:141], v[210:213], v[98:101]
	v_mfma_f32_16x16x32_bf16 v[86:89], v[114:117], v[236:239], v[86:89]
	v_mfma_f32_16x16x32_bf16 v[82:85], v[138:141], v[236:239], v[82:85]
	v_mfma_f32_16x16x32_bf16 v[146:149], v[126:129], v[158:161], v[146:149]
	v_mfma_f32_16x16x32_bf16 v[142:145], v[150:153], v[158:161], v[142:145]
	v_mfma_f32_16x16x32_bf16 v[122:125], v[126:129], v[206:209], v[122:125]
	v_mfma_f32_16x16x32_bf16 v[118:121], v[150:153], v[206:209], v[118:121]
	v_mfma_f32_16x16x32_bf16 v[102:105], v[126:129], v[218:221], v[102:105]
	v_mfma_f32_16x16x32_bf16 v[98:101], v[150:153], v[218:221], v[98:101]
	v_mfma_f32_16x16x32_bf16 v[86:89], v[126:129], v[240:243], v[86:89]
	v_mfma_f32_16x16x32_bf16 v[82:85], v[150:153], v[240:243], v[82:85]
	s_barrier
	s_add_i32 s9, s9, s25
	s_mov_b32 m0, s9
	ds_read_b128 v[154:157], v217 offset:49152
	ds_read_b128 v[158:161], v217 offset:50176
	ds_read_b128 v[170:173], v217 offset:51200
	ds_read_b128 v[206:209], v217 offset:52224
	ds_read_b128 v[210:213], v217 offset:53248
	ds_read_b128 v[218:221], v217 offset:54272
	ds_read_b128 v[236:239], v217 offset:55296
	ds_read_b128 v[240:243], v217 offset:56320
	s_add_u32 s100, s72, s60
	s_addc_u32 s101, s73, s61
	global_load_lds_dwordx4 v190, s[100:101]
	s_add_i32 m0, s9, 0x2000
	s_add_u32 s10, s72, 0x8080
	s_addc_u32 s11, s73, 0
	s_add_i32 s9, s12, s25
	global_load_lds_dwordx4 v174, s[100:101]
	s_mov_b32 m0, s9
	s_nop 0
	global_load_lds_dwordx4 v190, s[10:11]
	s_add_i32 m0, s9, 0x2000
	s_nop 0
	global_load_lds_dwordx4 v174, s[10:11]
	s_mov_b32 m0, s82
	s_add_u32 s100, s76, s60
	s_addc_u32 s101, s77, s61
	global_load_lds_dwordx4 v178, s[100:101]
	s_mov_b32 m0, s92
	s_nop 0
	global_load_lds_dwordx4 v176, s[100:101]
	s_cmp_lg_u32 s46, 0
	s_cbranch_scc1 .Llw_20750
	s_waitcnt vmcnt(8)
	s_waitcnt lgkmcnt(0)
.Llw_20750:
	s_barrier
	s_waitcnt vmcnt(8)
	s_waitcnt lgkmcnt(0)
	v_mfma_f32_16x16x32_bf16 v[78:81], v[50:53], v[154:157], v[78:81]
	v_mfma_f32_16x16x32_bf16 v[74:77], v[66:69], v[154:157], v[74:77]
	v_mfma_f32_16x16x32_bf16 v[62:65], v[50:53], v[170:173], v[62:65]
	v_mfma_f32_16x16x32_bf16 v[58:61], v[66:69], v[170:173], v[58:61]
	v_mfma_f32_16x16x32_bf16 v[30:33], v[50:53], v[210:213], v[30:33]
	v_mfma_f32_16x16x32_bf16 v[26:29], v[66:69], v[210:213], v[26:29]
	v_mfma_f32_16x16x32_bf16 v[14:17], v[50:53], v[236:239], v[14:17]
	v_mfma_f32_16x16x32_bf16 v[10:13], v[66:69], v[236:239], v[10:13]
	v_mfma_f32_16x16x32_bf16 v[78:81], v[54:57], v[158:161], v[78:81]
	v_mfma_f32_16x16x32_bf16 v[74:77], v[70:73], v[158:161], v[74:77]
	v_mfma_f32_16x16x32_bf16 v[62:65], v[54:57], v[206:209], v[62:65]
	v_mfma_f32_16x16x32_bf16 v[58:61], v[70:73], v[206:209], v[58:61]
	v_mfma_f32_16x16x32_bf16 v[30:33], v[54:57], v[218:221], v[30:33]
	v_mfma_f32_16x16x32_bf16 v[26:29], v[70:73], v[218:221], v[26:29]
	v_mfma_f32_16x16x32_bf16 v[14:17], v[54:57], v[240:243], v[14:17]
	v_mfma_f32_16x16x32_bf16 v[10:13], v[70:73], v[240:243], v[10:13]
	v_mfma_f32_16x16x32_bf16 v[34:37], v[114:117], v[154:157], v[34:37]
	v_mfma_f32_16x16x32_bf16 v[70:73], v[126:129], v[158:161], v[34:37]
	v_mfma_f32_16x16x32_bf16 v[34:37], v[138:141], v[154:157], v[38:41]
	v_mfma_f32_16x16x32_bf16 v[66:69], v[150:153], v[158:161], v[34:37]
	v_mfma_f32_16x16x32_bf16 v[34:37], v[114:117], v[170:173], v[46:49]
	v_mfma_f32_16x16x32_bf16 v[46:49], v[126:129], v[206:209], v[34:37]
	v_mfma_f32_16x16x32_bf16 v[34:37], v[138:141], v[170:173], v[42:45]
	v_mfma_f32_16x16x32_bf16 v[22:25], v[114:117], v[210:213], v[22:25]
	v_mfma_f32_16x16x32_bf16 v[18:21], v[138:141], v[210:213], v[18:21]
	v_mfma_f32_16x16x32_bf16 v[6:9], v[114:117], v[236:239], v[6:9]
	v_mfma_f32_16x16x32_bf16 v[2:5], v[138:141], v[236:239], v[2:5]
	v_mfma_f32_16x16x32_bf16 v[42:45], v[150:153], v[206:209], v[34:37]
	v_mfma_f32_16x16x32_bf16 v[22:25], v[126:129], v[218:221], v[22:25]
	v_mfma_f32_16x16x32_bf16 v[18:21], v[150:153], v[218:221], v[18:21]
	v_mfma_f32_16x16x32_bf16 v[6:9], v[126:129], v[240:243], v[6:9]
	v_mfma_f32_16x16x32_bf16 v[2:5], v[150:153], v[240:243], v[2:5]
	s_barrier
	s_add_i32 s8, s8, 2
	s_add_u32 s68, s68, 0x100
	s_addc_u32 s69, s69, 0
	s_add_u32 s6, s6, 0x100
	s_addc_u32 s7, s7, 0
	s_cmp_gt_u32 s8, 5
	s_cbranch_scc0 .LBB0_788
	s_and_b64 vcc, exec, s[46:47]
	s_cbranch_vccz .LBB0_791
	s_barrier

; #define PG8_STAGE(bufoff, gbase, voff) do { _Pragma("unroll") for (int _i = 0; _i < 2; ++_i) \
;         __builtin_amdgcn_global_load_lds((const unsigned*)((const char*)(gbase) + (voff)[_i]), (PG8_LAS unsigned*)(lds + (bufoff) + ldsw + _i * 8192), 16, 0, 0); } while (0)
; #define PG8_LDA(dst, b, h) do { _Pragma("unroll") for (int m = 0; m < 4; ++m) _Pragma("unroll") for (int k = 0; k < 2; ++k) dst[m][k] = *(const PG8_LAS bf16x8*)(lds + PG8_SA(b, h) + aoff + m * 2048 + k * 1024); } while (0)
; #define PG8_LDB(dst, b, h) do { _Pragma("unroll") for (int n = 0; n < 2; ++n) _Pragma("unroll") for (int k = 0; k < 2; ++k) dst[n][k] = *(const PG8_LAS bf16x8*)(lds + PG8_SB(b, h) + boff + n * 2048 + k * 1024); } while (0)
; #define PG8_WAIT_V(n) asm volatile("s_waitcnt vmcnt(" #n ")" ::: "memory")
; #define PG8_WAIT_L(n) asm volatile("s_waitcnt lgkmcnt(" #n ")" ::: "memory")
; #define PG8_BAR __builtin_amdgcn_s_barrier()
; #define PG8_SCHED __builtin_amdgcn_sched_barrier(0)
; template <class Epi, class Sched, bool ALIGN_EPI = false, bool SP2 = false>
; __device__ __forceinline__ void gemm_phase(PG8_LAS unsigned char* lds, const Gemm g, const Sched& S, const Epi& E) {
;     ...
;         const bool has_next = S.next(ui + 1, nxt);
;         const char* nA = has_next ? (const char*)g.A + (size_t)nxt.pm * tstep : cA; const char* nB = has_next ? (const char*)g.Bt + (size_t)nxt.pn * tstep : cB;
;         for (int t = 0; t < nt; t += 2) {
;             const bool last = (t == nt - 2);
;             const char* a1 = cA + (size_t)(t + 1) * kstep;
;             const char* a2 = last ? nA : cA + (size_t)(t + 2) * kstep; const char* b2 = last ? nB : cB + (size_t)(t + 2) * kstep;
;             const char* a3 = a2 + kstep; const char* b3 = b2 + kstep;
;             if (last && has_next) S.a_ready(nxt);
;             if constexpr (SP2) {
;             PG8_LDB(B0, 0, 0); PG8_LDB(B1, 0, 1); PG8_SCHED; PG8_LDA(At, 0, 0); PG8_STAGE(PG8_SA(1, 1), a1 + hstep, voffA);
;             PG8_WAIT_V(8); PG8_WAIT_L(0); PG8_BAR; PG8_MMA(0, 0, At, B0); PG8_MMA(0, 1, At, B1); PG8_BAR; PG8_SCHED;
;             PG8_LDA(At, 0, 1); PG8_STAGE(PG8_SB(0, 0), b2, voffB); PG8_STAGE(PG8_SB(0, 1), b2 + hstepB, voffB); PG8_STAGE(PG8_SA(0, 0), a2, voffA);
;             PG8_WAIT_V(8); PG8_WAIT_L(0); PG8_BAR; PG8_MMA(1, 0, At, B0); PG8_MMA(1, 1, At, B1); PG8_BAR; PG8_SCHED;
.LBB0_926:
	s_ashr_i32 s73, s72, 31
	s_lshl_b64 s[4:5], s[72:73], 20
	v_readlane_b32 s6, v249, 9
	v_readlane_b32 s7, v249, 10
	s_add_u32 s76, s6, s4
	s_addc_u32 s77, s7, s5
	s_and_b64 s[4:5], s[92:93], exec
	s_cselect_b32 s36, s77, s39
	s_cselect_b32 s37, s76, s38
	s_ashr_i32 s69, s68, 31
	s_lshl_b64 s[4:5], s[68:69], 20
	v_readlane_b32 s6, v249, 17
	v_readlane_b32 s7, v249, 18
	s_add_u32 s80, s6, s4
	s_addc_u32 s81, s7, s5
	s_and_b64 s[4:5], s[92:93], exec
	s_cselect_b32 s4, s81, s47
	s_cselect_b32 s5, s80, s46
	s_add_u32 s38, s38, 0x80080
	s_addc_u32 s39, s39, 0
	s_add_u32 s6, s46, 0x100
	v_mov_b32_e32 v2, 0
	s_addc_u32 s7, s47, 0
	s_mov_b32 s8, -2
	v_mov_b32_e32 v3, v2
	v_mov_b32_e32 v4, v2
	v_mov_b32_e32 v5, v2
	v_mov_b32_e32 v6, v2
	v_mov_b32_e32 v7, v2
	v_mov_b32_e32 v8, v2
	v_mov_b32_e32 v9, v2
	v_mov_b32_e32 v18, v2
	v_mov_b32_e32 v19, v2
	v_mov_b32_e32 v20, v2
	v_mov_b32_e32 v21, v2
	v_mov_b32_e32 v22, v2
	v_mov_b32_e32 v23, v2
	v_mov_b32_e32 v24, v2
	v_mov_b32_e32 v25, v2
	v_mov_b32_e32 v34, v2
	s_waitcnt lgkmcnt(0)
	v_add_u32_e32 v186, 0x10000, v193
	v_add_u32_e32 v187, 0x14000, v193
	v_add_u32_e32 v198, 0x18000, v193
	v_add_u32_e32 v199, 0x1c000, v193
	s_add_u32 s9, s38, 0xfff80080
	s_addc_u32 s10, s39, -1
	s_add_i32 s11, 0, 0x10000
	s_cmp_eq_u32 s8, 28
	s_cselect_b32 s95, s36, s10
	s_cselect_b32 s94, s37, s9
	s_cselect_b32 s47, s4, s7
	s_cselect_b32 s46, s5, s6
	s_add_i32 s9, 0, 0x14000
	ds_read_b128 v[66:69], v186
	ds_read_b128 v[70:73], v186 offset:1024
	ds_read_b128 v[78:81], v186 offset:2048
	ds_read_b128 v[86:89], v186 offset:3072
	ds_read_b128 v[146:149], v187
	ds_read_b128 v[150:153], v187 offset:1024
	ds_read_b128 v[154:157], v187 offset:2048
	ds_read_b128 v[158:161], v187 offset:3072
	s_add_i32 m0, s66, 0xc000
	ds_read_b128 v[162:165], v236
	ds_read_b128 v[166:169], v236 offset:1024
	ds_read_b128 v[170:173], v236 offset:2048
	ds_read_b128 v[174:177], v236 offset:3072
	ds_read_b128 v[178:181], v236 offset:4096
	ds_read_b128 v[182:185], v236 offset:5120
	ds_read_b128 v[216:219], v236 offset:6144
	ds_read_b128 v[220:223], v236 offset:7168
	global_load_lds_dwordx4 v212, s[38:39]
	s_add_i32 m0, s66, 0xe000
	s_nop 0
	global_load_lds_dwordx4 v214, s[38:39]
	s_cmp_lg_u32 s70, 0
	s_cbranch_scc1 .Llw_24898
	s_waitcnt vmcnt(8)
	s_waitcnt lgkmcnt(0)
.Llw_24898:
	s_barrier
	s_waitcnt vmcnt(8)
	s_waitcnt lgkmcnt(0)
	v_mfma_f32_16x16x32_bf16 v[142:145], v[66:69], v[162:165], 0
	v_mfma_f32_16x16x32_bf16 v[138:141], v[78:81], v[162:165], 0
	v_mfma_f32_16x16x32_bf16 v[126:129], v[66:69], v[170:173], 0
	v_mfma_f32_16x16x32_bf16 v[122:125], v[78:81], v[170:173], 0
	v_mfma_f32_16x16x32_bf16 v[110:113], v[66:69], v[178:181], 0
	v_mfma_f32_16x16x32_bf16 v[106:109], v[78:81], v[178:181], 0
	v_mfma_f32_16x16x32_bf16 v[94:97], v[66:69], v[216:219], 0
	v_mfma_f32_16x16x32_bf16 v[90:93], v[78:81], v[216:219], 0
	v_mfma_f32_16x16x32_bf16 v[142:145], v[70:73], v[166:169], v[142:145]
	v_mfma_f32_16x16x32_bf16 v[138:141], v[86:89], v[166:169], v[138:141]
	v_mfma_f32_16x16x32_bf16 v[126:129], v[70:73], v[174:177], v[126:129]
	v_mfma_f32_16x16x32_bf16 v[122:125], v[86:89], v[174:177], v[122:125]
	v_mfma_f32_16x16x32_bf16 v[110:113], v[70:73], v[182:185], v[110:113]
	v_mfma_f32_16x16x32_bf16 v[106:109], v[86:89], v[182:185], v[106:109]
	v_mfma_f32_16x16x32_bf16 v[94:97], v[70:73], v[220:223], v[94:97]
	v_mfma_f32_16x16x32_bf16 v[90:93], v[86:89], v[220:223], v[90:93]
	v_mfma_f32_16x16x32_bf16 v[134:137], v[146:149], v[162:165], 0
	v_mfma_f32_16x16x32_bf16 v[130:133], v[154:157], v[162:165], 0
	v_mfma_f32_16x16x32_bf16 v[118:121], v[146:149], v[170:173], 0
	v_mfma_f32_16x16x32_bf16 v[114:117], v[154:157], v[170:173], 0
	v_mfma_f32_16x16x32_bf16 v[102:105], v[146:149], v[178:181], 0
	v_mfma_f32_16x16x32_bf16 v[98:101], v[154:157], v[178:181], 0
	v_mfma_f32_16x16x32_bf16 v[82:85], v[146:149], v[216:219], 0
	v_mfma_f32_16x16x32_bf16 v[74:77], v[154:157], v[216:219], 0
	v_mfma_f32_16x16x32_bf16 v[134:137], v[150:153], v[166:169], v[134:137]
	v_mfma_f32_16x16x32_bf16 v[130:133], v[158:161], v[166:169], v[130:133]
	v_mfma_f32_16x16x32_bf16 v[118:121], v[150:153], v[174:177], v[118:121]
	v_mfma_f32_16x16x32_bf16 v[114:117], v[158:161], v[174:177], v[114:117]
	v_mfma_f32_16x16x32_bf16 v[102:105], v[150:153], v[182:185], v[102:105]
	v_mfma_f32_16x16x32_bf16 v[98:101], v[158:161], v[182:185], v[98:101]
	v_mfma_f32_16x16x32_bf16 v[82:85], v[150:153], v[220:223], v[82:85]
	v_mfma_f32_16x16x32_bf16 v[74:77], v[158:161], v[220:223], v[74:77]
	s_barrier
	s_add_i32 s10, s11, s25
	s_mov_b32 m0, s10
	ds_read_b128 v[162:165], v236 offset:16384
	ds_read_b128 v[166:169], v236 offset:17408
	ds_read_b128 v[170:173], v236 offset:18432
	ds_read_b128 v[174:177], v236 offset:19456
	ds_read_b128 v[178:181], v236 offset:20480
	ds_read_b128 v[182:185], v236 offset:21504
	ds_read_b128 v[216:219], v236 offset:22528
	ds_read_b128 v[220:223], v236 offset:23552
	global_load_lds_dwordx4 v190, s[46:47]
	s_add_i32 m0, s10, 0x2000
	s_add_u32 s10, s46, 0x20000
	s_addc_u32 s11, s47, 0
	s_add_i32 s9, s9, s25
	global_load_lds_dwordx4 v206, s[46:47]
	s_mov_b32 m0, s9
	s_nop 0
	global_load_lds_dwordx4 v190, s[10:11]
	s_add_i32 m0, s9, 0x2000
	s_nop 0
	global_load_lds_dwordx4 v206, s[10:11]
	s_mov_b32 m0, s66
	s_nop 0
	global_load_lds_dwordx4 v210, s[94:95]
	s_mov_b32 m0, s67
	s_nop 0
	global_load_lds_dwordx4 v208, s[94:95]
	s_cmp_lg_u32 s70, 0
	s_cbranch_scc1 .Llw_24967
	s_waitcnt vmcnt(8)
	s_waitcnt lgkmcnt(0)
; #define PG8_STAGE(bufoff, gbase, voff) do { _Pragma("unroll") for (int _i = 0; _i < 2; ++_i) \
;         __builtin_amdgcn_global_load_lds((const unsigned*)((const char*)(gbase) + (voff)[_i]), (PG8_LAS unsigned*)(lds + (bufoff) + ldsw + _i * 8192), 16, 0, 0); } while (0)
; #define PG8_LDA(dst, b, h) do { _Pragma("unroll") for (int m = 0; m < 4; ++m) _Pragma("unroll") for (int k = 0; k < 2; ++k) dst[m][k] = *(const PG8_LAS bf16x8*)(lds + PG8_SA(b, h) + aoff + m * 2048 + k * 1024); } while (0)
; #define PG8_LDB(dst, b, h) do { _Pragma("unroll") for (int n = 0; n < 2; ++n) _Pragma("unroll") for (int k = 0; k < 2; ++k) dst[n][k] = *(const PG8_LAS bf16x8*)(lds + PG8_SB(b, h) + boff + n * 2048 + k * 1024); } while (0)
; #define PG8_MMA(ai, bj, At, Bt) do { __builtin_amdgcn_s_setprio(1); _Pragma("unroll") for (int m = 0; m < 4; ++m) _Pragma("unroll") for (int n = 0; n < 2; ++n) _Pragma("unroll") for (int k = 0; k < 2; ++k) \
;         acc[ai][bj][m][n] = __builtin_amdgcn_mfma_f32_16x16x32_bf16(Bt[n][k], At[m][k], acc[ai][bj][m][n], 0, 0, 0); __builtin_amdgcn_s_setprio(0); } while (0)
; #define PG8_WAIT_V(n) asm volatile("s_waitcnt vmcnt(" #n ")" ::: "memory")
; #define PG8_WAIT_L(n) asm volatile("s_waitcnt lgkmcnt(" #n ")" ::: "memory")
; #define PG8_BAR __builtin_amdgcn_s_barrier()
; #define PG8_SCHED __builtin_amdgcn_sched_barrier(0)
; template <class Epi, class Sched, bool ALIGN_EPI = false, bool SP2 = false>
; __device__ __forceinline__ void gemm_phase(PG8_LAS unsigned char* lds, const Gemm g, const Sched& S, const Epi& E) {
;     ...
;             PG8_WAIT_V(8); PG8_WAIT_L(0); PG8_BAR; PG8_MMA(1, 0, At, B0); PG8_MMA(1, 1, At, B1); PG8_BAR; PG8_SCHED;
;             PG8_LDB(B0, 1, 0); PG8_LDB(B1, 1, 1); PG8_SCHED; PG8_LDA(At, 1, 0); PG8_STAGE(PG8_SA(0, 1), a2 + hstep, voffA);
;             PG8_WAIT_V(8); PG8_WAIT_L(0); PG8_BAR; PG8_MMA(0, 0, At, B0); PG8_MMA(0, 1, At, B1); PG8_BAR; PG8_SCHED;
.Llw_24967:
	s_barrier
	s_waitcnt vmcnt(8)
	s_waitcnt lgkmcnt(0)
	v_mfma_f32_16x16x32_bf16 v[62:65], v[66:69], v[162:165], 0
	v_mfma_f32_16x16x32_bf16 v[58:61], v[78:81], v[162:165], 0
	v_mfma_f32_16x16x32_bf16 v[46:49], v[66:69], v[170:173], 0
	v_mfma_f32_16x16x32_bf16 v[42:45], v[78:81], v[170:173], 0
	v_mfma_f32_16x16x32_bf16 v[30:33], v[66:69], v[178:181], 0
	v_mfma_f32_16x16x32_bf16 v[26:29], v[78:81], v[178:181], 0
	v_mfma_f32_16x16x32_bf16 v[14:17], v[66:69], v[216:219], 0
	v_mfma_f32_16x16x32_bf16 v[10:13], v[78:81], v[216:219], 0
	v_mfma_f32_16x16x32_bf16 v[62:65], v[70:73], v[166:169], v[62:65]
	v_mfma_f32_16x16x32_bf16 v[58:61], v[86:89], v[166:169], v[58:61]
	v_mfma_f32_16x16x32_bf16 v[46:49], v[70:73], v[174:177], v[46:49]
	v_mfma_f32_16x16x32_bf16 v[42:45], v[86:89], v[174:177], v[42:45]
	v_mfma_f32_16x16x32_bf16 v[30:33], v[70:73], v[182:185], v[30:33]
	v_mfma_f32_16x16x32_bf16 v[26:29], v[86:89], v[182:185], v[26:29]
	v_mfma_f32_16x16x32_bf16 v[14:17], v[70:73], v[220:223], v[14:17]
	v_mfma_f32_16x16x32_bf16 v[10:13], v[86:89], v[220:223], v[10:13]
	v_mfma_f32_16x16x32_bf16 v[54:57], v[146:149], v[162:165], 0
	v_mfma_f32_16x16x32_bf16 v[50:53], v[154:157], v[162:165], 0
	v_mfma_f32_16x16x32_bf16 v[38:41], v[146:149], v[170:173], 0
	v_mfma_f32_16x16x32_bf16 v[34:37], v[154:157], v[170:173], 0
	v_mfma_f32_16x16x32_bf16 v[22:25], v[146:149], v[178:181], 0
	v_mfma_f32_16x16x32_bf16 v[18:21], v[154:157], v[178:181], 0
	v_mfma_f32_16x16x32_bf16 v[6:9], v[146:149], v[216:219], 0
	v_mfma_f32_16x16x32_bf16 v[2:5], v[154:157], v[216:219], 0
	v_mfma_f32_16x16x32_bf16 v[54:57], v[150:153], v[166:169], v[54:57]
	v_mfma_f32_16x16x32_bf16 v[50:53], v[158:161], v[166:169], v[50:53]
	v_mfma_f32_16x16x32_bf16 v[38:41], v[150:153], v[174:177], v[38:41]
	v_mfma_f32_16x16x32_bf16 v[34:37], v[158:161], v[174:177], v[34:37]
	v_mfma_f32_16x16x32_bf16 v[22:25], v[150:153], v[182:185], v[22:25]
	v_mfma_f32_16x16x32_bf16 v[18:21], v[158:161], v[182:185], v[18:21]
	v_mfma_f32_16x16x32_bf16 v[6:9], v[150:153], v[220:223], v[6:9]
	v_mfma_f32_16x16x32_bf16 v[2:5], v[158:161], v[220:223], v[2:5]
	s_barrier
	s_add_i32 s9, 0, 0x18000
	s_add_i32 s12, 0, 0x1c000
	ds_read_b128 v[66:69], v198
	ds_read_b128 v[70:73], v198 offset:1024
	ds_read_b128 v[78:81], v198 offset:2048
	ds_read_b128 v[86:89], v198 offset:3072
	ds_read_b128 v[146:149], v199
	ds_read_b128 v[150:153], v199 offset:1024
	ds_read_b128 v[154:157], v199 offset:2048
	ds_read_b128 v[158:161], v199 offset:3072
	s_add_u32 s10, s94, 0x80000
	s_addc_u32 s11, s95, 0
	s_mov_b32 m0, s59
	ds_read_b128 v[162:165], v236 offset:32768
	ds_read_b128 v[166:169], v236 offset:33792
	ds_read_b128 v[170:173], v236 offset:34816
	ds_read_b128 v[174:177], v236 offset:35840
	ds_read_b128 v[178:181], v236 offset:36864
	ds_read_b128 v[182:185], v236 offset:37888
	ds_read_b128 v[216:219], v236 offset:38912
	ds_read_b128 v[220:223], v236 offset:39936
	global_load_lds_dwordx4 v210, s[10:11]
	s_mov_b32 m0, s74
	s_nop 0
	global_load_lds_dwordx4 v208, s[10:11]
	s_cmp_lg_u32 s70, 0
	s_cbranch_scc1 .Llw_25034
	s_waitcnt vmcnt(8)
	s_waitcnt lgkmcnt(0)
.Llw_25034:
	s_barrier
	s_waitcnt vmcnt(8)
	s_waitcnt lgkmcnt(0)
	v_mfma_f32_16x16x32_bf16 v[142:145], v[66:69], v[162:165], v[142:145]
	v_mfma_f32_16x16x32_bf16 v[138:141], v[78:81], v[162:165], v[138:141]
	v_mfma_f32_16x16x32_bf16 v[126:129], v[66:69], v[170:173], v[126:129]
	v_mfma_f32_16x16x32_bf16 v[122:125], v[78:81], v[170:173], v[122:125]
	v_mfma_f32_16x16x32_bf16 v[110:113], v[66:69], v[178:181], v[110:113]
	v_mfma_f32_16x16x32_bf16 v[106:109], v[78:81], v[178:181], v[106:109]
	v_mfma_f32_16x16x32_bf16 v[94:97], v[66:69], v[216:219], v[94:97]
	v_mfma_f32_16x16x32_bf16 v[90:93], v[78:81], v[216:219], v[90:93]
	v_mfma_f32_16x16x32_bf16 v[142:145], v[70:73], v[166:169], v[142:145]
	v_mfma_f32_16x16x32_bf16 v[138:141], v[86:89], v[166:169], v[138:141]
	v_mfma_f32_16x16x32_bf16 v[126:129], v[70:73], v[174:177], v[126:129]
	v_mfma_f32_16x16x32_bf16 v[122:125], v[86:89], v[174:177], v[122:125]
	v_mfma_f32_16x16x32_bf16 v[110:113], v[70:73], v[182:185], v[110:113]
	v_mfma_f32_16x16x32_bf16 v[106:109], v[86:89], v[182:185], v[106:109]
	v_mfma_f32_16x16x32_bf16 v[94:97], v[70:73], v[220:223], v[94:97]
	v_mfma_f32_16x16x32_bf16 v[90:93], v[86:89], v[220:223], v[90:93]
	v_mfma_f32_16x16x32_bf16 v[134:137], v[146:149], v[162:165], v[134:137]
	v_mfma_f32_16x16x32_bf16 v[130:133], v[154:157], v[162:165], v[130:133]
	v_mfma_f32_16x16x32_bf16 v[118:121], v[146:149], v[170:173], v[118:121]
	v_mfma_f32_16x16x32_bf16 v[114:117], v[154:157], v[170:173], v[114:117]
	v_mfma_f32_16x16x32_bf16 v[102:105], v[146:149], v[178:181], v[102:105]
	v_mfma_f32_16x16x32_bf16 v[98:101], v[154:157], v[178:181], v[98:101]
	v_mfma_f32_16x16x32_bf16 v[82:85], v[146:149], v[216:219], v[82:85]
	v_mfma_f32_16x16x32_bf16 v[74:77], v[154:157], v[216:219], v[74:77]
	v_mfma_f32_16x16x32_bf16 v[134:137], v[150:153], v[166:169], v[134:137]
	v_mfma_f32_16x16x32_bf16 v[130:133], v[158:161], v[166:169], v[130:133]
	v_mfma_f32_16x16x32_bf16 v[118:121], v[150:153], v[174:177], v[118:121]
	v_mfma_f32_16x16x32_bf16 v[114:117], v[158:161], v[174:177], v[114:117]
	v_mfma_f32_16x16x32_bf16 v[102:105], v[150:153], v[182:185], v[102:105]
	v_mfma_f32_16x16x32_bf16 v[98:101], v[158:161], v[182:185], v[98:101]
	v_mfma_f32_16x16x32_bf16 v[82:85], v[150:153], v[220:223], v[82:85]
	v_mfma_f32_16x16x32_bf16 v[74:77], v[158:161], v[220:223], v[74:77]
	s_barrier
	s_add_i32 s9, s9, s25
	s_mov_b32 m0, s9
	ds_read_b128 v[162:165], v236 offset:49152
	ds_read_b128 v[166:169], v236 offset:50176
	ds_read_b128 v[170:173], v236 offset:51200
	ds_read_b128 v[174:177], v236 offset:52224
	ds_read_b128 v[178:181], v236 offset:53248
	ds_read_b128 v[182:185], v236 offset:54272
	ds_read_b128 v[216:219], v236 offset:55296
	ds_read_b128 v[220:223], v236 offset:56320
	s_add_u32 s100, s46, s60
	s_addc_u32 s101, s47, s61
	global_load_lds_dwordx4 v190, s[100:101]
	s_add_i32 m0, s9, 0x2000
	s_add_u32 s10, s46, 0x20080
	s_addc_u32 s11, s47, 0
	s_add_i32 s9, s12, s25
	global_load_lds_dwordx4 v206, s[100:101]
	s_mov_b32 m0, s9
	s_nop 0
	global_load_lds_dwordx4 v190, s[10:11]
	s_add_i32 m0, s9, 0x2000
	s_nop 0
	global_load_lds_dwordx4 v206, s[10:11]
	s_mov_b32 m0, s75
	s_add_u32 s100, s94, s60
	s_addc_u32 s101, s95, s61
	global_load_lds_dwordx4 v210, s[100:101]
	s_mov_b32 m0, s0
	s_nop 0
	global_load_lds_dwordx4 v208, s[100:101]
	s_cmp_lg_u32 s70, 0
	s_cbranch_scc1 .Llw_25106
	s_waitcnt vmcnt(8)
	s_waitcnt lgkmcnt(0)
; #define PG8_STAGE(bufoff, gbase, voff) do { _Pragma("unroll") for (int _i = 0; _i < 2; ++_i) \
;         __builtin_amdgcn_global_load_lds((const unsigned*)((const char*)(gbase) + (voff)[_i]), (PG8_LAS unsigned*)(lds + (bufoff) + ldsw + _i * 8192), 16, 0, 0); } while (0)
; #define PG8_LDA(dst, b, h) do { _Pragma("unroll") for (int m = 0; m < 4; ++m) _Pragma("unroll") for (int k = 0; k < 2; ++k) dst[m][k] = *(const PG8_LAS bf16x8*)(lds + PG8_SA(b, h) + aoff + m * 2048 + k * 1024); } while (0)
; #define PG8_LDB(dst, b, h) do { _Pragma("unroll") for (int n = 0; n < 2; ++n) _Pragma("unroll") for (int k = 0; k < 2; ++k) dst[n][k] = *(const PG8_LAS bf16x8*)(lds + PG8_SB(b, h) + boff + n * 2048 + k * 1024); } while (0)
; #define PG8_MMA(ai, bj, At, Bt) do { __builtin_amdgcn_s_setprio(1); _Pragma("unroll") for (int m = 0; m < 4; ++m) _Pragma("unroll") for (int n = 0; n < 2; ++n) _Pragma("unroll") for (int k = 0; k < 2; ++k) \
;         acc[ai][bj][m][n] = __builtin_amdgcn_mfma_f32_16x16x32_bf16(Bt[n][k], At[m][k], acc[ai][bj][m][n], 0, 0, 0); __builtin_amdgcn_s_setprio(0); } while (0)
; #define PG8_WAIT_V(n) asm volatile("s_waitcnt vmcnt(" #n ")" ::: "memory")
; template <class Epi, class Sched, bool ALIGN_EPI = false, bool SP2 = false>
; __device__ __forceinline__ void gemm_phase(PG8_LAS unsigned char* lds, const Gemm g, const Sched& S, const Epi& E) {
;     ...
;             PG8_LDB(B0, 0, 0); PG8_LDB(B1, 0, 1); PG8_SCHED; PG8_LDA(At, 0, 0); PG8_STAGE(PG8_SA(1, 1), a1 + hstep, voffA);
;             PG8_WAIT_V(8); PG8_WAIT_L(0); PG8_BAR; PG8_MMA(0, 0, At, B0); PG8_MMA(0, 1, At, B1); PG8_BAR; PG8_SCHED;
;             PG8_LDA(At, 0, 1); PG8_STAGE(PG8_SB(0, 0), b2, voffB); PG8_STAGE(PG8_SB(0, 1), b2 + hstepB, voffB); PG8_STAGE(PG8_SA(0, 0), a2, voffA);
;             PG8_WAIT_V(8); PG8_WAIT_L(0); PG8_BAR; PG8_MMA(1, 0, At, B0); PG8_MMA(1, 1, At, B1); PG8_BAR; PG8_SCHED;
;             PG8_LDB(B0, 1, 0); PG8_LDB(B1, 1, 1); PG8_SCHED; PG8_LDA(At, 1, 0); PG8_STAGE(PG8_SA(0, 1), a2 + hstep, voffA);
;             PG8_WAIT_V(8); PG8_WAIT_L(0); PG8_BAR; PG8_MMA(0, 0, At, B0); PG8_MMA(0, 1, At, B1); PG8_BAR; PG8_SCHED;
;             PG8_LDA(At, 1, 1); PG8_STAGE(PG8_SB(1, 0), b3, voffB); PG8_STAGE(PG8_SB(1, 1), b3 + hstepB, voffB); PG8_STAGE(PG8_SA(1, 0), a3, voffA);
;             PG8_WAIT_V(8); PG8_WAIT_L(0); PG8_BAR; PG8_MMA(1, 0, At, B0); PG8_MMA(1, 1, At, B1); PG8_BAR; PG8_SCHED;
.Llw_25106:
	s_barrier
	s_waitcnt vmcnt(8)
	s_waitcnt lgkmcnt(0)
	v_mfma_f32_16x16x32_bf16 v[62:65], v[66:69], v[162:165], v[62:65]
	v_mfma_f32_16x16x32_bf16 v[58:61], v[78:81], v[162:165], v[58:61]
	v_mfma_f32_16x16x32_bf16 v[46:49], v[66:69], v[170:173], v[46:49]
	v_mfma_f32_16x16x32_bf16 v[42:45], v[78:81], v[170:173], v[42:45]
	v_mfma_f32_16x16x32_bf16 v[30:33], v[66:69], v[178:181], v[30:33]
	v_mfma_f32_16x16x32_bf16 v[26:29], v[78:81], v[178:181], v[26:29]
	v_mfma_f32_16x16x32_bf16 v[14:17], v[66:69], v[216:219], v[14:17]
	v_mfma_f32_16x16x32_bf16 v[10:13], v[78:81], v[216:219], v[10:13]
	v_mfma_f32_16x16x32_bf16 v[62:65], v[70:73], v[166:169], v[62:65]
	v_mfma_f32_16x16x32_bf16 v[58:61], v[86:89], v[166:169], v[58:61]
	v_mfma_f32_16x16x32_bf16 v[46:49], v[70:73], v[174:177], v[46:49]
	v_mfma_f32_16x16x32_bf16 v[42:45], v[86:89], v[174:177], v[42:45]
	v_mfma_f32_16x16x32_bf16 v[30:33], v[70:73], v[182:185], v[30:33]
	v_mfma_f32_16x16x32_bf16 v[26:29], v[86:89], v[182:185], v[26:29]
	v_mfma_f32_16x16x32_bf16 v[14:17], v[70:73], v[220:223], v[14:17]
	v_mfma_f32_16x16x32_bf16 v[10:13], v[86:89], v[220:223], v[10:13]
	v_mfma_f32_16x16x32_bf16 v[54:57], v[146:149], v[162:165], v[54:57]
	v_mfma_f32_16x16x32_bf16 v[50:53], v[154:157], v[162:165], v[50:53]
	v_mfma_f32_16x16x32_bf16 v[38:41], v[146:149], v[170:173], v[38:41]
	v_mfma_f32_16x16x32_bf16 v[34:37], v[154:157], v[170:173], v[34:37]
	v_mfma_f32_16x16x32_bf16 v[22:25], v[146:149], v[178:181], v[22:25]
	v_mfma_f32_16x16x32_bf16 v[18:21], v[154:157], v[178:181], v[18:21]
	v_mfma_f32_16x16x32_bf16 v[6:9], v[146:149], v[216:219], v[6:9]
	v_mfma_f32_16x16x32_bf16 v[2:5], v[154:157], v[216:219], v[2:5]
	v_mfma_f32_16x16x32_bf16 v[54:57], v[150:153], v[166:169], v[54:57]
	v_mfma_f32_16x16x32_bf16 v[50:53], v[158:161], v[166:169], v[50:53]
	v_mfma_f32_16x16x32_bf16 v[38:41], v[150:153], v[174:177], v[38:41]
	v_mfma_f32_16x16x32_bf16 v[34:37], v[158:161], v[174:177], v[34:37]
	v_mfma_f32_16x16x32_bf16 v[22:25], v[150:153], v[182:185], v[22:25]
	v_mfma_f32_16x16x32_bf16 v[18:21], v[158:161], v[182:185], v[18:21]
	v_mfma_f32_16x16x32_bf16 v[6:9], v[150:153], v[220:223], v[6:9]
	v_mfma_f32_16x16x32_bf16 v[2:5], v[158:161], v[220:223], v[2:5]
	s_barrier
	s_add_i32 s8, s8, 2
	s_add_u32 s38, s38, 0x100
	s_addc_u32 s39, s39, 0
	s_add_u32 s6, s6, 0x100
	s_addc_u32 s7, s7, 0
	s_cmp_gt_u32 s8, 29
.LBB0_927:
	s_add_u32 s9, s38, 0xfff80080
	s_addc_u32 s10, s39, -1
	s_add_i32 s11, 0, 0x10000
	s_cmp_eq_u32 s8, 28
	s_cselect_b32 s95, s36, s10
	s_cselect_b32 s94, s37, s9
	s_cselect_b32 s47, s4, s7
	s_cselect_b32 s46, s5, s6
	s_add_i32 s9, 0, 0x14000
	ds_read_b128 v[66:69], v186
	ds_read_b128 v[70:73], v186 offset:1024
	ds_read_b128 v[78:81], v186 offset:2048
	ds_read_b128 v[86:89], v186 offset:3072
	ds_read_b128 v[146:149], v187
	ds_read_b128 v[150:153], v187 offset:1024
	ds_read_b128 v[154:157], v187 offset:2048
	ds_read_b128 v[158:161], v187 offset:3072
	s_add_i32 m0, s66, 0xc000
	ds_read_b128 v[162:165], v236
	ds_read_b128 v[166:169], v236 offset:1024
	ds_read_b128 v[170:173], v236 offset:2048
	ds_read_b128 v[174:177], v236 offset:3072
	ds_read_b128 v[178:181], v236 offset:4096
	ds_read_b128 v[182:185], v236 offset:5120
	ds_read_b128 v[216:219], v236 offset:6144
	ds_read_b128 v[220:223], v236 offset:7168
	global_load_lds_dwordx4 v212, s[38:39]
	s_add_i32 m0, s66, 0xe000
	s_nop 0
	global_load_lds_dwordx4 v214, s[38:39]
	s_cmp_lg_u32 s70, 0
	s_cbranch_scc1 .Llw_25187
	s_waitcnt vmcnt(8)
	s_waitcnt lgkmcnt(0)
; #define PG8_STAGE(bufoff, gbase, voff) do { _Pragma("unroll") for (int _i = 0; _i < 2; ++_i) \
;         __builtin_amdgcn_global_load_lds((const unsigned*)((const char*)(gbase) + (voff)[_i]), (PG8_LAS unsigned*)(lds + (bufoff) + ldsw + _i * 8192), 16, 0, 0); } while (0)
; #define PG8_LDA(dst, b, h) do { _Pragma("unroll") for (int m = 0; m < 4; ++m) _Pragma("unroll") for (int k = 0; k < 2; ++k) dst[m][k] = *(const PG8_LAS bf16x8*)(lds + PG8_SA(b, h) + aoff + m * 2048 + k * 1024); } while (0)
; #define PG8_LDB(dst, b, h) do { _Pragma("unroll") for (int n = 0; n < 2; ++n) _Pragma("unroll") for (int k = 0; k < 2; ++k) dst[n][k] = *(const PG8_LAS bf16x8*)(lds + PG8_SB(b, h) + boff + n * 2048 + k * 1024); } while (0)
; #define PG8_MMA(ai, bj, At, Bt) do { __builtin_amdgcn_s_setprio(1); _Pragma("unroll") for (int m = 0; m < 4; ++m) _Pragma("unroll") for (int n = 0; n < 2; ++n) _Pragma("unroll") for (int k = 0; k < 2; ++k) \
;         acc[ai][bj][m][n] = __builtin_amdgcn_mfma_f32_16x16x32_bf16(Bt[n][k], At[m][k], acc[ai][bj][m][n], 0, 0, 0); __builtin_amdgcn_s_setprio(0); } while (0)
; #define PG8_WAIT_V(n) asm volatile("s_waitcnt vmcnt(" #n ")" ::: "memory")
; #define PG8_WAIT_L(n) asm volatile("s_waitcnt lgkmcnt(" #n ")" ::: "memory")
; #define PG8_BAR __builtin_amdgcn_s_barrier()
; #define PG8_SCHED __builtin_amdgcn_sched_barrier(0)
; template <class Epi, class Sched, bool ALIGN_EPI = false, bool SP2 = false>
; __device__ __forceinline__ void gemm_phase(PG8_LAS unsigned char* lds, const Gemm g, const Sched& S, const Epi& E) {
;     ...
;             PG8_WAIT_V(8); PG8_WAIT_L(0); PG8_BAR; PG8_MMA(0, 0, At, B0); PG8_MMA(0, 1, At, B1); PG8_BAR; PG8_SCHED;
;             PG8_LDA(At, 0, 1); PG8_STAGE(PG8_SB(0, 0), b2, voffB); PG8_STAGE(PG8_SB(0, 1), b2 + hstepB, voffB); PG8_STAGE(PG8_SA(0, 0), a2, voffA);
;             PG8_WAIT_V(8); PG8_WAIT_L(0); PG8_BAR; PG8_MMA(1, 0, At, B0); PG8_MMA(1, 1, At, B1); PG8_BAR; PG8_SCHED;
;             PG8_LDB(B0, 1, 0); PG8_LDB(B1, 1, 1); PG8_SCHED; PG8_LDA(At, 1, 0); PG8_STAGE(PG8_SA(0, 1), a2 + hstep, voffA);
.Llw_25187:
	s_barrier
	s_waitcnt vmcnt(8)
	s_waitcnt lgkmcnt(0)
	v_mfma_f32_16x16x32_bf16 v[142:145], v[66:69], v[162:165], v[142:145]
	v_mfma_f32_16x16x32_bf16 v[138:141], v[78:81], v[162:165], v[138:141]
	v_mfma_f32_16x16x32_bf16 v[126:129], v[66:69], v[170:173], v[126:129]
	v_mfma_f32_16x16x32_bf16 v[122:125], v[78:81], v[170:173], v[122:125]
	v_mfma_f32_16x16x32_bf16 v[110:113], v[66:69], v[178:181], v[110:113]
	v_mfma_f32_16x16x32_bf16 v[106:109], v[78:81], v[178:181], v[106:109]
	v_mfma_f32_16x16x32_bf16 v[94:97], v[66:69], v[216:219], v[94:97]
	v_mfma_f32_16x16x32_bf16 v[90:93], v[78:81], v[216:219], v[90:93]
	v_mfma_f32_16x16x32_bf16 v[142:145], v[70:73], v[166:169], v[142:145]
	v_mfma_f32_16x16x32_bf16 v[138:141], v[86:89], v[166:169], v[138:141]
	v_mfma_f32_16x16x32_bf16 v[126:129], v[70:73], v[174:177], v[126:129]
	v_mfma_f32_16x16x32_bf16 v[122:125], v[86:89], v[174:177], v[122:125]
	v_mfma_f32_16x16x32_bf16 v[110:113], v[70:73], v[182:185], v[110:113]
	v_mfma_f32_16x16x32_bf16 v[106:109], v[86:89], v[182:185], v[106:109]
	v_mfma_f32_16x16x32_bf16 v[94:97], v[70:73], v[220:223], v[94:97]
	v_mfma_f32_16x16x32_bf16 v[90:93], v[86:89], v[220:223], v[90:93]
	v_mfma_f32_16x16x32_bf16 v[134:137], v[146:149], v[162:165], v[134:137]
	v_mfma_f32_16x16x32_bf16 v[130:133], v[154:157], v[162:165], v[130:133]
	v_mfma_f32_16x16x32_bf16 v[118:121], v[146:149], v[170:173], v[118:121]
	v_mfma_f32_16x16x32_bf16 v[114:117], v[154:157], v[170:173], v[114:117]
	v_mfma_f32_16x16x32_bf16 v[102:105], v[146:149], v[178:181], v[102:105]
	v_mfma_f32_16x16x32_bf16 v[98:101], v[154:157], v[178:181], v[98:101]
	v_mfma_f32_16x16x32_bf16 v[82:85], v[146:149], v[216:219], v[82:85]
	v_mfma_f32_16x16x32_bf16 v[74:77], v[154:157], v[216:219], v[74:77]
	v_mfma_f32_16x16x32_bf16 v[134:137], v[150:153], v[166:169], v[134:137]
	v_mfma_f32_16x16x32_bf16 v[130:133], v[158:161], v[166:169], v[130:133]
	v_mfma_f32_16x16x32_bf16 v[118:121], v[150:153], v[174:177], v[118:121]
	v_mfma_f32_16x16x32_bf16 v[114:117], v[158:161], v[174:177], v[114:117]
	v_mfma_f32_16x16x32_bf16 v[102:105], v[150:153], v[182:185], v[102:105]
	v_mfma_f32_16x16x32_bf16 v[98:101], v[158:161], v[182:185], v[98:101]
	v_mfma_f32_16x16x32_bf16 v[82:85], v[150:153], v[220:223], v[82:85]
	v_mfma_f32_16x16x32_bf16 v[74:77], v[158:161], v[220:223], v[74:77]
	s_barrier
	s_add_i32 s10, s11, s25
	s_mov_b32 m0, s10
	ds_read_b128 v[162:165], v236 offset:16384
	ds_read_b128 v[166:169], v236 offset:17408
	ds_read_b128 v[170:173], v236 offset:18432
	ds_read_b128 v[174:177], v236 offset:19456
	ds_read_b128 v[178:181], v236 offset:20480
	ds_read_b128 v[182:185], v236 offset:21504
	ds_read_b128 v[216:219], v236 offset:22528
	ds_read_b128 v[220:223], v236 offset:23552
	global_load_lds_dwordx4 v190, s[46:47]
	s_add_i32 m0, s10, 0x2000
	s_add_u32 s10, s46, 0x20000
	s_addc_u32 s11, s47, 0
	s_add_i32 s9, s9, s25
	global_load_lds_dwordx4 v206, s[46:47]
	s_mov_b32 m0, s9
	s_nop 0
	global_load_lds_dwordx4 v190, s[10:11]
	s_add_i32 m0, s9, 0x2000
	s_nop 0
	global_load_lds_dwordx4 v206, s[10:11]
	s_mov_b32 m0, s66
	s_nop 0
	global_load_lds_dwordx4 v210, s[94:95]
	s_mov_b32 m0, s67
	s_nop 0
	global_load_lds_dwordx4 v208, s[94:95]
	s_cmp_lg_u32 s70, 0
	s_cbranch_scc1 .Llw_25256
	s_waitcnt vmcnt(8)
	s_waitcnt lgkmcnt(0)
.Llw_25256:
	s_barrier
	s_waitcnt vmcnt(8)
	s_waitcnt lgkmcnt(0)
	v_mfma_f32_16x16x32_bf16 v[62:65], v[66:69], v[162:165], v[62:65]
	v_mfma_f32_16x16x32_bf16 v[58:61], v[78:81], v[162:165], v[58:61]
	v_mfma_f32_16x16x32_bf16 v[46:49], v[66:69], v[170:173], v[46:49]
	v_mfma_f32_16x16x32_bf16 v[42:45], v[78:81], v[170:173], v[42:45]
	v_mfma_f32_16x16x32_bf16 v[30:33], v[66:69], v[178:181], v[30:33]
	v_mfma_f32_16x16x32_bf16 v[26:29], v[78:81], v[178:181], v[26:29]
	v_mfma_f32_16x16x32_bf16 v[14:17], v[66:69], v[216:219], v[14:17]
	v_mfma_f32_16x16x32_bf16 v[10:13], v[78:81], v[216:219], v[10:13]
	v_mfma_f32_16x16x32_bf16 v[62:65], v[70:73], v[166:169], v[62:65]
	v_mfma_f32_16x16x32_bf16 v[58:61], v[86:89], v[166:169], v[58:61]
	v_mfma_f32_16x16x32_bf16 v[46:49], v[70:73], v[174:177], v[46:49]
	v_mfma_f32_16x16x32_bf16 v[42:45], v[86:89], v[174:177], v[42:45]
	v_mfma_f32_16x16x32_bf16 v[30:33], v[70:73], v[182:185], v[30:33]
	v_mfma_f32_16x16x32_bf16 v[26:29], v[86:89], v[182:185], v[26:29]
	v_mfma_f32_16x16x32_bf16 v[14:17], v[70:73], v[220:223], v[14:17]
	v_mfma_f32_16x16x32_bf16 v[10:13], v[86:89], v[220:223], v[10:13]
	v_mfma_f32_16x16x32_bf16 v[54:57], v[146:149], v[162:165], v[54:57]
	v_mfma_f32_16x16x32_bf16 v[50:53], v[154:157], v[162:165], v[50:53]
	v_mfma_f32_16x16x32_bf16 v[38:41], v[146:149], v[170:173], v[38:41]
	v_mfma_f32_16x16x32_bf16 v[34:37], v[154:157], v[170:173], v[34:37]
	v_mfma_f32_16x16x32_bf16 v[22:25], v[146:149], v[178:181], v[22:25]
	v_mfma_f32_16x16x32_bf16 v[18:21], v[154:157], v[178:181], v[18:21]
	v_mfma_f32_16x16x32_bf16 v[6:9], v[146:149], v[216:219], v[6:9]
	v_mfma_f32_16x16x32_bf16 v[2:5], v[154:157], v[216:219], v[2:5]
	v_mfma_f32_16x16x32_bf16 v[54:57], v[150:153], v[166:169], v[54:57]
	v_mfma_f32_16x16x32_bf16 v[50:53], v[158:161], v[166:169], v[50:53]
	v_mfma_f32_16x16x32_bf16 v[38:41], v[150:153], v[174:177], v[38:41]
	v_mfma_f32_16x16x32_bf16 v[34:37], v[158:161], v[174:177], v[34:37]
	v_mfma_f32_16x16x32_bf16 v[22:25], v[150:153], v[182:185], v[22:25]
	v_mfma_f32_16x16x32_bf16 v[18:21], v[158:161], v[182:185], v[18:21]
	v_mfma_f32_16x16x32_bf16 v[6:9], v[150:153], v[220:223], v[6:9]
	v_mfma_f32_16x16x32_bf16 v[2:5], v[158:161], v[220:223], v[2:5]
	s_barrier
	s_add_i32 s9, 0, 0x18000
	s_add_i32 s12, 0, 0x1c000
	ds_read_b128 v[66:69], v198
	ds_read_b128 v[70:73], v198 offset:1024
	ds_read_b128 v[78:81], v198 offset:2048
	ds_read_b128 v[86:89], v198 offset:3072
	ds_read_b128 v[146:149], v199
	ds_read_b128 v[150:153], v199 offset:1024
	ds_read_b128 v[154:157], v199 offset:2048
	ds_read_b128 v[158:161], v199 offset:3072
	s_add_u32 s10, s94, 0x80000
	s_addc_u32 s11, s95, 0
	s_mov_b32 m0, s59
	ds_read_b128 v[162:165], v236 offset:32768
	ds_read_b128 v[166:169], v236 offset:33792
	ds_read_b128 v[170:173], v236 offset:34816
	ds_read_b128 v[174:177], v236 offset:35840
	ds_read_b128 v[178:181], v236 offset:36864
	ds_read_b128 v[182:185], v236 offset:37888
	ds_read_b128 v[216:219], v236 offset:38912
	ds_read_b128 v[220:223], v236 offset:39936
	global_load_lds_dwordx4 v210, s[10:11]
	s_mov_b32 m0, s74
	s_nop 0
	global_load_lds_dwordx4 v208, s[10:11]
	s_cmp_lg_u32 s70, 0
	s_cbranch_scc1 .Llw_25323
	s_waitcnt vmcnt(8)
	s_waitcnt lgkmcnt(0)

; #define PG8_STAGE(bufoff, gbase, voff) do { _Pragma("unroll") for (int _i = 0; _i < 2; ++_i) \
;         __builtin_amdgcn_global_load_lds((const unsigned*)((const char*)(gbase) + (voff)[_i]), (PG8_LAS unsigned*)(lds + (bufoff) + ldsw + _i * 8192), 16, 0, 0); } while (0)
; #define PG8_LDA(dst, b, h) do { _Pragma("unroll") for (int m = 0; m < 4; ++m) _Pragma("unroll") for (int k = 0; k < 2; ++k) dst[m][k] = *(const PG8_LAS bf16x8*)(lds + PG8_SA(b, h) + aoff + m * 2048 + k * 1024); } while (0)
; #define PG8_MMA(ai, bj, At, Bt) do { __builtin_amdgcn_s_setprio(1); _Pragma("unroll") for (int m = 0; m < 4; ++m) _Pragma("unroll") for (int n = 0; n < 2; ++n) _Pragma("unroll") for (int k = 0; k < 2; ++k) \
;         acc[ai][bj][m][n] = __builtin_amdgcn_mfma_f32_16x16x32_bf16(Bt[n][k], At[m][k], acc[ai][bj][m][n], 0, 0, 0); __builtin_amdgcn_s_setprio(0); } while (0)
; #define PG8_WAIT_V(n) asm volatile("s_waitcnt vmcnt(" #n ")" ::: "memory")
; #define PG8_WAIT_L(n) asm volatile("s_waitcnt lgkmcnt(" #n ")" ::: "memory")
; #define PG8_BAR __builtin_amdgcn_s_barrier()
; #define PG8_SCHED __builtin_amdgcn_sched_barrier(0)
; template <class Epi, class Sched, bool ALIGN_EPI = false, bool SP2 = false>
; __device__ __forceinline__ void gemm_phase(PG8_LAS unsigned char* lds, const Gemm g, const Sched& S, const Epi& E) {
;     ...
;             PG8_WAIT_V(8); PG8_WAIT_L(0); PG8_BAR; PG8_MMA(0, 0, At, B0); PG8_MMA(0, 1, At, B1); PG8_BAR; PG8_SCHED;
;             PG8_LDA(At, 1, 1); PG8_STAGE(PG8_SB(1, 0), b3, voffB); PG8_STAGE(PG8_SB(1, 1), b3 + hstepB, voffB); PG8_STAGE(PG8_SA(1, 0), a3, voffA);
;             PG8_WAIT_V(8); PG8_WAIT_L(0); PG8_BAR; PG8_MMA(1, 0, At, B0); PG8_MMA(1, 1, At, B1); PG8_BAR; PG8_SCHED;
;     ...
;         if constexpr (ALIGN_EPI) { if (wr == 0) PG8_BAR; }
.Llw_25395:
	s_barrier
	s_waitcnt vmcnt(8)
	s_waitcnt lgkmcnt(0)
	v_mfma_f32_16x16x32_bf16 v[62:65], v[66:69], v[162:165], v[62:65]
	v_mfma_f32_16x16x32_bf16 v[58:61], v[78:81], v[162:165], v[58:61]
	v_mfma_f32_16x16x32_bf16 v[46:49], v[66:69], v[170:173], v[46:49]
	v_mfma_f32_16x16x32_bf16 v[42:45], v[78:81], v[170:173], v[42:45]
	v_mfma_f32_16x16x32_bf16 v[30:33], v[66:69], v[178:181], v[30:33]
	v_mfma_f32_16x16x32_bf16 v[26:29], v[78:81], v[178:181], v[26:29]
	v_mfma_f32_16x16x32_bf16 v[14:17], v[66:69], v[216:219], v[14:17]
	v_mfma_f32_16x16x32_bf16 v[10:13], v[78:81], v[216:219], v[10:13]
	v_mfma_f32_16x16x32_bf16 v[62:65], v[70:73], v[166:169], v[62:65]
	v_mfma_f32_16x16x32_bf16 v[58:61], v[86:89], v[166:169], v[58:61]
	v_mfma_f32_16x16x32_bf16 v[46:49], v[70:73], v[174:177], v[46:49]
	v_mfma_f32_16x16x32_bf16 v[42:45], v[86:89], v[174:177], v[42:45]
	v_mfma_f32_16x16x32_bf16 v[30:33], v[70:73], v[182:185], v[30:33]
	v_mfma_f32_16x16x32_bf16 v[26:29], v[86:89], v[182:185], v[26:29]
	v_mfma_f32_16x16x32_bf16 v[14:17], v[70:73], v[220:223], v[14:17]
	v_mfma_f32_16x16x32_bf16 v[10:13], v[86:89], v[220:223], v[10:13]
	v_mfma_f32_16x16x32_bf16 v[54:57], v[146:149], v[162:165], v[54:57]
	v_mfma_f32_16x16x32_bf16 v[50:53], v[154:157], v[162:165], v[50:53]
	v_mfma_f32_16x16x32_bf16 v[38:41], v[146:149], v[170:173], v[38:41]
	v_mfma_f32_16x16x32_bf16 v[34:37], v[154:157], v[170:173], v[34:37]
	v_mfma_f32_16x16x32_bf16 v[22:25], v[146:149], v[178:181], v[22:25]
	v_mfma_f32_16x16x32_bf16 v[18:21], v[154:157], v[178:181], v[18:21]
	v_mfma_f32_16x16x32_bf16 v[6:9], v[146:149], v[216:219], v[6:9]
	v_mfma_f32_16x16x32_bf16 v[2:5], v[154:157], v[216:219], v[2:5]
	v_mfma_f32_16x16x32_bf16 v[54:57], v[150:153], v[166:169], v[54:57]
	v_mfma_f32_16x16x32_bf16 v[50:53], v[158:161], v[166:169], v[50:53]
	v_mfma_f32_16x16x32_bf16 v[38:41], v[150:153], v[174:177], v[38:41]
	v_mfma_f32_16x16x32_bf16 v[34:37], v[158:161], v[174:177], v[34:37]
	v_mfma_f32_16x16x32_bf16 v[22:25], v[150:153], v[182:185], v[22:25]
	v_mfma_f32_16x16x32_bf16 v[18:21], v[158:161], v[182:185], v[18:21]
	v_mfma_f32_16x16x32_bf16 v[6:9], v[150:153], v[220:223], v[6:9]
	v_mfma_f32_16x16x32_bf16 v[2:5], v[158:161], v[220:223], v[2:5]
	s_barrier
	s_add_i32 s8, s8, 2
	s_add_u32 s38, s38, 0x100
	s_addc_u32 s39, s39, 0
	s_add_u32 s6, s6, 0x100
	s_addc_u32 s7, s7, 0
	s_cmp_gt_u32 s8, 29
	s_cbranch_scc0 .LBB0_927
	s_and_b64 vcc, exec, s[70:71]
	s_cbranch_vccz .LBB0_930
	s_barrier

; #define PG8_STAGE(bufoff, gbase, voff) do { _Pragma("unroll") for (int _i = 0; _i < 2; ++_i) \
;         __builtin_amdgcn_global_load_lds((const unsigned*)((const char*)(gbase) + (voff)[_i]), (PG8_LAS unsigned*)(lds + (bufoff) + ldsw + _i * 8192), 16, 0, 0); } while (0)
; #define PG8_LDA(dst, b, h) do { _Pragma("unroll") for (int m = 0; m < 4; ++m) _Pragma("unroll") for (int k = 0; k < 2; ++k) dst[m][k] = *(const PG8_LAS bf16x8*)(lds + PG8_SA(b, h) + aoff + m * 2048 + k * 1024); } while (0)
; #define PG8_LDB(dst, b, h) do { _Pragma("unroll") for (int n = 0; n < 2; ++n) _Pragma("unroll") for (int k = 0; k < 2; ++k) dst[n][k] = *(const PG8_LAS bf16x8*)(lds + PG8_SB(b, h) + boff + n * 2048 + k * 1024); } while (0)
; #define PG8_WAIT_V(n) asm volatile("s_waitcnt vmcnt(" #n ")" ::: "memory")
; #define PG8_WAIT_L(n) asm volatile("s_waitcnt lgkmcnt(" #n ")" ::: "memory")
; #define PG8_BAR __builtin_amdgcn_s_barrier()
; #define PG8_SCHED __builtin_amdgcn_sched_barrier(0)
; template <class Epi, class Sched, bool ALIGN_EPI = false, bool SP2 = false>
; __device__ __forceinline__ void gemm_phase(PG8_LAS unsigned char* lds, const Gemm g, const Sched& S, const Epi& E) {
;     ...
;         const char* nA = has_next ? (const char*)g.A + (size_t)nxt.pm * tstep : cA; const char* nB = has_next ? (const char*)g.Bt + (size_t)nxt.pn * tstep : cB;
;         for (int t = 0; t < nt; t += 2) {
;             const bool last = (t == nt - 2);
;             const char* a1 = cA + (size_t)(t + 1) * kstep;
;             const char* a2 = last ? nA : cA + (size_t)(t + 2) * kstep; const char* b2 = last ? nB : cB + (size_t)(t + 2) * kstep;
;             const char* a3 = a2 + kstep; const char* b3 = b2 + kstep;
;             if (last && has_next) S.a_ready(nxt);
;             if constexpr (SP2) {
;             PG8_LDB(B0, 0, 0); PG8_LDB(B1, 0, 1); PG8_SCHED; PG8_LDA(At, 0, 0); PG8_STAGE(PG8_SA(1, 1), a1 + hstep, voffA);
;             PG8_WAIT_V(8); PG8_WAIT_L(0); PG8_BAR; PG8_MMA(0, 0, At, B0); PG8_MMA(0, 1, At, B1); PG8_BAR; PG8_SCHED;
;             PG8_LDA(At, 0, 1); PG8_STAGE(PG8_SB(0, 0), b2, voffB); PG8_STAGE(PG8_SB(0, 1), b2 + hstepB, voffB); PG8_STAGE(PG8_SA(0, 0), a2, voffA);
;             PG8_WAIT_V(8); PG8_WAIT_L(0); PG8_BAR; PG8_MMA(1, 0, At, B0); PG8_MMA(1, 1, At, B1); PG8_BAR; PG8_SCHED;
.LBB0_1070:
	s_ashr_i32 s97, s96, 31
	s_lshl_b64 s[4:5], s[96:97], 22
	s_add_u32 s26, s0, s4
	s_addc_u32 s27, s1, s5
	s_and_b64 s[4:5], s[92:93], exec
	s_cselect_b32 s97, s27, s39
	s_cselect_b32 s4, s26, s38
	s_ashr_i32 s85, s84, 31
	s_lshl_b64 s[6:7], s[84:85], 22
	s_add_u32 s94, s56, s6
	s_addc_u32 s95, s57, s7
	s_and_b64 s[6:7], s[92:93], exec
	s_cselect_b32 s5, s95, s47
	s_cselect_b32 s6, s94, s46
	s_add_u32 s38, s38, 0x200080
	s_addc_u32 s39, s39, 0
	s_add_u32 s7, s46, 0x100
	s_addc_u32 s8, s47, 0
	s_mov_b32 s9, -2
	s_waitcnt lgkmcnt(0)
	v_add_u32_e32 v186, 0x10000, v164
	v_add_u32_e32 v187, 0x14000, v164
	v_add_u32_e32 v198, 0x18000, v164
	v_add_u32_e32 v199, 0x1c000, v164
	s_add_u32 s10, s38, 0xffe00080
	s_addc_u32 s11, s39, -1
	s_add_i32 s12, 0, 0x10000
	s_cmpk_eq_i32 s9, 0x7c
	s_cselect_b32 vcc_hi, s97, s11
	s_cselect_b32 vcc_lo, s4, s10
	s_cselect_b32 s47, s5, s8
	s_cselect_b32 s46, s6, s7
	s_add_i32 s13, 0, 0x14000
	ds_read_b128 v[130:133], v186
	ds_read_b128 v[134:137], v186 offset:1024
	ds_read_b128 v[138:141], v186 offset:2048
	ds_read_b128 v[152:155], v186 offset:3072
	ds_read_b128 v[156:159], v187
	ds_read_b128 v[160:163], v187 offset:1024
	ds_read_b128 v[168:171], v187 offset:2048
	ds_read_b128 v[172:175], v187 offset:3072
	s_add_i32 m0, s74, 0xc000
	ds_read_b128 v[176:179], v166
	ds_read_b128 v[180:183], v166 offset:1024
	ds_read_b128 v[206:209], v166 offset:2048
	ds_read_b128 v[210:213], v166 offset:3072
	ds_read_b128 v[214:217], v166 offset:4096
	ds_read_b128 v[218:221], v166 offset:5120
	ds_read_b128 v[236:239], v166 offset:6144
	ds_read_b128 v[240:243], v166 offset:7168
	global_load_lds_dwordx4 v148, s[38:39]
	s_add_i32 m0, s74, 0xe000
	s_nop 0
	global_load_lds_dwordx4 v150, s[38:39]
	s_cmp_lg_u32 s72, 0
	s_cbranch_scc1 .Llw_27841
	s_waitcnt vmcnt(8)
	s_waitcnt lgkmcnt(0)
.Llw_27841:
	s_barrier
	s_waitcnt vmcnt(8)
	s_waitcnt lgkmcnt(0)
	v_mfma_f32_16x16x32_bf16 v[126:129], v[130:133], v[176:179], 0
	v_mfma_f32_16x16x32_bf16 v[122:125], v[138:141], v[176:179], 0
	v_mfma_f32_16x16x32_bf16 v[110:113], v[130:133], v[206:209], 0
	v_mfma_f32_16x16x32_bf16 v[106:109], v[138:141], v[206:209], 0
	v_mfma_f32_16x16x32_bf16 v[94:97], v[130:133], v[214:217], 0
	v_mfma_f32_16x16x32_bf16 v[90:93], v[138:141], v[214:217], 0
	v_mfma_f32_16x16x32_bf16 v[78:81], v[130:133], v[236:239], 0
	v_mfma_f32_16x16x32_bf16 v[74:77], v[138:141], v[236:239], 0
	v_mfma_f32_16x16x32_bf16 v[126:129], v[134:137], v[180:183], v[126:129]
	v_mfma_f32_16x16x32_bf16 v[122:125], v[152:155], v[180:183], v[122:125]
	v_mfma_f32_16x16x32_bf16 v[110:113], v[134:137], v[210:213], v[110:113]
	v_mfma_f32_16x16x32_bf16 v[106:109], v[152:155], v[210:213], v[106:109]
	v_mfma_f32_16x16x32_bf16 v[94:97], v[134:137], v[218:221], v[94:97]
	v_mfma_f32_16x16x32_bf16 v[90:93], v[152:155], v[218:221], v[90:93]
	v_mfma_f32_16x16x32_bf16 v[78:81], v[134:137], v[240:243], v[78:81]
	v_mfma_f32_16x16x32_bf16 v[74:77], v[152:155], v[240:243], v[74:77]
	v_mfma_f32_16x16x32_bf16 v[118:121], v[156:159], v[176:179], 0
	v_mfma_f32_16x16x32_bf16 v[114:117], v[168:171], v[176:179], 0
	v_mfma_f32_16x16x32_bf16 v[102:105], v[156:159], v[206:209], 0
	v_mfma_f32_16x16x32_bf16 v[98:101], v[168:171], v[206:209], 0
	v_mfma_f32_16x16x32_bf16 v[86:89], v[156:159], v[214:217], 0
	v_mfma_f32_16x16x32_bf16 v[82:85], v[168:171], v[214:217], 0
	v_mfma_f32_16x16x32_bf16 v[70:73], v[156:159], v[236:239], 0
	v_mfma_f32_16x16x32_bf16 v[66:69], v[168:171], v[236:239], 0
	v_mfma_f32_16x16x32_bf16 v[118:121], v[160:163], v[180:183], v[118:121]
	v_mfma_f32_16x16x32_bf16 v[114:117], v[172:175], v[180:183], v[114:117]
	v_mfma_f32_16x16x32_bf16 v[102:105], v[160:163], v[210:213], v[102:105]
	v_mfma_f32_16x16x32_bf16 v[98:101], v[172:175], v[210:213], v[98:101]
	v_mfma_f32_16x16x32_bf16 v[86:89], v[160:163], v[218:221], v[86:89]
	v_mfma_f32_16x16x32_bf16 v[82:85], v[172:175], v[218:221], v[82:85]
	v_mfma_f32_16x16x32_bf16 v[70:73], v[160:163], v[240:243], v[70:73]
	v_mfma_f32_16x16x32_bf16 v[66:69], v[172:175], v[240:243], v[66:69]
	s_barrier
	s_add_i32 s10, s12, s67
	s_mov_b32 m0, s10
	ds_read_b128 v[176:179], v166 offset:16384
	ds_read_b128 v[180:183], v166 offset:17408
	ds_read_b128 v[206:209], v166 offset:18432
	ds_read_b128 v[210:213], v166 offset:19456
	ds_read_b128 v[214:217], v166 offset:20480
	ds_read_b128 v[218:221], v166 offset:21504
	ds_read_b128 v[236:239], v166 offset:22528
	ds_read_b128 v[240:243], v166 offset:23552
	global_load_lds_dwordx4 v146, s[46:47]
	s_add_i32 m0, s10, 0x2000
	s_add_u32 s10, s46, 0x80000
	s_addc_u32 s11, s47, 0
	s_add_i32 s12, s13, s67
	global_load_lds_dwordx4 v142, s[46:47]
	s_mov_b32 m0, s12
	s_nop 0
	global_load_lds_dwordx4 v146, s[10:11]
	s_add_i32 m0, s12, 0x2000
	s_nop 0
	global_load_lds_dwordx4 v142, s[10:11]
	s_mov_b32 m0, s74
	s_nop 0
	global_load_lds_dwordx4 v190, vcc
	s_mov_b32 m0, s75
	s_nop 0
	global_load_lds_dwordx4 v144, vcc
	s_cmp_lg_u32 s72, 0
	s_cbranch_scc1 .Llw_27910
	s_waitcnt vmcnt(8)
	s_waitcnt lgkmcnt(0)
; #define PG8_STAGE(bufoff, gbase, voff) do { _Pragma("unroll") for (int _i = 0; _i < 2; ++_i) \
;         __builtin_amdgcn_global_load_lds((const unsigned*)((const char*)(gbase) + (voff)[_i]), (PG8_LAS unsigned*)(lds + (bufoff) + ldsw + _i * 8192), 16, 0, 0); } while (0)
; #define PG8_LDA(dst, b, h) do { _Pragma("unroll") for (int m = 0; m < 4; ++m) _Pragma("unroll") for (int k = 0; k < 2; ++k) dst[m][k] = *(const PG8_LAS bf16x8*)(lds + PG8_SA(b, h) + aoff + m * 2048 + k * 1024); } while (0)
; #define PG8_LDB(dst, b, h) do { _Pragma("unroll") for (int n = 0; n < 2; ++n) _Pragma("unroll") for (int k = 0; k < 2; ++k) dst[n][k] = *(const PG8_LAS bf16x8*)(lds + PG8_SB(b, h) + boff + n * 2048 + k * 1024); } while (0)
; #define PG8_MMA(ai, bj, At, Bt) do { __builtin_amdgcn_s_setprio(1); _Pragma("unroll") for (int m = 0; m < 4; ++m) _Pragma("unroll") for (int n = 0; n < 2; ++n) _Pragma("unroll") for (int k = 0; k < 2; ++k) \
;         acc[ai][bj][m][n] = __builtin_amdgcn_mfma_f32_16x16x32_bf16(Bt[n][k], At[m][k], acc[ai][bj][m][n], 0, 0, 0); __builtin_amdgcn_s_setprio(0); } while (0)
; #define PG8_WAIT_V(n) asm volatile("s_waitcnt vmcnt(" #n ")" ::: "memory")
; #define PG8_WAIT_L(n) asm volatile("s_waitcnt lgkmcnt(" #n ")" ::: "memory")
; #define PG8_BAR __builtin_amdgcn_s_barrier()
; #define PG8_SCHED __builtin_amdgcn_sched_barrier(0)
; template <class Epi, class Sched, bool ALIGN_EPI = false, bool SP2 = false>
; __device__ __forceinline__ void gemm_phase(PG8_LAS unsigned char* lds, const Gemm g, const Sched& S, const Epi& E) {
;     ...
;             PG8_WAIT_V(8); PG8_WAIT_L(0); PG8_BAR; PG8_MMA(1, 0, At, B0); PG8_MMA(1, 1, At, B1); PG8_BAR; PG8_SCHED;
;             PG8_LDB(B0, 1, 0); PG8_LDB(B1, 1, 1); PG8_SCHED; PG8_LDA(At, 1, 0); PG8_STAGE(PG8_SA(0, 1), a2 + hstep, voffA);
;             PG8_WAIT_V(8); PG8_WAIT_L(0); PG8_BAR; PG8_MMA(0, 0, At, B0); PG8_MMA(0, 1, At, B1); PG8_BAR; PG8_SCHED;
;             PG8_LDA(At, 1, 1); PG8_STAGE(PG8_SB(1, 0), b3, voffB); PG8_STAGE(PG8_SB(1, 1), b3 + hstepB, voffB); PG8_STAGE(PG8_SA(1, 0), a3, voffA);
;             PG8_WAIT_V(8); PG8_WAIT_L(0); PG8_BAR; PG8_MMA(1, 0, At, B0); PG8_MMA(1, 1, At, B1); PG8_BAR; PG8_SCHED;
.Llw_27910:
	s_barrier
	s_waitcnt vmcnt(8)
	s_waitcnt lgkmcnt(0)
	v_mfma_f32_16x16x32_bf16 v[62:65], v[130:133], v[176:179], 0
	v_mfma_f32_16x16x32_bf16 v[58:61], v[138:141], v[176:179], 0
	v_mfma_f32_16x16x32_bf16 v[46:49], v[130:133], v[206:209], 0
	v_mfma_f32_16x16x32_bf16 v[42:45], v[138:141], v[206:209], 0
	v_mfma_f32_16x16x32_bf16 v[30:33], v[130:133], v[214:217], 0
	v_mfma_f32_16x16x32_bf16 v[26:29], v[138:141], v[214:217], 0
	v_mfma_f32_16x16x32_bf16 v[14:17], v[130:133], v[236:239], 0
	v_mfma_f32_16x16x32_bf16 v[10:13], v[138:141], v[236:239], 0
	v_mfma_f32_16x16x32_bf16 v[62:65], v[134:137], v[180:183], v[62:65]
	v_mfma_f32_16x16x32_bf16 v[58:61], v[152:155], v[180:183], v[58:61]
	v_mfma_f32_16x16x32_bf16 v[46:49], v[134:137], v[210:213], v[46:49]
	v_mfma_f32_16x16x32_bf16 v[42:45], v[152:155], v[210:213], v[42:45]
	v_mfma_f32_16x16x32_bf16 v[30:33], v[134:137], v[218:221], v[30:33]
	v_mfma_f32_16x16x32_bf16 v[26:29], v[152:155], v[218:221], v[26:29]
	v_mfma_f32_16x16x32_bf16 v[14:17], v[134:137], v[240:243], v[14:17]
	v_mfma_f32_16x16x32_bf16 v[10:13], v[152:155], v[240:243], v[10:13]
	v_mfma_f32_16x16x32_bf16 v[54:57], v[156:159], v[176:179], 0
	v_mfma_f32_16x16x32_bf16 v[50:53], v[168:171], v[176:179], 0
	v_mfma_f32_16x16x32_bf16 v[38:41], v[156:159], v[206:209], 0
	v_mfma_f32_16x16x32_bf16 v[34:37], v[168:171], v[206:209], 0
	v_mfma_f32_16x16x32_bf16 v[22:25], v[156:159], v[214:217], 0
	v_mfma_f32_16x16x32_bf16 v[18:21], v[168:171], v[214:217], 0
	v_mfma_f32_16x16x32_bf16 v[6:9], v[156:159], v[236:239], 0
	v_mfma_f32_16x16x32_bf16 v[2:5], v[168:171], v[236:239], 0
	v_mfma_f32_16x16x32_bf16 v[54:57], v[160:163], v[180:183], v[54:57]
	v_mfma_f32_16x16x32_bf16 v[50:53], v[172:175], v[180:183], v[50:53]
	v_mfma_f32_16x16x32_bf16 v[38:41], v[160:163], v[210:213], v[38:41]
	v_mfma_f32_16x16x32_bf16 v[34:37], v[172:175], v[210:213], v[34:37]
	v_mfma_f32_16x16x32_bf16 v[22:25], v[160:163], v[218:221], v[22:25]
	v_mfma_f32_16x16x32_bf16 v[18:21], v[172:175], v[218:221], v[18:21]
	v_mfma_f32_16x16x32_bf16 v[6:9], v[160:163], v[240:243], v[6:9]
	v_mfma_f32_16x16x32_bf16 v[2:5], v[172:175], v[240:243], v[2:5]
	s_barrier
	s_add_i32 s12, 0, 0x18000
	s_add_i32 s13, 0, 0x1c000
	ds_read_b128 v[130:133], v198
	ds_read_b128 v[134:137], v198 offset:1024
	ds_read_b128 v[138:141], v198 offset:2048
	ds_read_b128 v[152:155], v198 offset:3072
	ds_read_b128 v[156:159], v199
	ds_read_b128 v[160:163], v199 offset:1024
	ds_read_b128 v[168:171], v199 offset:2048
	ds_read_b128 v[172:175], v199 offset:3072
	s_add_u32 s10, vcc_lo, 0x200000
	s_addc_u32 s11, vcc_hi, 0
	s_mov_b32 m0, s86
	ds_read_b128 v[176:179], v166 offset:32768
	ds_read_b128 v[180:183], v166 offset:33792
	ds_read_b128 v[206:209], v166 offset:34816
	ds_read_b128 v[210:213], v166 offset:35840
	ds_read_b128 v[214:217], v166 offset:36864
	ds_read_b128 v[218:221], v166 offset:37888
	ds_read_b128 v[236:239], v166 offset:38912
	ds_read_b128 v[240:243], v166 offset:39936
	global_load_lds_dwordx4 v190, s[10:11]
	s_mov_b32 m0, s87
	s_nop 0
	global_load_lds_dwordx4 v144, s[10:11]
	s_cmp_lg_u32 s72, 0
	s_cbranch_scc1 .Llw_27977
	s_waitcnt vmcnt(8)
	s_waitcnt lgkmcnt(0)
.Llw_27977:
	s_barrier
	s_waitcnt vmcnt(8)
	s_waitcnt lgkmcnt(0)
	v_mfma_f32_16x16x32_bf16 v[126:129], v[130:133], v[176:179], v[126:129]
	v_mfma_f32_16x16x32_bf16 v[122:125], v[138:141], v[176:179], v[122:125]
	v_mfma_f32_16x16x32_bf16 v[110:113], v[130:133], v[206:209], v[110:113]
	v_mfma_f32_16x16x32_bf16 v[106:109], v[138:141], v[206:209], v[106:109]
	v_mfma_f32_16x16x32_bf16 v[94:97], v[130:133], v[214:217], v[94:97]
	v_mfma_f32_16x16x32_bf16 v[90:93], v[138:141], v[214:217], v[90:93]
	v_mfma_f32_16x16x32_bf16 v[78:81], v[130:133], v[236:239], v[78:81]
	v_mfma_f32_16x16x32_bf16 v[74:77], v[138:141], v[236:239], v[74:77]
	v_mfma_f32_16x16x32_bf16 v[126:129], v[134:137], v[180:183], v[126:129]
	v_mfma_f32_16x16x32_bf16 v[122:125], v[152:155], v[180:183], v[122:125]
	v_mfma_f32_16x16x32_bf16 v[110:113], v[134:137], v[210:213], v[110:113]
	v_mfma_f32_16x16x32_bf16 v[106:109], v[152:155], v[210:213], v[106:109]
	v_mfma_f32_16x16x32_bf16 v[94:97], v[134:137], v[218:221], v[94:97]
	v_mfma_f32_16x16x32_bf16 v[90:93], v[152:155], v[218:221], v[90:93]
	v_mfma_f32_16x16x32_bf16 v[78:81], v[134:137], v[240:243], v[78:81]
	v_mfma_f32_16x16x32_bf16 v[74:77], v[152:155], v[240:243], v[74:77]
	v_mfma_f32_16x16x32_bf16 v[118:121], v[156:159], v[176:179], v[118:121]
	v_mfma_f32_16x16x32_bf16 v[114:117], v[168:171], v[176:179], v[114:117]
	v_mfma_f32_16x16x32_bf16 v[102:105], v[156:159], v[206:209], v[102:105]
	v_mfma_f32_16x16x32_bf16 v[98:101], v[168:171], v[206:209], v[98:101]
	v_mfma_f32_16x16x32_bf16 v[86:89], v[156:159], v[214:217], v[86:89]
	v_mfma_f32_16x16x32_bf16 v[82:85], v[168:171], v[214:217], v[82:85]
	v_mfma_f32_16x16x32_bf16 v[70:73], v[156:159], v[236:239], v[70:73]
	v_mfma_f32_16x16x32_bf16 v[66:69], v[168:171], v[236:239], v[66:69]
	v_mfma_f32_16x16x32_bf16 v[118:121], v[160:163], v[180:183], v[118:121]
	v_mfma_f32_16x16x32_bf16 v[114:117], v[172:175], v[180:183], v[114:117]
	v_mfma_f32_16x16x32_bf16 v[102:105], v[160:163], v[210:213], v[102:105]
	v_mfma_f32_16x16x32_bf16 v[98:101], v[172:175], v[210:213], v[98:101]
	v_mfma_f32_16x16x32_bf16 v[86:89], v[160:163], v[218:221], v[86:89]
	v_mfma_f32_16x16x32_bf16 v[82:85], v[172:175], v[218:221], v[82:85]
	v_mfma_f32_16x16x32_bf16 v[70:73], v[160:163], v[240:243], v[70:73]
	v_mfma_f32_16x16x32_bf16 v[66:69], v[172:175], v[240:243], v[66:69]
	s_barrier
	s_add_i32 s10, s12, s67
	s_mov_b32 m0, s10
	ds_read_b128 v[176:179], v166 offset:49152
	ds_read_b128 v[180:183], v166 offset:50176
	ds_read_b128 v[206:209], v166 offset:51200
	ds_read_b128 v[210:213], v166 offset:52224
	ds_read_b128 v[214:217], v166 offset:53248
	ds_read_b128 v[218:221], v166 offset:54272
	ds_read_b128 v[236:239], v166 offset:55296
	ds_read_b128 v[240:243], v166 offset:56320
	s_add_u32 s100, s46, s60
	s_addc_u32 s101, s47, s61
	global_load_lds_dwordx4 v146, s[100:101]
	s_add_i32 m0, s10, 0x2000
	s_add_u32 s10, s46, 0x80080
	s_addc_u32 s11, s47, 0
	s_add_i32 s12, s13, s67
	global_load_lds_dwordx4 v142, s[100:101]
	s_mov_b32 m0, s12
	s_nop 0
	global_load_lds_dwordx4 v146, s[10:11]
	s_add_i32 m0, s12, 0x2000
	s_nop 0
	global_load_lds_dwordx4 v142, s[10:11]
	s_mov_b32 m0, s82
	s_add_u32 s100, vcc_lo, s60
	s_addc_u32 s101, vcc_hi, s61
	global_load_lds_dwordx4 v190, s[100:101]
	s_mov_b32 m0, s42
	s_nop 0
	global_load_lds_dwordx4 v144, s[100:101]
	s_cmp_lg_u32 s72, 0
	s_cbranch_scc1 .Llw_28049
	s_waitcnt vmcnt(8)
	s_waitcnt lgkmcnt(0)
; #define PG8_STAGE(bufoff, gbase, voff) do { _Pragma("unroll") for (int _i = 0; _i < 2; ++_i) \
;         __builtin_amdgcn_global_load_lds((const unsigned*)((const char*)(gbase) + (voff)[_i]), (PG8_LAS unsigned*)(lds + (bufoff) + ldsw + _i * 8192), 16, 0, 0); } while (0)
; #define PG8_LDA(dst, b, h) do { _Pragma("unroll") for (int m = 0; m < 4; ++m) _Pragma("unroll") for (int k = 0; k < 2; ++k) dst[m][k] = *(const PG8_LAS bf16x8*)(lds + PG8_SA(b, h) + aoff + m * 2048 + k * 1024); } while (0)
; #define PG8_LDB(dst, b, h) do { _Pragma("unroll") for (int n = 0; n < 2; ++n) _Pragma("unroll") for (int k = 0; k < 2; ++k) dst[n][k] = *(const PG8_LAS bf16x8*)(lds + PG8_SB(b, h) + boff + n * 2048 + k * 1024); } while (0)
; #define PG8_MMA(ai, bj, At, Bt) do { __builtin_amdgcn_s_setprio(1); _Pragma("unroll") for (int m = 0; m < 4; ++m) _Pragma("unroll") for (int n = 0; n < 2; ++n) _Pragma("unroll") for (int k = 0; k < 2; ++k) \
;         acc[ai][bj][m][n] = __builtin_amdgcn_mfma_f32_16x16x32_bf16(Bt[n][k], At[m][k], acc[ai][bj][m][n], 0, 0, 0); __builtin_amdgcn_s_setprio(0); } while (0)
; #define PG8_WAIT_V(n) asm volatile("s_waitcnt vmcnt(" #n ")" ::: "memory")
; #define PG8_WAIT_L(n) asm volatile("s_waitcnt lgkmcnt(" #n ")" ::: "memory")
; #define PG8_BAR __builtin_amdgcn_s_barrier()
; #define PG8_SCHED __builtin_amdgcn_sched_barrier(0)
; template <class Epi, class Sched, bool ALIGN_EPI = false, bool SP2 = false>
; __device__ __forceinline__ void gemm_phase(PG8_LAS unsigned char* lds, const Gemm g, const Sched& S, const Epi& E) {
;     ...
;         for (int t = 0; t < nt; t += 2) {
;             const bool last = (t == nt - 2);
;             const char* a1 = cA + (size_t)(t + 1) * kstep;
;             const char* a2 = last ? nA : cA + (size_t)(t + 2) * kstep; const char* b2 = last ? nB : cB + (size_t)(t + 2) * kstep;
;             const char* a3 = a2 + kstep; const char* b3 = b2 + kstep;
;             if (last && has_next) S.a_ready(nxt);
;             if constexpr (SP2) {
;             PG8_LDB(B0, 0, 0); PG8_LDB(B1, 0, 1); PG8_SCHED; PG8_LDA(At, 0, 0); PG8_STAGE(PG8_SA(1, 1), a1 + hstep, voffA);
;             PG8_WAIT_V(8); PG8_WAIT_L(0); PG8_BAR; PG8_MMA(0, 0, At, B0); PG8_MMA(0, 1, At, B1); PG8_BAR; PG8_SCHED;
;     ...
;             PG8_WAIT_V(8); PG8_WAIT_L(0); PG8_BAR; PG8_MMA(1, 0, At, B0); PG8_MMA(1, 1, At, B1); PG8_BAR; PG8_SCHED;
.Llw_28049:
	s_barrier
	s_waitcnt vmcnt(8)
	s_waitcnt lgkmcnt(0)
	v_mfma_f32_16x16x32_bf16 v[62:65], v[130:133], v[176:179], v[62:65]
	v_mfma_f32_16x16x32_bf16 v[58:61], v[138:141], v[176:179], v[58:61]
	v_mfma_f32_16x16x32_bf16 v[46:49], v[130:133], v[206:209], v[46:49]
	v_mfma_f32_16x16x32_bf16 v[42:45], v[138:141], v[206:209], v[42:45]
	v_mfma_f32_16x16x32_bf16 v[30:33], v[130:133], v[214:217], v[30:33]
	v_mfma_f32_16x16x32_bf16 v[26:29], v[138:141], v[214:217], v[26:29]
	v_mfma_f32_16x16x32_bf16 v[14:17], v[130:133], v[236:239], v[14:17]
	v_mfma_f32_16x16x32_bf16 v[10:13], v[138:141], v[236:239], v[10:13]
	v_mfma_f32_16x16x32_bf16 v[62:65], v[134:137], v[180:183], v[62:65]
	v_mfma_f32_16x16x32_bf16 v[58:61], v[152:155], v[180:183], v[58:61]
	v_mfma_f32_16x16x32_bf16 v[46:49], v[134:137], v[210:213], v[46:49]
	v_mfma_f32_16x16x32_bf16 v[42:45], v[152:155], v[210:213], v[42:45]
	v_mfma_f32_16x16x32_bf16 v[30:33], v[134:137], v[218:221], v[30:33]
	v_mfma_f32_16x16x32_bf16 v[26:29], v[152:155], v[218:221], v[26:29]
	v_mfma_f32_16x16x32_bf16 v[14:17], v[134:137], v[240:243], v[14:17]
	v_mfma_f32_16x16x32_bf16 v[10:13], v[152:155], v[240:243], v[10:13]
	v_mfma_f32_16x16x32_bf16 v[54:57], v[156:159], v[176:179], v[54:57]
	v_mfma_f32_16x16x32_bf16 v[50:53], v[168:171], v[176:179], v[50:53]
	v_mfma_f32_16x16x32_bf16 v[38:41], v[156:159], v[206:209], v[38:41]
	v_mfma_f32_16x16x32_bf16 v[34:37], v[168:171], v[206:209], v[34:37]
	v_mfma_f32_16x16x32_bf16 v[22:25], v[156:159], v[214:217], v[22:25]
	v_mfma_f32_16x16x32_bf16 v[18:21], v[168:171], v[214:217], v[18:21]
	v_mfma_f32_16x16x32_bf16 v[6:9], v[156:159], v[236:239], v[6:9]
	v_mfma_f32_16x16x32_bf16 v[2:5], v[168:171], v[236:239], v[2:5]
	v_mfma_f32_16x16x32_bf16 v[54:57], v[160:163], v[180:183], v[54:57]
	v_mfma_f32_16x16x32_bf16 v[50:53], v[172:175], v[180:183], v[50:53]
	v_mfma_f32_16x16x32_bf16 v[38:41], v[160:163], v[210:213], v[38:41]
	v_mfma_f32_16x16x32_bf16 v[34:37], v[172:175], v[210:213], v[34:37]
	v_mfma_f32_16x16x32_bf16 v[22:25], v[160:163], v[218:221], v[22:25]
	v_mfma_f32_16x16x32_bf16 v[18:21], v[172:175], v[218:221], v[18:21]
	v_mfma_f32_16x16x32_bf16 v[6:9], v[160:163], v[240:243], v[6:9]
	v_mfma_f32_16x16x32_bf16 v[2:5], v[172:175], v[240:243], v[2:5]
	s_barrier
	s_add_i32 s9, s9, 2
	s_add_u32 s38, s38, 0x100
	s_addc_u32 s39, s39, 0
	s_add_u32 s7, s7, 0x100
	s_addc_u32 s8, s8, 0
	s_cmpk_gt_u32 s9, 0x7d
.LBB0_1071:
	s_add_u32 s10, s38, 0xffe00080
	s_addc_u32 s11, s39, -1
	s_add_i32 s12, 0, 0x10000
	s_cmpk_eq_i32 s9, 0x7c
	s_cselect_b32 vcc_hi, s97, s11
	s_cselect_b32 vcc_lo, s4, s10
	s_cselect_b32 s47, s5, s8
	s_cselect_b32 s46, s6, s7
	s_add_i32 s13, 0, 0x14000
	ds_read_b128 v[130:133], v186
	ds_read_b128 v[134:137], v186 offset:1024
	ds_read_b128 v[138:141], v186 offset:2048
	ds_read_b128 v[152:155], v186 offset:3072
	ds_read_b128 v[156:159], v187
	ds_read_b128 v[160:163], v187 offset:1024
	ds_read_b128 v[168:171], v187 offset:2048
	ds_read_b128 v[172:175], v187 offset:3072
	s_add_i32 m0, s74, 0xc000
	ds_read_b128 v[176:179], v166
	ds_read_b128 v[180:183], v166 offset:1024
	ds_read_b128 v[206:209], v166 offset:2048
	ds_read_b128 v[210:213], v166 offset:3072
	ds_read_b128 v[214:217], v166 offset:4096
	ds_read_b128 v[218:221], v166 offset:5120
	ds_read_b128 v[236:239], v166 offset:6144
	ds_read_b128 v[240:243], v166 offset:7168
	global_load_lds_dwordx4 v148, s[38:39]
	s_add_i32 m0, s74, 0xe000
	s_nop 0
	global_load_lds_dwordx4 v150, s[38:39]
	s_cmp_lg_u32 s72, 0
	s_cbranch_scc1 .Llw_28131
	s_waitcnt vmcnt(8)
	s_waitcnt lgkmcnt(0)
; #define PG8_STAGE(bufoff, gbase, voff) do { _Pragma("unroll") for (int _i = 0; _i < 2; ++_i) \
;         __builtin_amdgcn_global_load_lds((const unsigned*)((const char*)(gbase) + (voff)[_i]), (PG8_LAS unsigned*)(lds + (bufoff) + ldsw + _i * 8192), 16, 0, 0); } while (0)
; #define PG8_LDA(dst, b, h) do { _Pragma("unroll") for (int m = 0; m < 4; ++m) _Pragma("unroll") for (int k = 0; k < 2; ++k) dst[m][k] = *(const PG8_LAS bf16x8*)(lds + PG8_SA(b, h) + aoff + m * 2048 + k * 1024); } while (0)
; #define PG8_LDB(dst, b, h) do { _Pragma("unroll") for (int n = 0; n < 2; ++n) _Pragma("unroll") for (int k = 0; k < 2; ++k) dst[n][k] = *(const PG8_LAS bf16x8*)(lds + PG8_SB(b, h) + boff + n * 2048 + k * 1024); } while (0)
; #define PG8_MMA(ai, bj, At, Bt) do { __builtin_amdgcn_s_setprio(1); _Pragma("unroll") for (int m = 0; m < 4; ++m) _Pragma("unroll") for (int n = 0; n < 2; ++n) _Pragma("unroll") for (int k = 0; k < 2; ++k) \
;         acc[ai][bj][m][n] = __builtin_amdgcn_mfma_f32_16x16x32_bf16(Bt[n][k], At[m][k], acc[ai][bj][m][n], 0, 0, 0); __builtin_amdgcn_s_setprio(0); } while (0)
; #define PG8_WAIT_V(n) asm volatile("s_waitcnt vmcnt(" #n ")" ::: "memory")
; #define PG8_WAIT_L(n) asm volatile("s_waitcnt lgkmcnt(" #n ")" ::: "memory")
; #define PG8_BAR __builtin_amdgcn_s_barrier()
; #define PG8_SCHED __builtin_amdgcn_sched_barrier(0)
; template <class Epi, class Sched, bool ALIGN_EPI = false, bool SP2 = false>
; __device__ __forceinline__ void gemm_phase(PG8_LAS unsigned char* lds, const Gemm g, const Sched& S, const Epi& E) {
;     ...
;             PG8_WAIT_V(8); PG8_WAIT_L(0); PG8_BAR; PG8_MMA(0, 0, At, B0); PG8_MMA(0, 1, At, B1); PG8_BAR; PG8_SCHED;
;             PG8_LDA(At, 0, 1); PG8_STAGE(PG8_SB(0, 0), b2, voffB); PG8_STAGE(PG8_SB(0, 1), b2 + hstepB, voffB); PG8_STAGE(PG8_SA(0, 0), a2, voffA);
;             PG8_WAIT_V(8); PG8_WAIT_L(0); PG8_BAR; PG8_MMA(1, 0, At, B0); PG8_MMA(1, 1, At, B1); PG8_BAR; PG8_SCHED;
;             PG8_LDB(B0, 1, 0); PG8_LDB(B1, 1, 1); PG8_SCHED; PG8_LDA(At, 1, 0); PG8_STAGE(PG8_SA(0, 1), a2 + hstep, voffA);
;             PG8_WAIT_V(8); PG8_WAIT_L(0); PG8_BAR; PG8_MMA(0, 0, At, B0); PG8_MMA(0, 1, At, B1); PG8_BAR; PG8_SCHED;
;             PG8_LDA(At, 1, 1); PG8_STAGE(PG8_SB(1, 0), b3, voffB); PG8_STAGE(PG8_SB(1, 1), b3 + hstepB, voffB); PG8_STAGE(PG8_SA(1, 0), a3, voffA);
.Llw_28131:
	s_barrier
	s_waitcnt vmcnt(8)
	s_waitcnt lgkmcnt(0)
	v_mfma_f32_16x16x32_bf16 v[126:129], v[130:133], v[176:179], v[126:129]
	v_mfma_f32_16x16x32_bf16 v[122:125], v[138:141], v[176:179], v[122:125]
	v_mfma_f32_16x16x32_bf16 v[110:113], v[130:133], v[206:209], v[110:113]
	v_mfma_f32_16x16x32_bf16 v[106:109], v[138:141], v[206:209], v[106:109]
	v_mfma_f32_16x16x32_bf16 v[94:97], v[130:133], v[214:217], v[94:97]
	v_mfma_f32_16x16x32_bf16 v[90:93], v[138:141], v[214:217], v[90:93]
	v_mfma_f32_16x16x32_bf16 v[78:81], v[130:133], v[236:239], v[78:81]
	v_mfma_f32_16x16x32_bf16 v[74:77], v[138:141], v[236:239], v[74:77]
	v_mfma_f32_16x16x32_bf16 v[126:129], v[134:137], v[180:183], v[126:129]
	v_mfma_f32_16x16x32_bf16 v[122:125], v[152:155], v[180:183], v[122:125]
	v_mfma_f32_16x16x32_bf16 v[110:113], v[134:137], v[210:213], v[110:113]
	v_mfma_f32_16x16x32_bf16 v[106:109], v[152:155], v[210:213], v[106:109]
	v_mfma_f32_16x16x32_bf16 v[94:97], v[134:137], v[218:221], v[94:97]
	v_mfma_f32_16x16x32_bf16 v[90:93], v[152:155], v[218:221], v[90:93]
	v_mfma_f32_16x16x32_bf16 v[78:81], v[134:137], v[240:243], v[78:81]
	v_mfma_f32_16x16x32_bf16 v[74:77], v[152:155], v[240:243], v[74:77]
	v_mfma_f32_16x16x32_bf16 v[118:121], v[156:159], v[176:179], v[118:121]
	v_mfma_f32_16x16x32_bf16 v[114:117], v[168:171], v[176:179], v[114:117]
	v_mfma_f32_16x16x32_bf16 v[102:105], v[156:159], v[206:209], v[102:105]
	v_mfma_f32_16x16x32_bf16 v[98:101], v[168:171], v[206:209], v[98:101]
	v_mfma_f32_16x16x32_bf16 v[86:89], v[156:159], v[214:217], v[86:89]
	v_mfma_f32_16x16x32_bf16 v[82:85], v[168:171], v[214:217], v[82:85]
	v_mfma_f32_16x16x32_bf16 v[70:73], v[156:159], v[236:239], v[70:73]
	v_mfma_f32_16x16x32_bf16 v[66:69], v[168:171], v[236:239], v[66:69]
	v_mfma_f32_16x16x32_bf16 v[118:121], v[160:163], v[180:183], v[118:121]
	v_mfma_f32_16x16x32_bf16 v[114:117], v[172:175], v[180:183], v[114:117]
	v_mfma_f32_16x16x32_bf16 v[102:105], v[160:163], v[210:213], v[102:105]
	v_mfma_f32_16x16x32_bf16 v[98:101], v[172:175], v[210:213], v[98:101]
	v_mfma_f32_16x16x32_bf16 v[86:89], v[160:163], v[218:221], v[86:89]
	v_mfma_f32_16x16x32_bf16 v[82:85], v[172:175], v[218:221], v[82:85]
	v_mfma_f32_16x16x32_bf16 v[70:73], v[160:163], v[240:243], v[70:73]
	v_mfma_f32_16x16x32_bf16 v[66:69], v[172:175], v[240:243], v[66:69]
	s_barrier
	s_add_i32 s10, s12, s67
	s_mov_b32 m0, s10
	ds_read_b128 v[176:179], v166 offset:16384
	ds_read_b128 v[180:183], v166 offset:17408
	ds_read_b128 v[206:209], v166 offset:18432
	ds_read_b128 v[210:213], v166 offset:19456
	ds_read_b128 v[214:217], v166 offset:20480
	ds_read_b128 v[218:221], v166 offset:21504
	ds_read_b128 v[236:239], v166 offset:22528
	ds_read_b128 v[240:243], v166 offset:23552
	global_load_lds_dwordx4 v146, s[46:47]
	s_add_i32 m0, s10, 0x2000
	s_add_u32 s10, s46, 0x80000
	s_addc_u32 s11, s47, 0
	s_add_i32 s12, s13, s67
	global_load_lds_dwordx4 v142, s[46:47]
	s_mov_b32 m0, s12
	s_nop 0
	global_load_lds_dwordx4 v146, s[10:11]
	s_add_i32 m0, s12, 0x2000
	s_nop 0
	global_load_lds_dwordx4 v142, s[10:11]
	s_mov_b32 m0, s74
	s_nop 0
	global_load_lds_dwordx4 v190, vcc
	s_mov_b32 m0, s75
	s_nop 0
	global_load_lds_dwordx4 v144, vcc
	s_cmp_lg_u32 s72, 0
	s_cbranch_scc1 .Llw_28200
	s_waitcnt vmcnt(8)
	s_waitcnt lgkmcnt(0)
.Llw_28200:
	s_barrier
	s_waitcnt vmcnt(8)
	s_waitcnt lgkmcnt(0)
	v_mfma_f32_16x16x32_bf16 v[62:65], v[130:133], v[176:179], v[62:65]
	v_mfma_f32_16x16x32_bf16 v[58:61], v[138:141], v[176:179], v[58:61]
	v_mfma_f32_16x16x32_bf16 v[46:49], v[130:133], v[206:209], v[46:49]
	v_mfma_f32_16x16x32_bf16 v[42:45], v[138:141], v[206:209], v[42:45]
	v_mfma_f32_16x16x32_bf16 v[30:33], v[130:133], v[214:217], v[30:33]
	v_mfma_f32_16x16x32_bf16 v[26:29], v[138:141], v[214:217], v[26:29]
	v_mfma_f32_16x16x32_bf16 v[14:17], v[130:133], v[236:239], v[14:17]
	v_mfma_f32_16x16x32_bf16 v[10:13], v[138:141], v[236:239], v[10:13]
	v_mfma_f32_16x16x32_bf16 v[62:65], v[134:137], v[180:183], v[62:65]
	v_mfma_f32_16x16x32_bf16 v[58:61], v[152:155], v[180:183], v[58:61]
	v_mfma_f32_16x16x32_bf16 v[46:49], v[134:137], v[210:213], v[46:49]
	v_mfma_f32_16x16x32_bf16 v[42:45], v[152:155], v[210:213], v[42:45]
	v_mfma_f32_16x16x32_bf16 v[30:33], v[134:137], v[218:221], v[30:33]
	v_mfma_f32_16x16x32_bf16 v[26:29], v[152:155], v[218:221], v[26:29]
	v_mfma_f32_16x16x32_bf16 v[14:17], v[134:137], v[240:243], v[14:17]
	v_mfma_f32_16x16x32_bf16 v[10:13], v[152:155], v[240:243], v[10:13]
	v_mfma_f32_16x16x32_bf16 v[54:57], v[156:159], v[176:179], v[54:57]
	v_mfma_f32_16x16x32_bf16 v[50:53], v[168:171], v[176:179], v[50:53]
	v_mfma_f32_16x16x32_bf16 v[38:41], v[156:159], v[206:209], v[38:41]
	v_mfma_f32_16x16x32_bf16 v[34:37], v[168:171], v[206:209], v[34:37]
	v_mfma_f32_16x16x32_bf16 v[22:25], v[156:159], v[214:217], v[22:25]
	v_mfma_f32_16x16x32_bf16 v[18:21], v[168:171], v[214:217], v[18:21]
	v_mfma_f32_16x16x32_bf16 v[6:9], v[156:159], v[236:239], v[6:9]
	v_mfma_f32_16x16x32_bf16 v[2:5], v[168:171], v[236:239], v[2:5]
	v_mfma_f32_16x16x32_bf16 v[54:57], v[160:163], v[180:183], v[54:57]
	v_mfma_f32_16x16x32_bf16 v[50:53], v[172:175], v[180:183], v[50:53]
	v_mfma_f32_16x16x32_bf16 v[38:41], v[160:163], v[210:213], v[38:41]
	v_mfma_f32_16x16x32_bf16 v[34:37], v[172:175], v[210:213], v[34:37]
	v_mfma_f32_16x16x32_bf16 v[22:25], v[160:163], v[218:221], v[22:25]
	v_mfma_f32_16x16x32_bf16 v[18:21], v[172:175], v[218:221], v[18:21]
	v_mfma_f32_16x16x32_bf16 v[6:9], v[160:163], v[240:243], v[6:9]
	v_mfma_f32_16x16x32_bf16 v[2:5], v[172:175], v[240:243], v[2:5]
	s_barrier
	s_add_i32 s12, 0, 0x18000
	s_add_i32 s13, 0, 0x1c000
	ds_read_b128 v[130:133], v198
	ds_read_b128 v[134:137], v198 offset:1024
	ds_read_b128 v[138:141], v198 offset:2048
	ds_read_b128 v[152:155], v198 offset:3072
	ds_read_b128 v[156:159], v199
	ds_read_b128 v[160:163], v199 offset:1024
	ds_read_b128 v[168:171], v199 offset:2048
	ds_read_b128 v[172:175], v199 offset:3072
	s_add_u32 s10, vcc_lo, 0x200000
	s_addc_u32 s11, vcc_hi, 0
	s_mov_b32 m0, s86
	ds_read_b128 v[176:179], v166 offset:32768
	ds_read_b128 v[180:183], v166 offset:33792
	ds_read_b128 v[206:209], v166 offset:34816
	ds_read_b128 v[210:213], v166 offset:35840
	ds_read_b128 v[214:217], v166 offset:36864
	ds_read_b128 v[218:221], v166 offset:37888
	ds_read_b128 v[236:239], v166 offset:38912
	ds_read_b128 v[240:243], v166 offset:39936
	global_load_lds_dwordx4 v190, s[10:11]
	s_mov_b32 m0, s87
	s_nop 0
	global_load_lds_dwordx4 v144, s[10:11]
	s_cmp_lg_u32 s72, 0
	s_cbranch_scc1 .Llw_28267
	s_waitcnt vmcnt(8)
	s_waitcnt lgkmcnt(0)

; #define PG8_STAGE(bufoff, gbase, voff) do { _Pragma("unroll") for (int _i = 0; _i < 2; ++_i) \
;         __builtin_amdgcn_global_load_lds((const unsigned*)((const char*)(gbase) + (voff)[_i]), (PG8_LAS unsigned*)(lds + (bufoff) + ldsw + _i * 8192), 16, 0, 0); } while (0)
; #define PG8_LDA(dst, b, h) do { _Pragma("unroll") for (int m = 0; m < 4; ++m) _Pragma("unroll") for (int k = 0; k < 2; ++k) dst[m][k] = *(const PG8_LAS bf16x8*)(lds + PG8_SA(b, h) + aoff + m * 2048 + k * 1024); } while (0)
; #define PG8_MMA(ai, bj, At, Bt) do { __builtin_amdgcn_s_setprio(1); _Pragma("unroll") for (int m = 0; m < 4; ++m) _Pragma("unroll") for (int n = 0; n < 2; ++n) _Pragma("unroll") for (int k = 0; k < 2; ++k) \
;         acc[ai][bj][m][n] = __builtin_amdgcn_mfma_f32_16x16x32_bf16(Bt[n][k], At[m][k], acc[ai][bj][m][n], 0, 0, 0); __builtin_amdgcn_s_setprio(0); } while (0)
; #define PG8_WAIT_V(n) asm volatile("s_waitcnt vmcnt(" #n ")" ::: "memory")
; #define PG8_WAIT_L(n) asm volatile("s_waitcnt lgkmcnt(" #n ")" ::: "memory")
; #define PG8_BAR __builtin_amdgcn_s_barrier()
; #define PG8_SCHED __builtin_amdgcn_sched_barrier(0)
; template <class Epi, class Sched, bool ALIGN_EPI = false, bool SP2 = false>
; __device__ __forceinline__ void gemm_phase(PG8_LAS unsigned char* lds, const Gemm g, const Sched& S, const Epi& E) {
;     ...
;             PG8_WAIT_V(8); PG8_WAIT_L(0); PG8_BAR; PG8_MMA(0, 0, At, B0); PG8_MMA(0, 1, At, B1); PG8_BAR; PG8_SCHED;
;             PG8_LDA(At, 1, 1); PG8_STAGE(PG8_SB(1, 0), b3, voffB); PG8_STAGE(PG8_SB(1, 1), b3 + hstepB, voffB); PG8_STAGE(PG8_SA(1, 0), a3, voffA);
;             PG8_WAIT_V(8); PG8_WAIT_L(0); PG8_BAR; PG8_MMA(1, 0, At, B0); PG8_MMA(1, 1, At, B1); PG8_BAR; PG8_SCHED;
;     ...
;         if constexpr (ALIGN_EPI) { if (wr == 0) PG8_BAR; }
.Llw_28339:
	s_barrier
	s_waitcnt vmcnt(8)
	s_waitcnt lgkmcnt(0)
	v_mfma_f32_16x16x32_bf16 v[62:65], v[130:133], v[176:179], v[62:65]
	v_mfma_f32_16x16x32_bf16 v[58:61], v[138:141], v[176:179], v[58:61]
	v_mfma_f32_16x16x32_bf16 v[46:49], v[130:133], v[206:209], v[46:49]
	v_mfma_f32_16x16x32_bf16 v[42:45], v[138:141], v[206:209], v[42:45]
	v_mfma_f32_16x16x32_bf16 v[30:33], v[130:133], v[214:217], v[30:33]
	v_mfma_f32_16x16x32_bf16 v[26:29], v[138:141], v[214:217], v[26:29]
	v_mfma_f32_16x16x32_bf16 v[14:17], v[130:133], v[236:239], v[14:17]
	v_mfma_f32_16x16x32_bf16 v[10:13], v[138:141], v[236:239], v[10:13]
	v_mfma_f32_16x16x32_bf16 v[62:65], v[134:137], v[180:183], v[62:65]
	v_mfma_f32_16x16x32_bf16 v[58:61], v[152:155], v[180:183], v[58:61]
	v_mfma_f32_16x16x32_bf16 v[46:49], v[134:137], v[210:213], v[46:49]
	v_mfma_f32_16x16x32_bf16 v[42:45], v[152:155], v[210:213], v[42:45]
	v_mfma_f32_16x16x32_bf16 v[30:33], v[134:137], v[218:221], v[30:33]
	v_mfma_f32_16x16x32_bf16 v[26:29], v[152:155], v[218:221], v[26:29]
	v_mfma_f32_16x16x32_bf16 v[14:17], v[134:137], v[240:243], v[14:17]
	v_mfma_f32_16x16x32_bf16 v[10:13], v[152:155], v[240:243], v[10:13]
	v_mfma_f32_16x16x32_bf16 v[54:57], v[156:159], v[176:179], v[54:57]
	v_mfma_f32_16x16x32_bf16 v[50:53], v[168:171], v[176:179], v[50:53]
	v_mfma_f32_16x16x32_bf16 v[38:41], v[156:159], v[206:209], v[38:41]
	v_mfma_f32_16x16x32_bf16 v[34:37], v[168:171], v[206:209], v[34:37]
	v_mfma_f32_16x16x32_bf16 v[22:25], v[156:159], v[214:217], v[22:25]
	v_mfma_f32_16x16x32_bf16 v[18:21], v[168:171], v[214:217], v[18:21]
	v_mfma_f32_16x16x32_bf16 v[6:9], v[156:159], v[236:239], v[6:9]
	v_mfma_f32_16x16x32_bf16 v[2:5], v[168:171], v[236:239], v[2:5]
	v_mfma_f32_16x16x32_bf16 v[54:57], v[160:163], v[180:183], v[54:57]
	v_mfma_f32_16x16x32_bf16 v[50:53], v[172:175], v[180:183], v[50:53]
	v_mfma_f32_16x16x32_bf16 v[38:41], v[160:163], v[210:213], v[38:41]
	v_mfma_f32_16x16x32_bf16 v[34:37], v[172:175], v[210:213], v[34:37]
	v_mfma_f32_16x16x32_bf16 v[22:25], v[160:163], v[218:221], v[22:25]
	v_mfma_f32_16x16x32_bf16 v[18:21], v[172:175], v[218:221], v[18:21]
	v_mfma_f32_16x16x32_bf16 v[6:9], v[160:163], v[240:243], v[6:9]
	v_mfma_f32_16x16x32_bf16 v[2:5], v[172:175], v[240:243], v[2:5]
	s_barrier
	s_add_i32 s9, s9, 2
	s_add_u32 s38, s38, 0x100
	s_addc_u32 s39, s39, 0
	s_add_u32 s7, s7, 0x100
	s_addc_u32 s8, s8, 0
	s_cmpk_gt_u32 s9, 0x7d
	s_cbranch_scc0 .LBB0_1071
	s_and_b64 vcc, exec, s[72:73]
	s_cbranch_vccz .LBB0_1074
	s_barrier

; #define PG8_STAGE(bufoff, gbase, voff) do { _Pragma("unroll") for (int _i = 0; _i < 2; ++_i) \
;         __builtin_amdgcn_global_load_lds((const unsigned*)((const char*)(gbase) + (voff)[_i]), (PG8_LAS unsigned*)(lds + (bufoff) + ldsw + _i * 8192), 16, 0, 0); } while (0)
; #define PG8_LDA(dst, b, h) do { _Pragma("unroll") for (int m = 0; m < 4; ++m) _Pragma("unroll") for (int k = 0; k < 2; ++k) dst[m][k] = *(const PG8_LAS bf16x8*)(lds + PG8_SA(b, h) + aoff + m * 2048 + k * 1024); } while (0)
; #define PG8_LDB(dst, b, h) do { _Pragma("unroll") for (int n = 0; n < 2; ++n) _Pragma("unroll") for (int k = 0; k < 2; ++k) dst[n][k] = *(const PG8_LAS bf16x8*)(lds + PG8_SB(b, h) + boff + n * 2048 + k * 1024); } while (0)
; #define PG8_WAIT_V(n) asm volatile("s_waitcnt vmcnt(" #n ")" ::: "memory")
; #define PG8_WAIT_L(n) asm volatile("s_waitcnt lgkmcnt(" #n ")" ::: "memory")
; #define PG8_BAR __builtin_amdgcn_s_barrier()
; #define PG8_SCHED __builtin_amdgcn_sched_barrier(0)
; template <class Epi, class Sched, bool ALIGN_EPI = false, bool SP2 = false>
; __device__ __forceinline__ void gemm_phase(PG8_LAS unsigned char* lds, const Gemm g, const Sched& S, const Epi& E) {
;     ...
;         const char* nA = has_next ? (const char*)g.A + (size_t)nxt.pm * tstep : cA; const char* nB = has_next ? (const char*)g.Bt + (size_t)nxt.pn * tstep : cB;
;         for (int t = 0; t < nt; t += 2) {
;             const bool last = (t == nt - 2);
;             const char* a1 = cA + (size_t)(t + 1) * kstep;
;             const char* a2 = last ? nA : cA + (size_t)(t + 2) * kstep; const char* b2 = last ? nB : cB + (size_t)(t + 2) * kstep;
;             const char* a3 = a2 + kstep; const char* b3 = b2 + kstep;
;             if (last && has_next) S.a_ready(nxt);
;             if constexpr (SP2) {
;             PG8_LDB(B0, 0, 0); PG8_LDB(B1, 0, 1); PG8_SCHED; PG8_LDA(At, 0, 0); PG8_STAGE(PG8_SA(1, 1), a1 + hstep, voffA);
;             PG8_WAIT_V(8); PG8_WAIT_L(0); PG8_BAR; PG8_MMA(0, 0, At, B0); PG8_MMA(0, 1, At, B1); PG8_BAR; PG8_SCHED;
;             PG8_LDA(At, 0, 1); PG8_STAGE(PG8_SB(0, 0), b2, voffB); PG8_STAGE(PG8_SB(0, 1), b2 + hstepB, voffB); PG8_STAGE(PG8_SA(0, 0), a2, voffA);
;             PG8_WAIT_V(8); PG8_WAIT_L(0); PG8_BAR; PG8_MMA(1, 0, At, B0); PG8_MMA(1, 1, At, B1); PG8_BAR; PG8_SCHED;
.LBB0_1232:
	s_add_u32 s36, s80, 0x100
	s_addc_u32 s37, s81, 0
	s_ashr_i32 s73, s72, 31
	s_lshl_b64 s[4:5], s[72:73], 20
	s_add_u32 s78, s0, s4
	s_addc_u32 s79, s1, s5
	s_and_b64 s[4:5], s[46:47], exec
	s_cselect_b32 s4, s79, s69
	s_cselect_b32 s5, s78, s68
	s_ashr_i32 s71, s70, 31
	s_lshl_b64 s[6:7], s[70:71], 20
	s_add_u32 s76, s34, s6
	s_addc_u32 s77, s35, s7
	s_and_b64 s[6:7], s[46:47], exec
	s_cselect_b32 s6, s77, s81
	s_cselect_b32 s7, s76, s80
	s_add_u32 s8, s68, 0x80080
	s_addc_u32 s9, s69, 0
	v_lshl_add_u64 v[140:141], s[8:9], 0, v[136:137]
	v_lshl_add_u64 v[142:143], s[8:9], 0, v[138:139]
	s_mov_b32 s8, -2
	s_mov_b64 s[80:81], 0
	v_add_u32_e32 v186, 0x10000, v145
	v_add_u32_e32 v187, 0x14000, v145
	v_add_u32_e32 v198, 0x18000, v145
	v_add_u32_e32 v199, 0x1c000, v145
	s_add_u32 s9, s68, s80
	s_addc_u32 s10, s69, s81
	s_add_u32 s9, s9, 0x100
	s_addc_u32 s10, s10, 0
	s_add_u32 s100, s9, 0x7ff80
	s_addc_u32 s101, s10, 0
	s_add_u32 s11, s36, s80
	s_addc_u32 s12, s37, s81
	s_add_i32 s13, 0, 0x10000
	s_cmpk_eq_i32 s80, 0xf00
	s_cselect_b32 s93, s4, s10
	s_cselect_b32 s92, s5, s9
	s_cselect_b32 s85, s6, s12
	s_cselect_b32 s84, s7, s11
	s_add_i32 s9, 0, 0x14000
	ds_read_b128 v[152:155], v186
	ds_read_b128 v[156:159], v186 offset:1024
	ds_read_b128 v[160:163], v186 offset:2048
	ds_read_b128 v[164:167], v186 offset:3072
	ds_read_b128 v[168:171], v187
	ds_read_b128 v[172:175], v187 offset:1024
	ds_read_b128 v[176:179], v187 offset:2048
	ds_read_b128 v[180:183], v187 offset:3072
	s_add_i32 m0, s51, 0xc000
	ds_read_b128 v[206:209], v151
	ds_read_b128 v[210:213], v151 offset:1024
	ds_read_b128 v[214:217], v151 offset:2048
	ds_read_b128 v[218:221], v151 offset:3072
	ds_read_b128 v[236:239], v151 offset:4096
	ds_read_b128 v[240:243], v151 offset:5120
	ds_read_b128 v[244:247], v151 offset:6144
	ds_read_b128 v[194:197], v151 offset:7168
	global_load_lds_dwordx4 v136, s[100:101]
	s_add_i32 m0, s51, 0xe000
	s_nop 0
	global_load_lds_dwordx4 v138, s[100:101]
	s_cmp_lg_u32 s62, 0
	s_cbranch_scc1 .Llw_30872
	s_waitcnt vmcnt(8)
	s_waitcnt lgkmcnt(0)
.Llw_30872:
	s_barrier
	s_waitcnt vmcnt(8)
	s_waitcnt lgkmcnt(0)
	v_mfma_f32_16x16x32_bf16 v[126:129], v[152:155], v[206:209], 0
	v_mfma_f32_16x16x32_bf16 v[122:125], v[160:163], v[206:209], 0
	v_mfma_f32_16x16x32_bf16 v[118:121], v[152:155], v[214:217], 0
	v_mfma_f32_16x16x32_bf16 v[114:117], v[160:163], v[214:217], 0
	v_mfma_f32_16x16x32_bf16 v[110:113], v[152:155], v[236:239], 0
	v_mfma_f32_16x16x32_bf16 v[106:109], v[160:163], v[236:239], 0
	v_mfma_f32_16x16x32_bf16 v[102:105], v[152:155], v[244:247], 0
	v_mfma_f32_16x16x32_bf16 v[98:101], v[160:163], v[244:247], 0
	v_mfma_f32_16x16x32_bf16 v[126:129], v[156:159], v[210:213], v[126:129]
	v_mfma_f32_16x16x32_bf16 v[122:125], v[164:167], v[210:213], v[122:125]
	v_mfma_f32_16x16x32_bf16 v[118:121], v[156:159], v[218:221], v[118:121]
	v_mfma_f32_16x16x32_bf16 v[114:117], v[164:167], v[218:221], v[114:117]
	v_mfma_f32_16x16x32_bf16 v[110:113], v[156:159], v[240:243], v[110:113]
	v_mfma_f32_16x16x32_bf16 v[106:109], v[164:167], v[240:243], v[106:109]
	v_mfma_f32_16x16x32_bf16 v[102:105], v[156:159], v[194:197], v[102:105]
	v_mfma_f32_16x16x32_bf16 v[98:101], v[164:167], v[194:197], v[98:101]
	v_mfma_f32_16x16x32_bf16 v[94:97], v[168:171], v[206:209], 0
	v_mfma_f32_16x16x32_bf16 v[90:93], v[176:179], v[206:209], 0
	v_mfma_f32_16x16x32_bf16 v[86:89], v[168:171], v[214:217], 0
	v_mfma_f32_16x16x32_bf16 v[82:85], v[176:179], v[214:217], 0
	v_mfma_f32_16x16x32_bf16 v[78:81], v[168:171], v[236:239], 0
	v_mfma_f32_16x16x32_bf16 v[74:77], v[176:179], v[236:239], 0
	v_mfma_f32_16x16x32_bf16 v[70:73], v[168:171], v[244:247], 0
	v_mfma_f32_16x16x32_bf16 v[66:69], v[176:179], v[244:247], 0
	v_mfma_f32_16x16x32_bf16 v[94:97], v[172:175], v[210:213], v[94:97]
	v_mfma_f32_16x16x32_bf16 v[90:93], v[180:183], v[210:213], v[90:93]
	v_mfma_f32_16x16x32_bf16 v[86:89], v[172:175], v[218:221], v[86:89]
	v_mfma_f32_16x16x32_bf16 v[82:85], v[180:183], v[218:221], v[82:85]
	v_mfma_f32_16x16x32_bf16 v[78:81], v[172:175], v[240:243], v[78:81]
	v_mfma_f32_16x16x32_bf16 v[74:77], v[180:183], v[240:243], v[74:77]
	v_mfma_f32_16x16x32_bf16 v[70:73], v[172:175], v[194:197], v[70:73]
	v_mfma_f32_16x16x32_bf16 v[66:69], v[180:183], v[194:197], v[66:69]
	s_barrier
	s_add_i32 s10, s13, s42
	s_mov_b32 m0, s10
	ds_read_b128 v[194:197], v151 offset:16384
	ds_read_b128 v[206:209], v151 offset:17408
	ds_read_b128 v[210:213], v151 offset:18432
	ds_read_b128 v[214:217], v151 offset:19456
	ds_read_b128 v[218:221], v151 offset:20480
	ds_read_b128 v[236:239], v151 offset:21504
	ds_read_b128 v[240:243], v151 offset:22528
	ds_read_b128 v[244:247], v151 offset:23552
	global_load_lds_dwordx4 v130, s[84:85]
	s_add_i32 m0, s10, 0x2000
	s_add_u32 s10, s84, 0x20000
	s_addc_u32 s11, s85, 0
	s_add_i32 s9, s9, s42
	global_load_lds_dwordx4 v134, s[84:85]
	s_mov_b32 m0, s9
	s_nop 0
	global_load_lds_dwordx4 v130, s[10:11]
	s_add_i32 m0, s9, 0x2000
	s_nop 0
	global_load_lds_dwordx4 v134, s[10:11]
	s_mov_b32 m0, s51
	s_nop 0
	global_load_lds_dwordx4 v190, s[92:93]
	s_mov_b32 m0, s67
	s_nop 0
	global_load_lds_dwordx4 v132, s[92:93]
	s_cmp_lg_u32 s62, 0
	s_cbranch_scc1 .Llw_30941
	s_waitcnt vmcnt(8)
	s_waitcnt lgkmcnt(0)
; #define PG8_STAGE(bufoff, gbase, voff) do { _Pragma("unroll") for (int _i = 0; _i < 2; ++_i) \
;         __builtin_amdgcn_global_load_lds((const unsigned*)((const char*)(gbase) + (voff)[_i]), (PG8_LAS unsigned*)(lds + (bufoff) + ldsw + _i * 8192), 16, 0, 0); } while (0)
; #define PG8_LDA(dst, b, h) do { _Pragma("unroll") for (int m = 0; m < 4; ++m) _Pragma("unroll") for (int k = 0; k < 2; ++k) dst[m][k] = *(const PG8_LAS bf16x8*)(lds + PG8_SA(b, h) + aoff + m * 2048 + k * 1024); } while (0)
; #define PG8_LDB(dst, b, h) do { _Pragma("unroll") for (int n = 0; n < 2; ++n) _Pragma("unroll") for (int k = 0; k < 2; ++k) dst[n][k] = *(const PG8_LAS bf16x8*)(lds + PG8_SB(b, h) + boff + n * 2048 + k * 1024); } while (0)
; #define PG8_MMA(ai, bj, At, Bt) do { __builtin_amdgcn_s_setprio(1); _Pragma("unroll") for (int m = 0; m < 4; ++m) _Pragma("unroll") for (int n = 0; n < 2; ++n) _Pragma("unroll") for (int k = 0; k < 2; ++k) \
;         acc[ai][bj][m][n] = __builtin_amdgcn_mfma_f32_16x16x32_bf16(Bt[n][k], At[m][k], acc[ai][bj][m][n], 0, 0, 0); __builtin_amdgcn_s_setprio(0); } while (0)
; #define PG8_WAIT_V(n) asm volatile("s_waitcnt vmcnt(" #n ")" ::: "memory")
; #define PG8_WAIT_L(n) asm volatile("s_waitcnt lgkmcnt(" #n ")" ::: "memory")
; #define PG8_BAR __builtin_amdgcn_s_barrier()
; #define PG8_SCHED __builtin_amdgcn_sched_barrier(0)
; template <class Epi, class Sched, bool ALIGN_EPI = false, bool SP2 = false>
; __device__ __forceinline__ void gemm_phase(PG8_LAS unsigned char* lds, const Gemm g, const Sched& S, const Epi& E) {
;     ...
;             PG8_WAIT_V(8); PG8_WAIT_L(0); PG8_BAR; PG8_MMA(1, 0, At, B0); PG8_MMA(1, 1, At, B1); PG8_BAR; PG8_SCHED;
;             PG8_LDB(B0, 1, 0); PG8_LDB(B1, 1, 1); PG8_SCHED; PG8_LDA(At, 1, 0); PG8_STAGE(PG8_SA(0, 1), a2 + hstep, voffA);
;             PG8_WAIT_V(8); PG8_WAIT_L(0); PG8_BAR; PG8_MMA(0, 0, At, B0); PG8_MMA(0, 1, At, B1); PG8_BAR; PG8_SCHED;
;             PG8_LDA(At, 1, 1); PG8_STAGE(PG8_SB(1, 0), b3, voffB); PG8_STAGE(PG8_SB(1, 1), b3 + hstepB, voffB); PG8_STAGE(PG8_SA(1, 0), a3, voffA);
;             PG8_WAIT_V(8); PG8_WAIT_L(0); PG8_BAR; PG8_MMA(1, 0, At, B0); PG8_MMA(1, 1, At, B1); PG8_BAR; PG8_SCHED;
.Llw_30941:
	s_barrier
	s_waitcnt vmcnt(8)
	s_waitcnt lgkmcnt(0)
	v_mfma_f32_16x16x32_bf16 v[62:65], v[152:155], v[194:197], 0
	v_mfma_f32_16x16x32_bf16 v[58:61], v[160:163], v[194:197], 0
	v_mfma_f32_16x16x32_bf16 v[54:57], v[152:155], v[210:213], 0
	v_mfma_f32_16x16x32_bf16 v[50:53], v[160:163], v[210:213], 0
	v_mfma_f32_16x16x32_bf16 v[46:49], v[152:155], v[218:221], 0
	v_mfma_f32_16x16x32_bf16 v[42:45], v[160:163], v[218:221], 0
	v_mfma_f32_16x16x32_bf16 v[38:41], v[152:155], v[240:243], 0
	v_mfma_f32_16x16x32_bf16 v[34:37], v[160:163], v[240:243], 0
	v_mfma_f32_16x16x32_bf16 v[62:65], v[156:159], v[206:209], v[62:65]
	v_mfma_f32_16x16x32_bf16 v[58:61], v[164:167], v[206:209], v[58:61]
	v_mfma_f32_16x16x32_bf16 v[54:57], v[156:159], v[214:217], v[54:57]
	v_mfma_f32_16x16x32_bf16 v[50:53], v[164:167], v[214:217], v[50:53]
	v_mfma_f32_16x16x32_bf16 v[46:49], v[156:159], v[236:239], v[46:49]
	v_mfma_f32_16x16x32_bf16 v[42:45], v[164:167], v[236:239], v[42:45]
	v_mfma_f32_16x16x32_bf16 v[38:41], v[156:159], v[244:247], v[38:41]
	v_mfma_f32_16x16x32_bf16 v[34:37], v[164:167], v[244:247], v[34:37]
	v_mfma_f32_16x16x32_bf16 v[30:33], v[168:171], v[194:197], 0
	v_mfma_f32_16x16x32_bf16 v[26:29], v[176:179], v[194:197], 0
	v_mfma_f32_16x16x32_bf16 v[22:25], v[168:171], v[210:213], 0
	v_mfma_f32_16x16x32_bf16 v[18:21], v[176:179], v[210:213], 0
	v_mfma_f32_16x16x32_bf16 v[14:17], v[168:171], v[218:221], 0
	v_mfma_f32_16x16x32_bf16 v[10:13], v[176:179], v[218:221], 0
	v_mfma_f32_16x16x32_bf16 v[6:9], v[168:171], v[240:243], 0
	v_mfma_f32_16x16x32_bf16 v[2:5], v[176:179], v[240:243], 0
	v_mfma_f32_16x16x32_bf16 v[30:33], v[172:175], v[206:209], v[30:33]
	v_mfma_f32_16x16x32_bf16 v[26:29], v[180:183], v[206:209], v[26:29]
	v_mfma_f32_16x16x32_bf16 v[22:25], v[172:175], v[214:217], v[22:25]
	v_mfma_f32_16x16x32_bf16 v[18:21], v[180:183], v[214:217], v[18:21]
	v_mfma_f32_16x16x32_bf16 v[14:17], v[172:175], v[236:239], v[14:17]
	v_mfma_f32_16x16x32_bf16 v[10:13], v[180:183], v[236:239], v[10:13]
	v_mfma_f32_16x16x32_bf16 v[6:9], v[172:175], v[244:247], v[6:9]
	v_mfma_f32_16x16x32_bf16 v[2:5], v[180:183], v[244:247], v[2:5]
	s_barrier
	s_add_i32 s9, 0, 0x18000
	s_add_i32 s12, 0, 0x1c000
	ds_read_b128 v[152:155], v198
	ds_read_b128 v[156:159], v198 offset:1024
	ds_read_b128 v[160:163], v198 offset:2048
	ds_read_b128 v[164:167], v198 offset:3072
	ds_read_b128 v[168:171], v199
	ds_read_b128 v[172:175], v199 offset:1024
	ds_read_b128 v[176:179], v199 offset:2048
	ds_read_b128 v[180:183], v199 offset:3072
	s_add_u32 s10, s92, 0x80000
	s_addc_u32 s11, s93, 0
	s_mov_b32 m0, s74
	ds_read_b128 v[194:197], v151 offset:32768
	ds_read_b128 v[206:209], v151 offset:33792
	ds_read_b128 v[210:213], v151 offset:34816
	ds_read_b128 v[214:217], v151 offset:35840
	ds_read_b128 v[218:221], v151 offset:36864
	ds_read_b128 v[236:239], v151 offset:37888
	ds_read_b128 v[240:243], v151 offset:38912
	ds_read_b128 v[244:247], v151 offset:39936
	global_load_lds_dwordx4 v190, s[10:11]
	s_mov_b32 m0, s75
	s_nop 0
	global_load_lds_dwordx4 v132, s[10:11]
	s_cmp_lg_u32 s62, 0
	s_cbranch_scc1 .Llw_31008
	s_waitcnt vmcnt(8)
	s_waitcnt lgkmcnt(0)
.Llw_31008:
	s_barrier
	s_waitcnt vmcnt(8)
	s_waitcnt lgkmcnt(0)
	v_mfma_f32_16x16x32_bf16 v[126:129], v[152:155], v[194:197], v[126:129]
	v_mfma_f32_16x16x32_bf16 v[122:125], v[160:163], v[194:197], v[122:125]
	v_mfma_f32_16x16x32_bf16 v[118:121], v[152:155], v[210:213], v[118:121]
	v_mfma_f32_16x16x32_bf16 v[114:117], v[160:163], v[210:213], v[114:117]
	v_mfma_f32_16x16x32_bf16 v[110:113], v[152:155], v[218:221], v[110:113]
	v_mfma_f32_16x16x32_bf16 v[106:109], v[160:163], v[218:221], v[106:109]
	v_mfma_f32_16x16x32_bf16 v[102:105], v[152:155], v[240:243], v[102:105]
	v_mfma_f32_16x16x32_bf16 v[98:101], v[160:163], v[240:243], v[98:101]
	v_mfma_f32_16x16x32_bf16 v[126:129], v[156:159], v[206:209], v[126:129]
	v_mfma_f32_16x16x32_bf16 v[122:125], v[164:167], v[206:209], v[122:125]
	v_mfma_f32_16x16x32_bf16 v[118:121], v[156:159], v[214:217], v[118:121]
	v_mfma_f32_16x16x32_bf16 v[114:117], v[164:167], v[214:217], v[114:117]
	v_mfma_f32_16x16x32_bf16 v[110:113], v[156:159], v[236:239], v[110:113]
	v_mfma_f32_16x16x32_bf16 v[106:109], v[164:167], v[236:239], v[106:109]
	v_mfma_f32_16x16x32_bf16 v[102:105], v[156:159], v[244:247], v[102:105]
	v_mfma_f32_16x16x32_bf16 v[98:101], v[164:167], v[244:247], v[98:101]
	v_mfma_f32_16x16x32_bf16 v[94:97], v[168:171], v[194:197], v[94:97]
	v_mfma_f32_16x16x32_bf16 v[90:93], v[176:179], v[194:197], v[90:93]
	v_mfma_f32_16x16x32_bf16 v[86:89], v[168:171], v[210:213], v[86:89]
	v_mfma_f32_16x16x32_bf16 v[82:85], v[176:179], v[210:213], v[82:85]
	v_mfma_f32_16x16x32_bf16 v[78:81], v[168:171], v[218:221], v[78:81]
	v_mfma_f32_16x16x32_bf16 v[74:77], v[176:179], v[218:221], v[74:77]
	v_mfma_f32_16x16x32_bf16 v[70:73], v[168:171], v[240:243], v[70:73]
	v_mfma_f32_16x16x32_bf16 v[66:69], v[176:179], v[240:243], v[66:69]
	v_mfma_f32_16x16x32_bf16 v[94:97], v[172:175], v[206:209], v[94:97]
	v_mfma_f32_16x16x32_bf16 v[90:93], v[180:183], v[206:209], v[90:93]
	v_mfma_f32_16x16x32_bf16 v[86:89], v[172:175], v[214:217], v[86:89]
	v_mfma_f32_16x16x32_bf16 v[82:85], v[180:183], v[214:217], v[82:85]
	v_mfma_f32_16x16x32_bf16 v[78:81], v[172:175], v[236:239], v[78:81]
	v_mfma_f32_16x16x32_bf16 v[74:77], v[180:183], v[236:239], v[74:77]
	v_mfma_f32_16x16x32_bf16 v[70:73], v[172:175], v[244:247], v[70:73]
	v_mfma_f32_16x16x32_bf16 v[66:69], v[180:183], v[244:247], v[66:69]
	s_barrier
	s_add_i32 s9, s9, s42
	s_mov_b32 m0, s9
	ds_read_b128 v[194:197], v151 offset:49152
	ds_read_b128 v[206:209], v151 offset:50176
	ds_read_b128 v[210:213], v151 offset:51200
	ds_read_b128 v[214:217], v151 offset:52224
	ds_read_b128 v[218:221], v151 offset:53248
	ds_read_b128 v[236:239], v151 offset:54272
	ds_read_b128 v[240:243], v151 offset:55296
	ds_read_b128 v[244:247], v151 offset:56320
	s_add_u32 s100, s84, s60
	s_addc_u32 s101, s85, s61
	global_load_lds_dwordx4 v130, s[100:101]
	s_add_i32 m0, s9, 0x2000
	s_add_u32 s10, s84, 0x20080
	s_addc_u32 s11, s85, 0
	s_add_i32 s9, s12, s42
	global_load_lds_dwordx4 v134, s[100:101]
	s_mov_b32 m0, s9
	s_nop 0
	global_load_lds_dwordx4 v130, s[10:11]
	s_add_i32 m0, s9, 0x2000
	s_nop 0
	global_load_lds_dwordx4 v134, s[10:11]
	s_mov_b32 m0, s82
	s_add_u32 s100, s92, s60
	s_addc_u32 s101, s93, s61
	global_load_lds_dwordx4 v190, s[100:101]
	s_mov_b32 m0, s86
	s_nop 0
	global_load_lds_dwordx4 v132, s[100:101]
	s_cmp_lg_u32 s62, 0
	s_cbranch_scc1 .Llw_31080
	s_waitcnt vmcnt(8)
	s_waitcnt lgkmcnt(0)
; #define PG8_STAGE(bufoff, gbase, voff) do { _Pragma("unroll") for (int _i = 0; _i < 2; ++_i) \
;         __builtin_amdgcn_global_load_lds((const unsigned*)((const char*)(gbase) + (voff)[_i]), (PG8_LAS unsigned*)(lds + (bufoff) + ldsw + _i * 8192), 16, 0, 0); } while (0)
; #define PG8_LDA(dst, b, h) do { _Pragma("unroll") for (int m = 0; m < 4; ++m) _Pragma("unroll") for (int k = 0; k < 2; ++k) dst[m][k] = *(const PG8_LAS bf16x8*)(lds + PG8_SA(b, h) + aoff + m * 2048 + k * 1024); } while (0)
; #define PG8_LDB(dst, b, h) do { _Pragma("unroll") for (int n = 0; n < 2; ++n) _Pragma("unroll") for (int k = 0; k < 2; ++k) dst[n][k] = *(const PG8_LAS bf16x8*)(lds + PG8_SB(b, h) + boff + n * 2048 + k * 1024); } while (0)
; #define PG8_MMA(ai, bj, At, Bt) do { __builtin_amdgcn_s_setprio(1); _Pragma("unroll") for (int m = 0; m < 4; ++m) _Pragma("unroll") for (int n = 0; n < 2; ++n) _Pragma("unroll") for (int k = 0; k < 2; ++k) \
;         acc[ai][bj][m][n] = __builtin_amdgcn_mfma_f32_16x16x32_bf16(Bt[n][k], At[m][k], acc[ai][bj][m][n], 0, 0, 0); __builtin_amdgcn_s_setprio(0); } while (0)
; #define PG8_WAIT_V(n) asm volatile("s_waitcnt vmcnt(" #n ")" ::: "memory")
; #define PG8_WAIT_L(n) asm volatile("s_waitcnt lgkmcnt(" #n ")" ::: "memory")
; #define PG8_BAR __builtin_amdgcn_s_barrier()
; #define PG8_SCHED __builtin_amdgcn_sched_barrier(0)
; template <class Epi, class Sched, bool ALIGN_EPI = false, bool SP2 = false>
; __device__ __forceinline__ void gemm_phase(PG8_LAS unsigned char* lds, const Gemm g, const Sched& S, const Epi& E) {
;     ...
;         for (int t = 0; t < nt; t += 2) {
;             const bool last = (t == nt - 2);
;             const char* a1 = cA + (size_t)(t + 1) * kstep;
;             const char* a2 = last ? nA : cA + (size_t)(t + 2) * kstep; const char* b2 = last ? nB : cB + (size_t)(t + 2) * kstep;
;             const char* a3 = a2 + kstep; const char* b3 = b2 + kstep;
;             if (last && has_next) S.a_ready(nxt);
;             if constexpr (SP2) {
;             PG8_LDB(B0, 0, 0); PG8_LDB(B1, 0, 1); PG8_SCHED; PG8_LDA(At, 0, 0); PG8_STAGE(PG8_SA(1, 1), a1 + hstep, voffA);
;             PG8_WAIT_V(8); PG8_WAIT_L(0); PG8_BAR; PG8_MMA(0, 0, At, B0); PG8_MMA(0, 1, At, B1); PG8_BAR; PG8_SCHED;
;     ...
;             PG8_WAIT_V(8); PG8_WAIT_L(0); PG8_BAR; PG8_MMA(1, 0, At, B0); PG8_MMA(1, 1, At, B1); PG8_BAR; PG8_SCHED;
.Llw_31080:
	s_barrier
	s_waitcnt vmcnt(8)
	s_waitcnt lgkmcnt(0)
	v_mfma_f32_16x16x32_bf16 v[62:65], v[152:155], v[194:197], v[62:65]
	v_mfma_f32_16x16x32_bf16 v[58:61], v[160:163], v[194:197], v[58:61]
	v_mfma_f32_16x16x32_bf16 v[54:57], v[152:155], v[210:213], v[54:57]
	v_mfma_f32_16x16x32_bf16 v[50:53], v[160:163], v[210:213], v[50:53]
	v_mfma_f32_16x16x32_bf16 v[46:49], v[152:155], v[218:221], v[46:49]
	v_mfma_f32_16x16x32_bf16 v[42:45], v[160:163], v[218:221], v[42:45]
	v_mfma_f32_16x16x32_bf16 v[38:41], v[152:155], v[240:243], v[38:41]
	v_mfma_f32_16x16x32_bf16 v[34:37], v[160:163], v[240:243], v[34:37]
	v_mfma_f32_16x16x32_bf16 v[62:65], v[156:159], v[206:209], v[62:65]
	v_mfma_f32_16x16x32_bf16 v[58:61], v[164:167], v[206:209], v[58:61]
	v_mfma_f32_16x16x32_bf16 v[54:57], v[156:159], v[214:217], v[54:57]
	v_mfma_f32_16x16x32_bf16 v[50:53], v[164:167], v[214:217], v[50:53]
	v_mfma_f32_16x16x32_bf16 v[46:49], v[156:159], v[236:239], v[46:49]
	v_mfma_f32_16x16x32_bf16 v[42:45], v[164:167], v[236:239], v[42:45]
	v_mfma_f32_16x16x32_bf16 v[38:41], v[156:159], v[244:247], v[38:41]
	v_mfma_f32_16x16x32_bf16 v[34:37], v[164:167], v[244:247], v[34:37]
	v_mfma_f32_16x16x32_bf16 v[30:33], v[168:171], v[194:197], v[30:33]
	v_mfma_f32_16x16x32_bf16 v[26:29], v[176:179], v[194:197], v[26:29]
	v_mfma_f32_16x16x32_bf16 v[22:25], v[168:171], v[210:213], v[22:25]
	v_mfma_f32_16x16x32_bf16 v[18:21], v[176:179], v[210:213], v[18:21]
	v_mfma_f32_16x16x32_bf16 v[14:17], v[168:171], v[218:221], v[14:17]
	v_mfma_f32_16x16x32_bf16 v[10:13], v[176:179], v[218:221], v[10:13]
	v_mfma_f32_16x16x32_bf16 v[6:9], v[168:171], v[240:243], v[6:9]
	v_mfma_f32_16x16x32_bf16 v[2:5], v[176:179], v[240:243], v[2:5]
	v_mfma_f32_16x16x32_bf16 v[30:33], v[172:175], v[206:209], v[30:33]
	v_mfma_f32_16x16x32_bf16 v[26:29], v[180:183], v[206:209], v[26:29]
	v_mfma_f32_16x16x32_bf16 v[22:25], v[172:175], v[214:217], v[22:25]
	v_mfma_f32_16x16x32_bf16 v[18:21], v[180:183], v[214:217], v[18:21]
	v_mfma_f32_16x16x32_bf16 v[14:17], v[172:175], v[236:239], v[14:17]
	v_mfma_f32_16x16x32_bf16 v[10:13], v[180:183], v[236:239], v[10:13]
	v_mfma_f32_16x16x32_bf16 v[6:9], v[172:175], v[244:247], v[6:9]
	v_mfma_f32_16x16x32_bf16 v[2:5], v[180:183], v[244:247], v[2:5]
	s_barrier
	s_add_i32 s8, s8, 2
	s_add_u32 s80, s80, 0x100
	s_addc_u32 s81, s81, 0
	s_cmp_gt_u32 s8, 29
.LBB0_1233:
	s_add_u32 s9, s68, s80
	s_addc_u32 s10, s69, s81
	s_add_u32 s9, s9, 0x100
	s_addc_u32 s10, s10, 0
	s_add_u32 s100, s9, 0x7ff80
	s_addc_u32 s101, s10, 0
	s_add_u32 s11, s36, s80
	s_addc_u32 s12, s37, s81
	s_add_i32 s13, 0, 0x10000
	s_cmpk_eq_i32 s80, 0xf00
	s_cselect_b32 s93, s4, s10
	s_cselect_b32 s92, s5, s9
	s_cselect_b32 s85, s6, s12
	s_cselect_b32 s84, s7, s11
	s_add_i32 s9, 0, 0x14000
	ds_read_b128 v[152:155], v186
	ds_read_b128 v[156:159], v186 offset:1024
	ds_read_b128 v[160:163], v186 offset:2048
	ds_read_b128 v[164:167], v186 offset:3072
	ds_read_b128 v[168:171], v187
	ds_read_b128 v[172:175], v187 offset:1024
	ds_read_b128 v[176:179], v187 offset:2048
	ds_read_b128 v[180:183], v187 offset:3072
	s_add_i32 m0, s51, 0xc000
	ds_read_b128 v[206:209], v151
	ds_read_b128 v[210:213], v151 offset:1024
	ds_read_b128 v[214:217], v151 offset:2048
	ds_read_b128 v[218:221], v151 offset:3072
	ds_read_b128 v[236:239], v151 offset:4096
	ds_read_b128 v[240:243], v151 offset:5120
	ds_read_b128 v[244:247], v151 offset:6144
	ds_read_b128 v[194:197], v151 offset:7168
	global_load_lds_dwordx4 v136, s[100:101]
	s_add_i32 m0, s51, 0xe000
	s_nop 0
	global_load_lds_dwordx4 v138, s[100:101]
	s_cmp_lg_u32 s62, 0
	s_cbranch_scc1 .Llw_31166
	s_waitcnt vmcnt(8)
	s_waitcnt lgkmcnt(0)
; #define PG8_STAGE(bufoff, gbase, voff) do { _Pragma("unroll") for (int _i = 0; _i < 2; ++_i) \
;         __builtin_amdgcn_global_load_lds((const unsigned*)((const char*)(gbase) + (voff)[_i]), (PG8_LAS unsigned*)(lds + (bufoff) + ldsw + _i * 8192), 16, 0, 0); } while (0)
; #define PG8_LDA(dst, b, h) do { _Pragma("unroll") for (int m = 0; m < 4; ++m) _Pragma("unroll") for (int k = 0; k < 2; ++k) dst[m][k] = *(const PG8_LAS bf16x8*)(lds + PG8_SA(b, h) + aoff + m * 2048 + k * 1024); } while (0)
; #define PG8_LDB(dst, b, h) do { _Pragma("unroll") for (int n = 0; n < 2; ++n) _Pragma("unroll") for (int k = 0; k < 2; ++k) dst[n][k] = *(const PG8_LAS bf16x8*)(lds + PG8_SB(b, h) + boff + n * 2048 + k * 1024); } while (0)
; #define PG8_MMA(ai, bj, At, Bt) do { __builtin_amdgcn_s_setprio(1); _Pragma("unroll") for (int m = 0; m < 4; ++m) _Pragma("unroll") for (int n = 0; n < 2; ++n) _Pragma("unroll") for (int k = 0; k < 2; ++k) \
;         acc[ai][bj][m][n] = __builtin_amdgcn_mfma_f32_16x16x32_bf16(Bt[n][k], At[m][k], acc[ai][bj][m][n], 0, 0, 0); __builtin_amdgcn_s_setprio(0); } while (0)
; #define PG8_WAIT_V(n) asm volatile("s_waitcnt vmcnt(" #n ")" ::: "memory")
; #define PG8_WAIT_L(n) asm volatile("s_waitcnt lgkmcnt(" #n ")" ::: "memory")
; #define PG8_BAR __builtin_amdgcn_s_barrier()
; #define PG8_SCHED __builtin_amdgcn_sched_barrier(0)
; template <class Epi, class Sched, bool ALIGN_EPI = false, bool SP2 = false>
; __device__ __forceinline__ void gemm_phase(PG8_LAS unsigned char* lds, const Gemm g, const Sched& S, const Epi& E) {
;     ...
;             PG8_WAIT_V(8); PG8_WAIT_L(0); PG8_BAR; PG8_MMA(0, 0, At, B0); PG8_MMA(0, 1, At, B1); PG8_BAR; PG8_SCHED;
;             PG8_LDA(At, 0, 1); PG8_STAGE(PG8_SB(0, 0), b2, voffB); PG8_STAGE(PG8_SB(0, 1), b2 + hstepB, voffB); PG8_STAGE(PG8_SA(0, 0), a2, voffA);
;             PG8_WAIT_V(8); PG8_WAIT_L(0); PG8_BAR; PG8_MMA(1, 0, At, B0); PG8_MMA(1, 1, At, B1); PG8_BAR; PG8_SCHED;
;             PG8_LDB(B0, 1, 0); PG8_LDB(B1, 1, 1); PG8_SCHED; PG8_LDA(At, 1, 0); PG8_STAGE(PG8_SA(0, 1), a2 + hstep, voffA);
;             PG8_WAIT_V(8); PG8_WAIT_L(0); PG8_BAR; PG8_MMA(0, 0, At, B0); PG8_MMA(0, 1, At, B1); PG8_BAR; PG8_SCHED;
;             PG8_LDA(At, 1, 1); PG8_STAGE(PG8_SB(1, 0), b3, voffB); PG8_STAGE(PG8_SB(1, 1), b3 + hstepB, voffB); PG8_STAGE(PG8_SA(1, 0), a3, voffA);
.Llw_31166:
	s_barrier
	s_waitcnt vmcnt(8)
	s_waitcnt lgkmcnt(0)
	v_mfma_f32_16x16x32_bf16 v[126:129], v[152:155], v[206:209], v[126:129]
	v_mfma_f32_16x16x32_bf16 v[122:125], v[160:163], v[206:209], v[122:125]
	v_mfma_f32_16x16x32_bf16 v[118:121], v[152:155], v[214:217], v[118:121]
	v_mfma_f32_16x16x32_bf16 v[114:117], v[160:163], v[214:217], v[114:117]
	v_mfma_f32_16x16x32_bf16 v[110:113], v[152:155], v[236:239], v[110:113]
	v_mfma_f32_16x16x32_bf16 v[106:109], v[160:163], v[236:239], v[106:109]
	v_mfma_f32_16x16x32_bf16 v[102:105], v[152:155], v[244:247], v[102:105]
	v_mfma_f32_16x16x32_bf16 v[98:101], v[160:163], v[244:247], v[98:101]
	v_mfma_f32_16x16x32_bf16 v[126:129], v[156:159], v[210:213], v[126:129]
	v_mfma_f32_16x16x32_bf16 v[122:125], v[164:167], v[210:213], v[122:125]
	v_mfma_f32_16x16x32_bf16 v[118:121], v[156:159], v[218:221], v[118:121]
	v_mfma_f32_16x16x32_bf16 v[114:117], v[164:167], v[218:221], v[114:117]
	v_mfma_f32_16x16x32_bf16 v[110:113], v[156:159], v[240:243], v[110:113]
	v_mfma_f32_16x16x32_bf16 v[106:109], v[164:167], v[240:243], v[106:109]
	v_mfma_f32_16x16x32_bf16 v[102:105], v[156:159], v[194:197], v[102:105]
	v_mfma_f32_16x16x32_bf16 v[98:101], v[164:167], v[194:197], v[98:101]
	v_mfma_f32_16x16x32_bf16 v[94:97], v[168:171], v[206:209], v[94:97]
	v_mfma_f32_16x16x32_bf16 v[90:93], v[176:179], v[206:209], v[90:93]
	v_mfma_f32_16x16x32_bf16 v[86:89], v[168:171], v[214:217], v[86:89]
	v_mfma_f32_16x16x32_bf16 v[82:85], v[176:179], v[214:217], v[82:85]
	v_mfma_f32_16x16x32_bf16 v[78:81], v[168:171], v[236:239], v[78:81]
	v_mfma_f32_16x16x32_bf16 v[74:77], v[176:179], v[236:239], v[74:77]
	v_mfma_f32_16x16x32_bf16 v[70:73], v[168:171], v[244:247], v[70:73]
	v_mfma_f32_16x16x32_bf16 v[66:69], v[176:179], v[244:247], v[66:69]
	v_mfma_f32_16x16x32_bf16 v[94:97], v[172:175], v[210:213], v[94:97]
	v_mfma_f32_16x16x32_bf16 v[90:93], v[180:183], v[210:213], v[90:93]
	v_mfma_f32_16x16x32_bf16 v[86:89], v[172:175], v[218:221], v[86:89]
	v_mfma_f32_16x16x32_bf16 v[82:85], v[180:183], v[218:221], v[82:85]
	v_mfma_f32_16x16x32_bf16 v[78:81], v[172:175], v[240:243], v[78:81]
	v_mfma_f32_16x16x32_bf16 v[74:77], v[180:183], v[240:243], v[74:77]
	v_mfma_f32_16x16x32_bf16 v[70:73], v[172:175], v[194:197], v[70:73]
	v_mfma_f32_16x16x32_bf16 v[66:69], v[180:183], v[194:197], v[66:69]
	s_barrier
	s_add_i32 s10, s13, s42
	s_mov_b32 m0, s10
	ds_read_b128 v[194:197], v151 offset:16384
	ds_read_b128 v[206:209], v151 offset:17408
	ds_read_b128 v[210:213], v151 offset:18432
	ds_read_b128 v[214:217], v151 offset:19456
	ds_read_b128 v[218:221], v151 offset:20480
	ds_read_b128 v[236:239], v151 offset:21504
	ds_read_b128 v[240:243], v151 offset:22528
	ds_read_b128 v[244:247], v151 offset:23552
	global_load_lds_dwordx4 v130, s[84:85]
	s_add_i32 m0, s10, 0x2000
	s_add_u32 s10, s84, 0x20000
	s_addc_u32 s11, s85, 0
	s_add_i32 s9, s9, s42
	global_load_lds_dwordx4 v134, s[84:85]
	s_mov_b32 m0, s9
	s_nop 0
	global_load_lds_dwordx4 v130, s[10:11]
	s_add_i32 m0, s9, 0x2000
	s_nop 0
	global_load_lds_dwordx4 v134, s[10:11]
	s_mov_b32 m0, s51
	s_nop 0
	global_load_lds_dwordx4 v190, s[92:93]
	s_mov_b32 m0, s67
	s_nop 0
	global_load_lds_dwordx4 v132, s[92:93]
	s_cmp_lg_u32 s62, 0
	s_cbranch_scc1 .Llw_31235
	s_waitcnt vmcnt(8)
	s_waitcnt lgkmcnt(0)
.Llw_31235:
	s_barrier
	s_waitcnt vmcnt(8)
	s_waitcnt lgkmcnt(0)
	v_mfma_f32_16x16x32_bf16 v[62:65], v[152:155], v[194:197], v[62:65]
	v_mfma_f32_16x16x32_bf16 v[58:61], v[160:163], v[194:197], v[58:61]
	v_mfma_f32_16x16x32_bf16 v[54:57], v[152:155], v[210:213], v[54:57]
	v_mfma_f32_16x16x32_bf16 v[50:53], v[160:163], v[210:213], v[50:53]
	v_mfma_f32_16x16x32_bf16 v[46:49], v[152:155], v[218:221], v[46:49]
	v_mfma_f32_16x16x32_bf16 v[42:45], v[160:163], v[218:221], v[42:45]
	v_mfma_f32_16x16x32_bf16 v[38:41], v[152:155], v[240:243], v[38:41]
	v_mfma_f32_16x16x32_bf16 v[34:37], v[160:163], v[240:243], v[34:37]
	v_mfma_f32_16x16x32_bf16 v[62:65], v[156:159], v[206:209], v[62:65]
	v_mfma_f32_16x16x32_bf16 v[58:61], v[164:167], v[206:209], v[58:61]
	v_mfma_f32_16x16x32_bf16 v[54:57], v[156:159], v[214:217], v[54:57]
	v_mfma_f32_16x16x32_bf16 v[50:53], v[164:167], v[214:217], v[50:53]
	v_mfma_f32_16x16x32_bf16 v[46:49], v[156:159], v[236:239], v[46:49]
	v_mfma_f32_16x16x32_bf16 v[42:45], v[164:167], v[236:239], v[42:45]
	v_mfma_f32_16x16x32_bf16 v[38:41], v[156:159], v[244:247], v[38:41]
	v_mfma_f32_16x16x32_bf16 v[34:37], v[164:167], v[244:247], v[34:37]
	v_mfma_f32_16x16x32_bf16 v[30:33], v[168:171], v[194:197], v[30:33]
	v_mfma_f32_16x16x32_bf16 v[26:29], v[176:179], v[194:197], v[26:29]
	v_mfma_f32_16x16x32_bf16 v[22:25], v[168:171], v[210:213], v[22:25]
	v_mfma_f32_16x16x32_bf16 v[18:21], v[176:179], v[210:213], v[18:21]
	v_mfma_f32_16x16x32_bf16 v[14:17], v[168:171], v[218:221], v[14:17]
	v_mfma_f32_16x16x32_bf16 v[10:13], v[176:179], v[218:221], v[10:13]
	v_mfma_f32_16x16x32_bf16 v[6:9], v[168:171], v[240:243], v[6:9]
	v_mfma_f32_16x16x32_bf16 v[2:5], v[176:179], v[240:243], v[2:5]
	v_mfma_f32_16x16x32_bf16 v[30:33], v[172:175], v[206:209], v[30:33]
	v_mfma_f32_16x16x32_bf16 v[26:29], v[180:183], v[206:209], v[26:29]
	v_mfma_f32_16x16x32_bf16 v[22:25], v[172:175], v[214:217], v[22:25]
	v_mfma_f32_16x16x32_bf16 v[18:21], v[180:183], v[214:217], v[18:21]
	v_mfma_f32_16x16x32_bf16 v[14:17], v[172:175], v[236:239], v[14:17]
	v_mfma_f32_16x16x32_bf16 v[10:13], v[180:183], v[236:239], v[10:13]
	v_mfma_f32_16x16x32_bf16 v[6:9], v[172:175], v[244:247], v[6:9]
	v_mfma_f32_16x16x32_bf16 v[2:5], v[180:183], v[244:247], v[2:5]
	s_barrier
	s_add_i32 s9, 0, 0x18000
	s_add_i32 s12, 0, 0x1c000
	ds_read_b128 v[152:155], v198
	ds_read_b128 v[156:159], v198 offset:1024
	ds_read_b128 v[160:163], v198 offset:2048
	ds_read_b128 v[164:167], v198 offset:3072
	ds_read_b128 v[168:171], v199
	ds_read_b128 v[172:175], v199 offset:1024
	ds_read_b128 v[176:179], v199 offset:2048
	ds_read_b128 v[180:183], v199 offset:3072
	s_add_u32 s10, s92, 0x80000
	s_addc_u32 s11, s93, 0
	s_mov_b32 m0, s74
	ds_read_b128 v[194:197], v151 offset:32768
	ds_read_b128 v[206:209], v151 offset:33792
	ds_read_b128 v[210:213], v151 offset:34816
	ds_read_b128 v[214:217], v151 offset:35840
	ds_read_b128 v[218:221], v151 offset:36864
	ds_read_b128 v[236:239], v151 offset:37888
	ds_read_b128 v[240:243], v151 offset:38912
	ds_read_b128 v[244:247], v151 offset:39936
	global_load_lds_dwordx4 v190, s[10:11]
	s_mov_b32 m0, s75
	s_nop 0
	global_load_lds_dwordx4 v132, s[10:11]
	s_cmp_lg_u32 s62, 0
	s_cbranch_scc1 .Llw_31302
	s_waitcnt vmcnt(8)
	s_waitcnt lgkmcnt(0)

; #define PG8_STAGE(bufoff, gbase, voff) do { _Pragma("unroll") for (int _i = 0; _i < 2; ++_i) \
;         __builtin_amdgcn_global_load_lds((const unsigned*)((const char*)(gbase) + (voff)[_i]), (PG8_LAS unsigned*)(lds + (bufoff) + ldsw + _i * 8192), 16, 0, 0); } while (0)
; #define PG8_LDA(dst, b, h) do { _Pragma("unroll") for (int m = 0; m < 4; ++m) _Pragma("unroll") for (int k = 0; k < 2; ++k) dst[m][k] = *(const PG8_LAS bf16x8*)(lds + PG8_SA(b, h) + aoff + m * 2048 + k * 1024); } while (0)
; #define PG8_MMA(ai, bj, At, Bt) do { __builtin_amdgcn_s_setprio(1); _Pragma("unroll") for (int m = 0; m < 4; ++m) _Pragma("unroll") for (int n = 0; n < 2; ++n) _Pragma("unroll") for (int k = 0; k < 2; ++k) \
;         acc[ai][bj][m][n] = __builtin_amdgcn_mfma_f32_16x16x32_bf16(Bt[n][k], At[m][k], acc[ai][bj][m][n], 0, 0, 0); __builtin_amdgcn_s_setprio(0); } while (0)
; #define PG8_WAIT_V(n) asm volatile("s_waitcnt vmcnt(" #n ")" ::: "memory")
; #define PG8_WAIT_L(n) asm volatile("s_waitcnt lgkmcnt(" #n ")" ::: "memory")
; #define PG8_BAR __builtin_amdgcn_s_barrier()
; #define PG8_SCHED __builtin_amdgcn_sched_barrier(0)
; template <class Epi, class Sched, bool ALIGN_EPI = false, bool SP2 = false>
; __device__ __forceinline__ void gemm_phase(PG8_LAS unsigned char* lds, const Gemm g, const Sched& S, const Epi& E) {
;     ...
;             PG8_WAIT_V(8); PG8_WAIT_L(0); PG8_BAR; PG8_MMA(0, 0, At, B0); PG8_MMA(0, 1, At, B1); PG8_BAR; PG8_SCHED;
;             PG8_LDA(At, 1, 1); PG8_STAGE(PG8_SB(1, 0), b3, voffB); PG8_STAGE(PG8_SB(1, 1), b3 + hstepB, voffB); PG8_STAGE(PG8_SA(1, 0), a3, voffA);
;             PG8_WAIT_V(8); PG8_WAIT_L(0); PG8_BAR; PG8_MMA(1, 0, At, B0); PG8_MMA(1, 1, At, B1); PG8_BAR; PG8_SCHED;
;     ...
;         if constexpr (ALIGN_EPI) { if (wr == 0) PG8_BAR; }
.Llw_31374:
	s_barrier
	s_waitcnt vmcnt(8)
	s_waitcnt lgkmcnt(0)
	v_mfma_f32_16x16x32_bf16 v[62:65], v[152:155], v[194:197], v[62:65]
	v_mfma_f32_16x16x32_bf16 v[58:61], v[160:163], v[194:197], v[58:61]
	v_mfma_f32_16x16x32_bf16 v[54:57], v[152:155], v[210:213], v[54:57]
	v_mfma_f32_16x16x32_bf16 v[50:53], v[160:163], v[210:213], v[50:53]
	v_mfma_f32_16x16x32_bf16 v[46:49], v[152:155], v[218:221], v[46:49]
	v_mfma_f32_16x16x32_bf16 v[42:45], v[160:163], v[218:221], v[42:45]
	v_mfma_f32_16x16x32_bf16 v[38:41], v[152:155], v[240:243], v[38:41]
	v_mfma_f32_16x16x32_bf16 v[34:37], v[160:163], v[240:243], v[34:37]
	v_mfma_f32_16x16x32_bf16 v[62:65], v[156:159], v[206:209], v[62:65]
	v_mfma_f32_16x16x32_bf16 v[58:61], v[164:167], v[206:209], v[58:61]
	v_mfma_f32_16x16x32_bf16 v[54:57], v[156:159], v[214:217], v[54:57]
	v_mfma_f32_16x16x32_bf16 v[50:53], v[164:167], v[214:217], v[50:53]
	v_mfma_f32_16x16x32_bf16 v[46:49], v[156:159], v[236:239], v[46:49]
	v_mfma_f32_16x16x32_bf16 v[42:45], v[164:167], v[236:239], v[42:45]
	v_mfma_f32_16x16x32_bf16 v[38:41], v[156:159], v[244:247], v[38:41]
	v_mfma_f32_16x16x32_bf16 v[34:37], v[164:167], v[244:247], v[34:37]
	v_mfma_f32_16x16x32_bf16 v[30:33], v[168:171], v[194:197], v[30:33]
	v_mfma_f32_16x16x32_bf16 v[26:29], v[176:179], v[194:197], v[26:29]
	v_mfma_f32_16x16x32_bf16 v[22:25], v[168:171], v[210:213], v[22:25]
	v_mfma_f32_16x16x32_bf16 v[18:21], v[176:179], v[210:213], v[18:21]
	v_mfma_f32_16x16x32_bf16 v[14:17], v[168:171], v[218:221], v[14:17]
	v_mfma_f32_16x16x32_bf16 v[10:13], v[176:179], v[218:221], v[10:13]
	v_mfma_f32_16x16x32_bf16 v[6:9], v[168:171], v[240:243], v[6:9]
	v_mfma_f32_16x16x32_bf16 v[2:5], v[176:179], v[240:243], v[2:5]
	v_mfma_f32_16x16x32_bf16 v[30:33], v[172:175], v[206:209], v[30:33]
	v_mfma_f32_16x16x32_bf16 v[26:29], v[180:183], v[206:209], v[26:29]
	v_mfma_f32_16x16x32_bf16 v[22:25], v[172:175], v[214:217], v[22:25]
	v_mfma_f32_16x16x32_bf16 v[18:21], v[180:183], v[214:217], v[18:21]
	v_mfma_f32_16x16x32_bf16 v[14:17], v[172:175], v[236:239], v[14:17]
	v_mfma_f32_16x16x32_bf16 v[10:13], v[180:183], v[236:239], v[10:13]
	v_mfma_f32_16x16x32_bf16 v[6:9], v[172:175], v[244:247], v[6:9]
	v_mfma_f32_16x16x32_bf16 v[2:5], v[180:183], v[244:247], v[2:5]
	s_barrier
	s_add_i32 s8, s8, 2
	s_add_u32 s80, s80, 0x100
	s_addc_u32 s81, s81, 0
	s_cmp_gt_u32 s8, 29
	s_cbranch_scc0 .LBB0_1233
	s_and_b64 vcc, exec, s[62:63]
	s_cbranch_vccz .LBB0_1236
	s_barrier
